# v27 re-measure (v21 + one s_nop 0 before each closing barrier)
# speedup vs baseline: 1.0070x; 1.0070x over previous
; #define PG8_STAGE(bufoff, gbase, voff) do { _Pragma("unroll") for (int _i = 0; _i < 2; ++_i) \
;         __builtin_amdgcn_global_load_lds((const unsigned*)((const char*)(gbase) + (voff)[_i]), (PG8_LAS unsigned*)(lds + (bufoff) + ldsw + _i * 8192), 16, 0, 0); } while (0)
; #define PG8_WAIT_V(n) asm volatile("s_waitcnt vmcnt(" #n ")" ::: "memory")
; #define PG8_WAIT_L(n) asm volatile("s_waitcnt lgkmcnt(" #n ")" ::: "memory")
; #define PG8_BAR __builtin_amdgcn_s_barrier()
; #define PG8_SCHED __builtin_amdgcn_sched_barrier(0)
; template <class Epi, class Sched, bool ALIGN_EPI = true, bool SP2 = true>
; __device__ __forceinline__ void gemm_phase(PG8_LAS unsigned char* lds, const int K  , const Sched& S, const Epi& E) {
;     ...
;             const char* a1 = cA + (size_t)(t + 1) * kstep;
;             const char* a2 = last ? nA : cA + (size_t)(t + 2) * kstep; const char* b2 = last ? nB : cB + (size_t)(t + 2) * kstep;
;             const char* a3 = a2 + kstep; const char* b3 = b2 + kstep;
;             if constexpr (SP2) {
;             PG8_LDB(B0, 0, 0); PG8_LDB(B1, 0, 1); PG8_SCHED; PG8_LDA(At, 0, 0); PG8_STAGE(PG8_SA(1, 1), a1 + hstep, voffA);
;             PG8_WAIT_V(8); PG8_WAIT_L(0); PG8_BAR; PG8_MMA(0, 0, At, B0); PG8_MMA(0, 1, At, B1); PG8_BAR; PG8_SCHED;
;             PG8_LDA(At, 0, 1); PG8_STAGE(PG8_SB(0, 0), b2, voffB); PG8_STAGE(PG8_SB(0, 1), b2 + hstep, voffB); PG8_STAGE(PG8_SA(0, 0), a2, voffA);
;             PG8_WAIT_V(8); PG8_WAIT_L(0); PG8_BAR; PG8_MMA(1, 0, At, B0); PG8_MMA(1, 1, At, B1); PG8_BAR; PG8_SCHED;
.LBB0_219:
	ds_read_b128 v[148:151], v154
	ds_read_b128 v[160:163], v154 offset:1024
	ds_read_b128 v[164:167], v154 offset:2048
	ds_read_b128 v[168:171], v154 offset:3072
	ds_read_b128 v[172:175], v155
	ds_read_b128 v[176:179], v155 offset:1024
	ds_read_b128 v[180:183], v155 offset:2048
	ds_read_b128 v[184:187], v155 offset:3072
	s_add_u32 s22, s20, 0xfff80080
	s_addc_u32 s23, s21, -1
	s_cmp_eq_u32 s48, 28
	s_cselect_b32 s25, s13, s23
	s_cselect_b32 s24, s44, s22
	s_cselect_b32 s23, s11, s47
	s_cselect_b32 s22, s45, s46
	v_lshl_add_u64 v[220:221], s[20:21], 0, v[140:141]
	s_add_i32 m0, s19, 0xc000
	ds_read_b128 v[188:191], v156
	ds_read_b128 v[192:195], v156 offset:1024
	ds_read_b128 v[196:199], v156 offset:2048
	ds_read_b128 v[200:203], v156 offset:3072
	ds_read_b128 v[204:207], v156 offset:4096
	ds_read_b128 v[208:211], v156 offset:5120
	ds_read_b128 v[212:215], v156 offset:6144
	ds_read_b128 v[216:219], v156 offset:7168
	global_load_lds_dwordx4 v[220:221], off
	v_lshl_add_u64 v[220:221], s[20:21], 0, v[142:143]
	s_add_i32 m0, s19, 0xe000
	s_nop 0
	global_load_lds_dwordx4 v[220:221], off
	s_waitcnt vmcnt(8)
	s_waitcnt lgkmcnt(0)
	s_setprio 1
	s_barrier
	v_mfma_f32_16x16x32_bf16 v[126:129], v[148:151], v[188:191], v[126:129]
	v_mfma_f32_16x16x32_bf16 v[118:121], v[164:167], v[188:191], v[118:121]
	v_mfma_f32_16x16x32_bf16 v[110:113], v[148:151], v[196:199], v[110:113]
	v_mfma_f32_16x16x32_bf16 v[102:105], v[164:167], v[196:199], v[102:105]
	v_mfma_f32_16x16x32_bf16 v[94:97], v[148:151], v[204:207], v[94:97]
	v_mfma_f32_16x16x32_bf16 v[86:89], v[164:167], v[204:207], v[86:89]
	v_mfma_f32_16x16x32_bf16 v[78:81], v[148:151], v[212:215], v[78:81]
	v_mfma_f32_16x16x32_bf16 v[70:73], v[164:167], v[212:215], v[70:73]
	v_mfma_f32_16x16x32_bf16 v[126:129], v[160:163], v[192:195], v[126:129]
	v_mfma_f32_16x16x32_bf16 v[118:121], v[168:171], v[192:195], v[118:121]
	v_mfma_f32_16x16x32_bf16 v[110:113], v[160:163], v[200:203], v[110:113]
	v_mfma_f32_16x16x32_bf16 v[102:105], v[168:171], v[200:203], v[102:105]
	v_mfma_f32_16x16x32_bf16 v[94:97], v[160:163], v[208:211], v[94:97]
	v_mfma_f32_16x16x32_bf16 v[86:89], v[168:171], v[208:211], v[86:89]
	v_mfma_f32_16x16x32_bf16 v[78:81], v[160:163], v[216:219], v[78:81]
	v_mfma_f32_16x16x32_bf16 v[70:73], v[168:171], v[216:219], v[70:73]
	s_setprio 0
	s_setprio 1
	v_mfma_f32_16x16x32_bf16 v[122:125], v[172:175], v[188:191], v[122:125]
	v_mfma_f32_16x16x32_bf16 v[114:117], v[180:183], v[188:191], v[114:117]
	v_mfma_f32_16x16x32_bf16 v[106:109], v[172:175], v[196:199], v[106:109]
	v_mfma_f32_16x16x32_bf16 v[98:101], v[180:183], v[196:199], v[98:101]
	v_mfma_f32_16x16x32_bf16 v[90:93], v[172:175], v[204:207], v[90:93]
	v_mfma_f32_16x16x32_bf16 v[82:85], v[180:183], v[204:207], v[82:85]
	v_mfma_f32_16x16x32_bf16 v[74:77], v[172:175], v[212:215], v[74:77]
	v_mfma_f32_16x16x32_bf16 v[66:69], v[180:183], v[212:215], v[66:69]
	v_mfma_f32_16x16x32_bf16 v[122:125], v[176:179], v[192:195], v[122:125]
	v_mfma_f32_16x16x32_bf16 v[114:117], v[184:187], v[192:195], v[114:117]
	v_mfma_f32_16x16x32_bf16 v[106:109], v[176:179], v[200:203], v[106:109]
	v_mfma_f32_16x16x32_bf16 v[98:101], v[184:187], v[200:203], v[98:101]
	v_mfma_f32_16x16x32_bf16 v[90:93], v[176:179], v[208:211], v[90:93]
	v_mfma_f32_16x16x32_bf16 v[82:85], v[184:187], v[208:211], v[82:85]
	v_mfma_f32_16x16x32_bf16 v[74:77], v[176:179], v[216:219], v[74:77]
	v_mfma_f32_16x16x32_bf16 v[66:69], v[184:187], v[216:219], v[66:69]
	s_nop 0
	s_barrier
	s_setprio 0
	s_add_i32 s49, s39, s29
	v_lshl_add_u64 v[220:221], s[22:23], 0, v[136:137]
	s_mov_b32 m0, s49
	ds_read_b128 v[188:191], v156 offset:16384
	ds_read_b128 v[192:195], v156 offset:17408
	ds_read_b128 v[196:199], v156 offset:18432
	ds_read_b128 v[200:203], v156 offset:19456
	ds_read_b128 v[204:207], v156 offset:20480
	ds_read_b128 v[208:211], v156 offset:21504
	ds_read_b128 v[212:215], v156 offset:22528
	ds_read_b128 v[216:219], v156 offset:23552
	global_load_lds_dwordx4 v[220:221], off
	s_add_i32 m0, s49, 0x2000
	s_add_u32 s50, s22, 0x80000
	v_lshl_add_u64 v[222:223], s[22:23], 0, v[132:133]
	s_addc_u32 s51, s23, 0
	s_add_i32 s49, s40, s29
	global_load_lds_dwordx4 v[222:223], off
	v_lshl_add_u64 v[224:225], s[50:51], 0, v[136:137]
	s_mov_b32 m0, s49
	v_lshl_add_u64 v[226:227], s[24:25], 0, v[134:135]
	global_load_lds_dwordx4 v[224:225], off
	v_lshl_add_u64 v[224:225], s[50:51], 0, v[132:133]
	s_add_i32 m0, s49, 0x2000
	s_nop 0
	global_load_lds_dwordx4 v[224:225], off
	v_lshl_add_u64 v[224:225], s[24:25], 0, v[138:139]
	s_mov_b32 m0, s19
	s_nop 0
	global_load_lds_dwordx4 v[224:225], off
	s_mov_b32 m0, s31
	s_nop 0
	global_load_lds_dwordx4 v[226:227], off
	s_waitcnt vmcnt(8)
	s_waitcnt lgkmcnt(0)
	s_setprio 1
	s_barrier
; #define PG8_STAGE(bufoff, gbase, voff) do { _Pragma("unroll") for (int _i = 0; _i < 2; ++_i) \
;         __builtin_amdgcn_global_load_lds((const unsigned*)((const char*)(gbase) + (voff)[_i]), (PG8_LAS unsigned*)(lds + (bufoff) + ldsw + _i * 8192), 16, 0, 0); } while (0)
; #define PG8_WAIT_V(n) asm volatile("s_waitcnt vmcnt(" #n ")" ::: "memory")
; #define PG8_WAIT_L(n) asm volatile("s_waitcnt lgkmcnt(" #n ")" ::: "memory")
; #define PG8_BAR __builtin_amdgcn_s_barrier()
; #define PG8_SCHED __builtin_amdgcn_sched_barrier(0)
; template <class Epi, class Sched, bool ALIGN_EPI = true, bool SP2 = true>
; __device__ __forceinline__ void gemm_phase(PG8_LAS unsigned char* lds, const int K  , const Sched& S, const Epi& E) {
;     ...
;             PG8_WAIT_V(8); PG8_WAIT_L(0); PG8_BAR; PG8_MMA(1, 0, At, B0); PG8_MMA(1, 1, At, B1); PG8_BAR; PG8_SCHED;
;             PG8_LDB(B0, 1, 0); PG8_LDB(B1, 1, 1); PG8_SCHED; PG8_LDA(At, 1, 0); PG8_STAGE(PG8_SA(0, 1), a2 + hstep, voffA);
;             PG8_WAIT_V(8); PG8_WAIT_L(0); PG8_BAR; PG8_MMA(0, 0, At, B0); PG8_MMA(0, 1, At, B1); PG8_BAR; PG8_SCHED;
	v_mfma_f32_16x16x32_bf16 v[62:65], v[148:151], v[188:191], v[62:65]
	v_mfma_f32_16x16x32_bf16 v[54:57], v[164:167], v[188:191], v[54:57]
	v_mfma_f32_16x16x32_bf16 v[46:49], v[148:151], v[196:199], v[46:49]
	v_mfma_f32_16x16x32_bf16 v[38:41], v[164:167], v[196:199], v[38:41]
	v_mfma_f32_16x16x32_bf16 v[30:33], v[148:151], v[204:207], v[30:33]
	v_mfma_f32_16x16x32_bf16 v[22:25], v[164:167], v[204:207], v[22:25]
	v_mfma_f32_16x16x32_bf16 v[14:17], v[148:151], v[212:215], v[14:17]
	v_mfma_f32_16x16x32_bf16 v[6:9], v[164:167], v[212:215], v[6:9]
	v_mfma_f32_16x16x32_bf16 v[62:65], v[160:163], v[192:195], v[62:65]
	v_mfma_f32_16x16x32_bf16 v[54:57], v[168:171], v[192:195], v[54:57]
	v_mfma_f32_16x16x32_bf16 v[46:49], v[160:163], v[200:203], v[46:49]
	v_mfma_f32_16x16x32_bf16 v[38:41], v[168:171], v[200:203], v[38:41]
	v_mfma_f32_16x16x32_bf16 v[30:33], v[160:163], v[208:211], v[30:33]
	v_mfma_f32_16x16x32_bf16 v[22:25], v[168:171], v[208:211], v[22:25]
	v_mfma_f32_16x16x32_bf16 v[14:17], v[160:163], v[216:219], v[14:17]
	v_mfma_f32_16x16x32_bf16 v[6:9], v[168:171], v[216:219], v[6:9]
	s_setprio 0
	s_setprio 1
	v_mfma_f32_16x16x32_bf16 v[58:61], v[172:175], v[188:191], v[58:61]
	v_mfma_f32_16x16x32_bf16 v[50:53], v[180:183], v[188:191], v[50:53]
	v_mfma_f32_16x16x32_bf16 v[42:45], v[172:175], v[196:199], v[42:45]
	v_mfma_f32_16x16x32_bf16 v[34:37], v[180:183], v[196:199], v[34:37]
	v_mfma_f32_16x16x32_bf16 v[26:29], v[172:175], v[204:207], v[26:29]
	v_mfma_f32_16x16x32_bf16 v[18:21], v[180:183], v[204:207], v[18:21]
	v_mfma_f32_16x16x32_bf16 v[10:13], v[172:175], v[212:215], v[10:13]
	v_mfma_f32_16x16x32_bf16 v[2:5], v[180:183], v[212:215], v[2:5]
	v_mfma_f32_16x16x32_bf16 v[58:61], v[176:179], v[192:195], v[58:61]
	v_mfma_f32_16x16x32_bf16 v[50:53], v[184:187], v[192:195], v[50:53]
	v_mfma_f32_16x16x32_bf16 v[42:45], v[176:179], v[200:203], v[42:45]
	v_mfma_f32_16x16x32_bf16 v[34:37], v[184:187], v[200:203], v[34:37]
	v_mfma_f32_16x16x32_bf16 v[26:29], v[176:179], v[208:211], v[26:29]
	v_mfma_f32_16x16x32_bf16 v[18:21], v[184:187], v[208:211], v[18:21]
	v_mfma_f32_16x16x32_bf16 v[10:13], v[176:179], v[216:219], v[10:13]
	v_mfma_f32_16x16x32_bf16 v[2:5], v[184:187], v[216:219], v[2:5]
	s_nop 0
	s_barrier
	s_setprio 0
	s_add_i32 s49, 0, 0x18000
	v_add_u32_e32 v159, s49, v152
	s_add_i32 s50, 0, 0x1c000
	ds_read_b128 v[148:151], v159
	ds_read_b128 v[160:163], v159 offset:1024
	ds_read_b128 v[164:167], v159 offset:2048
	ds_read_b128 v[168:171], v159 offset:3072
	v_add_u32_e32 v159, s50, v152
	ds_read_b128 v[172:175], v159
	ds_read_b128 v[176:179], v159 offset:1024
	ds_read_b128 v[180:183], v159 offset:2048
	ds_read_b128 v[184:187], v159 offset:3072
	s_add_u32 s24, s24, 0x80000
	s_addc_u32 s25, s25, 0
	s_mov_b32 m0, s33
	v_lshl_add_u64 v[230:231], s[24:25], 0, v[138:139]
	ds_read_b128 v[188:191], v156 offset:32768
	ds_read_b128 v[192:195], v156 offset:33792
	ds_read_b128 v[196:199], v156 offset:34816
	ds_read_b128 v[200:203], v156 offset:35840
	ds_read_b128 v[204:207], v156 offset:36864
	ds_read_b128 v[208:211], v156 offset:37888
	ds_read_b128 v[212:215], v156 offset:38912
	ds_read_b128 v[216:219], v156 offset:39936
	global_load_lds_dwordx4 v[230:231], off
	v_lshl_add_u64 v[230:231], s[24:25], 0, v[134:135]
	s_mov_b32 m0, s34
	s_nop 0
	global_load_lds_dwordx4 v[230:231], off
	s_waitcnt vmcnt(8)
	s_waitcnt lgkmcnt(0)
	s_setprio 1
	s_barrier
	v_mfma_f32_16x16x32_bf16 v[126:129], v[148:151], v[188:191], v[126:129]
	v_mfma_f32_16x16x32_bf16 v[118:121], v[164:167], v[188:191], v[118:121]
	v_mfma_f32_16x16x32_bf16 v[110:113], v[148:151], v[196:199], v[110:113]
	v_mfma_f32_16x16x32_bf16 v[102:105], v[164:167], v[196:199], v[102:105]
	v_mfma_f32_16x16x32_bf16 v[94:97], v[148:151], v[204:207], v[94:97]
	v_mfma_f32_16x16x32_bf16 v[86:89], v[164:167], v[204:207], v[86:89]
	v_mfma_f32_16x16x32_bf16 v[78:81], v[148:151], v[212:215], v[78:81]
	v_mfma_f32_16x16x32_bf16 v[70:73], v[164:167], v[212:215], v[70:73]
	v_mfma_f32_16x16x32_bf16 v[126:129], v[160:163], v[192:195], v[126:129]
	v_mfma_f32_16x16x32_bf16 v[118:121], v[168:171], v[192:195], v[118:121]
	v_mfma_f32_16x16x32_bf16 v[110:113], v[160:163], v[200:203], v[110:113]
	v_mfma_f32_16x16x32_bf16 v[102:105], v[168:171], v[200:203], v[102:105]
	v_mfma_f32_16x16x32_bf16 v[94:97], v[160:163], v[208:211], v[94:97]
	v_mfma_f32_16x16x32_bf16 v[86:89], v[168:171], v[208:211], v[86:89]
	v_mfma_f32_16x16x32_bf16 v[78:81], v[160:163], v[216:219], v[78:81]
	v_mfma_f32_16x16x32_bf16 v[70:73], v[168:171], v[216:219], v[70:73]
	s_setprio 0
	s_setprio 1
	v_mfma_f32_16x16x32_bf16 v[122:125], v[172:175], v[188:191], v[122:125]
	v_mfma_f32_16x16x32_bf16 v[114:117], v[180:183], v[188:191], v[114:117]
	v_mfma_f32_16x16x32_bf16 v[106:109], v[172:175], v[196:199], v[106:109]
	v_mfma_f32_16x16x32_bf16 v[98:101], v[180:183], v[196:199], v[98:101]
	v_mfma_f32_16x16x32_bf16 v[90:93], v[172:175], v[204:207], v[90:93]
	v_mfma_f32_16x16x32_bf16 v[82:85], v[180:183], v[204:207], v[82:85]
	v_mfma_f32_16x16x32_bf16 v[74:77], v[172:175], v[212:215], v[74:77]
	v_mfma_f32_16x16x32_bf16 v[66:69], v[180:183], v[212:215], v[66:69]
	v_mfma_f32_16x16x32_bf16 v[122:125], v[176:179], v[192:195], v[122:125]
	v_mfma_f32_16x16x32_bf16 v[114:117], v[184:187], v[192:195], v[114:117]
	v_mfma_f32_16x16x32_bf16 v[106:109], v[176:179], v[200:203], v[106:109]
	v_mfma_f32_16x16x32_bf16 v[98:101], v[184:187], v[200:203], v[98:101]
	v_mfma_f32_16x16x32_bf16 v[90:93], v[176:179], v[208:211], v[90:93]
	v_mfma_f32_16x16x32_bf16 v[82:85], v[184:187], v[208:211], v[82:85]
	v_mfma_f32_16x16x32_bf16 v[74:77], v[176:179], v[216:219], v[74:77]
	v_mfma_f32_16x16x32_bf16 v[66:69], v[184:187], v[216:219], v[66:69]
	s_nop 0
	s_barrier
; #define PG8_STAGE(bufoff, gbase, voff) do { _Pragma("unroll") for (int _i = 0; _i < 2; ++_i) \
;         __builtin_amdgcn_global_load_lds((const unsigned*)((const char*)(gbase) + (voff)[_i]), (PG8_LAS unsigned*)(lds + (bufoff) + ldsw + _i * 8192), 16, 0, 0); } while (0)
; #define PG8_WAIT_V(n) asm volatile("s_waitcnt vmcnt(" #n ")" ::: "memory")
; #define PG8_WAIT_L(n) asm volatile("s_waitcnt lgkmcnt(" #n ")" ::: "memory")
; #define PG8_BAR __builtin_amdgcn_s_barrier()
; #define PG8_SCHED __builtin_amdgcn_sched_barrier(0)
;     __device__ __forceinline__ int nt(const pg8::Unit& u) const { return u.kind == 0 ? ntiles : q_nt(u.kind - 1); }
; template <class Epi, class Sched, bool ALIGN_EPI = true, bool SP2 = true>
; __device__ __forceinline__ void gemm_phase(PG8_LAS unsigned char* lds, const int K  , const Sched& S, const Epi& E) {
;     ...
;         for (int t = 0; t < nt; t += 2) {
;             const bool last = (t == nt - 2);
;             const char* a1 = cA + (size_t)(t + 1) * kstep;
;             const char* a2 = last ? nA : cA + (size_t)(t + 2) * kstep; const char* b2 = last ? nB : cB + (size_t)(t + 2) * kstep;
;     ...
;             PG8_LDA(At, 1, 1); PG8_STAGE(PG8_SB(1, 0), b3, voffB); PG8_STAGE(PG8_SB(1, 1), b3 + hstep, voffB); PG8_STAGE(PG8_SA(1, 0), a3, voffA);
;             PG8_WAIT_V(8); PG8_WAIT_L(0); PG8_BAR; PG8_MMA(1, 0, At, B0); PG8_MMA(1, 1, At, B1); PG8_BAR; PG8_SCHED;
	s_setprio 0
	s_add_i32 s24, s49, s29
	v_lshl_add_u64 v[220:221], v[220:221], 0, s[6:7]
	s_mov_b32 m0, s24
	ds_read_b128 v[188:191], v156 offset:49152
	ds_read_b128 v[192:195], v156 offset:50176
	ds_read_b128 v[196:199], v156 offset:51200
	ds_read_b128 v[200:203], v156 offset:52224
	ds_read_b128 v[204:207], v156 offset:53248
	ds_read_b128 v[208:211], v156 offset:54272
	ds_read_b128 v[212:215], v156 offset:55296
	ds_read_b128 v[216:219], v156 offset:56320
	global_load_lds_dwordx4 v[220:221], off
	s_add_i32 m0, s24, 0x2000
	s_add_u32 s22, s22, 0x80080
	v_lshl_add_u64 v[220:221], v[222:223], 0, s[6:7]
	s_addc_u32 s23, s23, 0
	s_add_i32 s24, s50, s29
	global_load_lds_dwordx4 v[220:221], off
	v_lshl_add_u64 v[220:221], s[22:23], 0, v[136:137]
	s_mov_b32 m0, s24
	s_nop 0
	global_load_lds_dwordx4 v[220:221], off
	v_lshl_add_u64 v[220:221], s[22:23], 0, v[132:133]
	s_add_i32 m0, s24, 0x2000
	s_nop 0
	global_load_lds_dwordx4 v[220:221], off
	v_lshl_add_u64 v[220:221], v[224:225], 0, s[6:7]
	s_mov_b32 m0, s36
	s_nop 0
	global_load_lds_dwordx4 v[220:221], off
	v_lshl_add_u64 v[220:221], v[226:227], 0, s[6:7]
	s_mov_b32 m0, s37
	s_nop 0
	global_load_lds_dwordx4 v[220:221], off
	s_waitcnt vmcnt(8)
	s_waitcnt lgkmcnt(0)
	s_setprio 1
	s_barrier
	v_mfma_f32_16x16x32_bf16 v[62:65], v[148:151], v[188:191], v[62:65]
	v_mfma_f32_16x16x32_bf16 v[54:57], v[164:167], v[188:191], v[54:57]
	v_mfma_f32_16x16x32_bf16 v[46:49], v[148:151], v[196:199], v[46:49]
	v_mfma_f32_16x16x32_bf16 v[38:41], v[164:167], v[196:199], v[38:41]
	v_mfma_f32_16x16x32_bf16 v[30:33], v[148:151], v[204:207], v[30:33]
	v_mfma_f32_16x16x32_bf16 v[22:25], v[164:167], v[204:207], v[22:25]
	v_mfma_f32_16x16x32_bf16 v[14:17], v[148:151], v[212:215], v[14:17]
	v_mfma_f32_16x16x32_bf16 v[6:9], v[164:167], v[212:215], v[6:9]
	v_mfma_f32_16x16x32_bf16 v[62:65], v[160:163], v[192:195], v[62:65]
	v_mfma_f32_16x16x32_bf16 v[54:57], v[168:171], v[192:195], v[54:57]
	v_mfma_f32_16x16x32_bf16 v[46:49], v[160:163], v[200:203], v[46:49]
	v_mfma_f32_16x16x32_bf16 v[38:41], v[168:171], v[200:203], v[38:41]
	v_mfma_f32_16x16x32_bf16 v[30:33], v[160:163], v[208:211], v[30:33]
	v_mfma_f32_16x16x32_bf16 v[22:25], v[168:171], v[208:211], v[22:25]
	v_mfma_f32_16x16x32_bf16 v[14:17], v[160:163], v[216:219], v[14:17]
	v_mfma_f32_16x16x32_bf16 v[6:9], v[168:171], v[216:219], v[6:9]
	s_setprio 0
	s_setprio 1
	v_mfma_f32_16x16x32_bf16 v[58:61], v[172:175], v[188:191], v[58:61]
	v_mfma_f32_16x16x32_bf16 v[50:53], v[180:183], v[188:191], v[50:53]
	v_mfma_f32_16x16x32_bf16 v[42:45], v[172:175], v[196:199], v[42:45]
	v_mfma_f32_16x16x32_bf16 v[34:37], v[180:183], v[196:199], v[34:37]
	v_mfma_f32_16x16x32_bf16 v[26:29], v[172:175], v[204:207], v[26:29]
	v_mfma_f32_16x16x32_bf16 v[18:21], v[180:183], v[204:207], v[18:21]
	v_mfma_f32_16x16x32_bf16 v[10:13], v[172:175], v[212:215], v[10:13]
	v_mfma_f32_16x16x32_bf16 v[2:5], v[180:183], v[212:215], v[2:5]
	v_mfma_f32_16x16x32_bf16 v[58:61], v[176:179], v[192:195], v[58:61]
	v_mfma_f32_16x16x32_bf16 v[50:53], v[184:187], v[192:195], v[50:53]
	v_mfma_f32_16x16x32_bf16 v[42:45], v[176:179], v[200:203], v[42:45]
	v_mfma_f32_16x16x32_bf16 v[34:37], v[184:187], v[200:203], v[34:37]
	v_mfma_f32_16x16x32_bf16 v[26:29], v[176:179], v[208:211], v[26:29]
	v_mfma_f32_16x16x32_bf16 v[18:21], v[184:187], v[208:211], v[18:21]
	v_mfma_f32_16x16x32_bf16 v[10:13], v[176:179], v[216:219], v[10:13]
	v_mfma_f32_16x16x32_bf16 v[2:5], v[184:187], v[216:219], v[2:5]
	s_nop 0
	s_barrier
	s_setprio 0
	s_add_i32 s48, s48, 2
	s_add_u32 s20, s20, 0x100
	s_addc_u32 s21, s21, 0
	s_add_u32 s46, s46, 0x100
	s_addc_u32 s47, s47, 0
	s_cmp_gt_u32 s48, 29
	s_cbranch_scc0 .LBB0_219
	s_and_b64 vcc, exec, s[8:9]
	s_cbranch_vccz .LBB0_222
	s_barrier

; #define PG8_STAGE(bufoff, gbase, voff) do { _Pragma("unroll") for (int _i = 0; _i < 2; ++_i) \
;         __builtin_amdgcn_global_load_lds((const unsigned*)((const char*)(gbase) + (voff)[_i]), (PG8_LAS unsigned*)(lds + (bufoff) + ldsw + _i * 8192), 16, 0, 0); } while (0)
; #define PG8_WAIT_V(n) asm volatile("s_waitcnt vmcnt(" #n ")" ::: "memory")
; #define PG8_WAIT_L(n) asm volatile("s_waitcnt lgkmcnt(" #n ")" ::: "memory")
; #define PG8_BAR __builtin_amdgcn_s_barrier()
; #define PG8_SCHED __builtin_amdgcn_sched_barrier(0)
; template <class Epi, class Sched, bool ALIGN_EPI = true, bool SP2 = true>
; __device__ __forceinline__ void gemm_phase(PG8_LAS unsigned char* lds, const int K  , const Sched& S, const Epi& E) {
;     ...
;             const char* a1 = cA + (size_t)(t + 1) * kstep;
;             const char* a2 = last ? nA : cA + (size_t)(t + 2) * kstep; const char* b2 = last ? nB : cB + (size_t)(t + 2) * kstep;
;             const char* a3 = a2 + kstep; const char* b3 = b2 + kstep;
;             if constexpr (SP2) {
;             PG8_LDB(B0, 0, 0); PG8_LDB(B1, 0, 1); PG8_SCHED; PG8_LDA(At, 0, 0); PG8_STAGE(PG8_SA(1, 1), a1 + hstep, voffA);
;             PG8_WAIT_V(8); PG8_WAIT_L(0); PG8_BAR; PG8_MMA(0, 0, At, B0); PG8_MMA(0, 1, At, B1); PG8_BAR; PG8_SCHED;
;             PG8_LDA(At, 0, 1); PG8_STAGE(PG8_SB(0, 0), b2, voffB); PG8_STAGE(PG8_SB(0, 1), b2 + hstep, voffB); PG8_STAGE(PG8_SA(0, 0), a2, voffA);
;             PG8_WAIT_V(8); PG8_WAIT_L(0); PG8_BAR; PG8_MMA(1, 0, At, B0); PG8_MMA(1, 1, At, B1); PG8_BAR; PG8_SCHED;
.LBB0_393:
	ds_read_b128 v[18:21], v190
	ds_read_b128 v[22:25], v190 offset:1024
	ds_read_b128 v[26:29], v190 offset:2048
	ds_read_b128 v[30:33], v190 offset:3072
	ds_read_b128 v[2:5], v191
	ds_read_b128 v[6:9], v191 offset:1024
	ds_read_b128 v[10:13], v191 offset:2048
	ds_read_b128 v[14:17], v191 offset:3072
	s_add_i32 s50, s22, 2
	s_add_u32 s20, s18, 0xfff50080
	s_addc_u32 s21, s19, -1
	s_cmp_eq_u32 s47, s22
	s_cselect_b32 s22, s14, s20
	s_cselect_b32 s23, s15, s21
	s_cselect_b32 s21, s17, s49
	s_cselect_b32 s20, s16, s48
	v_lshl_add_u64 v[218:219], s[18:19], 0, v[170:171]
	s_add_i32 m0, s26, 0xc000
	ds_read_b128 v[178:181], v192
	ds_read_b128 v[182:185], v192 offset:1024
	ds_read_b128 v[194:197], v192 offset:2048
	ds_read_b128 v[198:201], v192 offset:3072
	ds_read_b128 v[202:205], v192 offset:4096
	ds_read_b128 v[206:209], v192 offset:5120
	ds_read_b128 v[210:213], v192 offset:6144
	ds_read_b128 v[214:217], v192 offset:7168
	global_load_lds_dwordx4 v[218:219], off
	v_lshl_add_u64 v[218:219], s[18:19], 0, v[172:173]
	s_add_i32 m0, s26, 0xe000
	s_nop 0
	global_load_lds_dwordx4 v[218:219], off
	s_waitcnt vmcnt(8)
	s_waitcnt lgkmcnt(0)
	s_setprio 1
	s_barrier
	v_mfma_scale_f32_16x16x128_f8f6f4 v[158:161], v[18:25], v[178:185], v[158:161], v186, v186 op_sel_hi:[0,0,0]
	v_mfma_scale_f32_16x16x128_f8f6f4 v[154:157], v[26:33], v[178:185], v[154:157], v186, v186 op_sel_hi:[0,0,0]
	v_mfma_scale_f32_16x16x128_f8f6f4 v[150:153], v[18:25], v[194:201], v[150:153], v186, v186 op_sel_hi:[0,0,0]
	v_mfma_scale_f32_16x16x128_f8f6f4 v[142:145], v[26:33], v[194:201], v[142:145], v186, v186 op_sel_hi:[0,0,0]
	v_mfma_scale_f32_16x16x128_f8f6f4 v[134:137], v[18:25], v[202:209], v[134:137], v186, v186 op_sel_hi:[0,0,0]
	v_mfma_scale_f32_16x16x128_f8f6f4 v[126:129], v[26:33], v[202:209], v[126:129], v186, v186 op_sel_hi:[0,0,0]
	v_mfma_scale_f32_16x16x128_f8f6f4 v[118:121], v[18:25], v[210:217], v[118:121], v186, v186 op_sel_hi:[0,0,0]
	v_mfma_scale_f32_16x16x128_f8f6f4 v[110:113], v[26:33], v[210:217], v[110:113], v186, v186 op_sel_hi:[0,0,0]
	s_setprio 0
	s_setprio 1
	v_mfma_scale_f32_16x16x128_f8f6f4 v[146:149], v[2:9], v[178:185], v[146:149], v186, v186 op_sel_hi:[0,0,0]
	v_mfma_scale_f32_16x16x128_f8f6f4 v[138:141], v[10:17], v[178:185], v[138:141], v186, v186 op_sel_hi:[0,0,0]
	v_mfma_scale_f32_16x16x128_f8f6f4 v[130:133], v[2:9], v[194:201], v[130:133], v186, v186 op_sel_hi:[0,0,0]
	v_mfma_scale_f32_16x16x128_f8f6f4 v[122:125], v[10:17], v[194:201], v[122:125], v186, v186 op_sel_hi:[0,0,0]
	v_mfma_scale_f32_16x16x128_f8f6f4 v[114:117], v[2:9], v[202:209], v[114:117], v186, v186 op_sel_hi:[0,0,0]
	v_mfma_scale_f32_16x16x128_f8f6f4 v[106:109], v[10:17], v[202:209], v[106:109], v186, v186 op_sel_hi:[0,0,0]
	v_mfma_scale_f32_16x16x128_f8f6f4 v[102:105], v[2:9], v[210:217], v[102:105], v186, v186 op_sel_hi:[0,0,0]
	v_mfma_scale_f32_16x16x128_f8f6f4 v[98:101], v[10:17], v[210:217], v[98:101], v186, v186 op_sel_hi:[0,0,0]
	s_nop 0
	s_barrier
	s_setprio 0
	s_add_i32 s51, s37, s25
	v_lshl_add_u64 v[178:179], s[20:21], 0, v[164:165]
	s_mov_b32 m0, s51
	ds_read_b128 v[194:197], v192 offset:16384
	ds_read_b128 v[198:201], v192 offset:17408
	ds_read_b128 v[202:205], v192 offset:18432
	ds_read_b128 v[206:209], v192 offset:19456
	ds_read_b128 v[210:213], v192 offset:20480
	ds_read_b128 v[214:217], v192 offset:21504
	ds_read_b128 v[218:221], v192 offset:22528
	ds_read_b128 v[222:225], v192 offset:23552
	global_load_lds_dwordx4 v[178:179], off
	s_add_i32 m0, s51, 0x2000
	s_add_u32 s68, s20, 0xb0000
	v_lshl_add_u64 v[180:181], s[20:21], 0, v[168:169]
	s_addc_u32 s69, s21, 0
	s_add_i32 s51, s38, s25
	global_load_lds_dwordx4 v[180:181], off
	v_lshl_add_u64 v[182:183], s[68:69], 0, v[164:165]
	s_mov_b32 m0, s51
	v_lshl_add_u64 v[184:185], s[22:23], 0, v[166:167]
	global_load_lds_dwordx4 v[182:183], off
	v_lshl_add_u64 v[182:183], s[68:69], 0, v[168:169]
	s_add_i32 m0, s51, 0x2000
	s_nop 0
	global_load_lds_dwordx4 v[182:183], off
	v_lshl_add_u64 v[182:183], s[22:23], 0, v[162:163]
	s_mov_b32 m0, s26
	s_nop 0
	global_load_lds_dwordx4 v[182:183], off
	s_mov_b32 m0, s27
	s_nop 0
	global_load_lds_dwordx4 v[184:185], off
	s_waitcnt vmcnt(8)
	s_waitcnt lgkmcnt(0)
	s_setprio 1
	s_barrier
	v_mfma_scale_f32_16x16x128_f8f6f4 v[94:97], v[18:25], v[194:201], v[94:97], v186, v186 op_sel_hi:[0,0,0]
	v_mfma_scale_f32_16x16x128_f8f6f4 v[90:93], v[26:33], v[194:201], v[90:93], v186, v186 op_sel_hi:[0,0,0]
	v_mfma_scale_f32_16x16x128_f8f6f4 v[86:89], v[18:25], v[202:209], v[86:89], v186, v186 op_sel_hi:[0,0,0]
	v_mfma_scale_f32_16x16x128_f8f6f4 v[78:81], v[26:33], v[202:209], v[78:81], v186, v186 op_sel_hi:[0,0,0]
	v_mfma_scale_f32_16x16x128_f8f6f4 v[70:73], v[18:25], v[210:217], v[70:73], v186, v186 op_sel_hi:[0,0,0]
	v_mfma_scale_f32_16x16x128_f8f6f4 v[62:65], v[26:33], v[210:217], v[62:65], v186, v186 op_sel_hi:[0,0,0]
	v_mfma_scale_f32_16x16x128_f8f6f4 v[54:57], v[18:25], v[218:225], v[54:57], v186, v186 op_sel_hi:[0,0,0]
	v_mfma_scale_f32_16x16x128_f8f6f4 v[46:49], v[26:33], v[218:225], v[46:49], v186, v186 op_sel_hi:[0,0,0]
	s_setprio 0
	s_setprio 1
	v_mfma_scale_f32_16x16x128_f8f6f4 v[82:85], v[2:9], v[194:201], v[82:85], v186, v186 op_sel_hi:[0,0,0]
	v_mfma_scale_f32_16x16x128_f8f6f4 v[74:77], v[10:17], v[194:201], v[74:77], v186, v186 op_sel_hi:[0,0,0]
	v_mfma_scale_f32_16x16x128_f8f6f4 v[66:69], v[2:9], v[202:209], v[66:69], v186, v186 op_sel_hi:[0,0,0]
	v_mfma_scale_f32_16x16x128_f8f6f4 v[58:61], v[10:17], v[202:209], v[58:61], v186, v186 op_sel_hi:[0,0,0]
	v_mfma_scale_f32_16x16x128_f8f6f4 v[50:53], v[2:9], v[210:217], v[50:53], v186, v186 op_sel_hi:[0,0,0]
	v_mfma_scale_f32_16x16x128_f8f6f4 v[42:45], v[10:17], v[210:217], v[42:45], v186, v186 op_sel_hi:[0,0,0]
	v_mfma_scale_f32_16x16x128_f8f6f4 v[38:41], v[2:9], v[218:225], v[38:41], v186, v186 op_sel_hi:[0,0,0]
	v_mfma_scale_f32_16x16x128_f8f6f4 v[34:37], v[10:17], v[218:225], v[34:37], v186, v186 op_sel_hi:[0,0,0]
	s_nop 0
	s_barrier
; #define PG8_STAGE(bufoff, gbase, voff) do { _Pragma("unroll") for (int _i = 0; _i < 2; ++_i) \
;         __builtin_amdgcn_global_load_lds((const unsigned*)((const char*)(gbase) + (voff)[_i]), (PG8_LAS unsigned*)(lds + (bufoff) + ldsw + _i * 8192), 16, 0, 0); } while (0)
; #define PG8_WAIT_V(n) asm volatile("s_waitcnt vmcnt(" #n ")" ::: "memory")
; #define PG8_WAIT_L(n) asm volatile("s_waitcnt lgkmcnt(" #n ")" ::: "memory")
; #define PG8_BAR __builtin_amdgcn_s_barrier()
; #define PG8_SCHED __builtin_amdgcn_sched_barrier(0)
; template <class Epi, class Sched, bool ALIGN_EPI = true, bool SP2 = true>
; __device__ __forceinline__ void gemm_phase(PG8_LAS unsigned char* lds, const int K  , const Sched& S, const Epi& E) {
;     ...
;             PG8_WAIT_V(8); PG8_WAIT_L(0); PG8_BAR; PG8_MMA(1, 0, At, B0); PG8_MMA(1, 1, At, B1); PG8_BAR; PG8_SCHED;
;             PG8_LDB(B0, 1, 0); PG8_LDB(B1, 1, 1); PG8_SCHED; PG8_LDA(At, 1, 0); PG8_STAGE(PG8_SA(0, 1), a2 + hstep, voffA);
;             PG8_WAIT_V(8); PG8_WAIT_L(0); PG8_BAR; PG8_MMA(0, 0, At, B0); PG8_MMA(0, 1, At, B1); PG8_BAR; PG8_SCHED;
;             PG8_LDA(At, 1, 1); PG8_STAGE(PG8_SB(1, 0), b3, voffB); PG8_STAGE(PG8_SB(1, 1), b3 + hstep, voffB); PG8_STAGE(PG8_SA(1, 0), a3, voffA);
;             PG8_WAIT_V(8); PG8_WAIT_L(0); PG8_BAR; PG8_MMA(1, 0, At, B0); PG8_MMA(1, 1, At, B1); PG8_BAR; PG8_SCHED;
;     ...
;         if constexpr (Epi::FP8) asm volatile("s_nop 15\n\ts_nop 15\n\ts_nop 15\n\ts_nop 15\n\ts_nop 15" ::: "memory");
	s_setprio 0
	s_add_i32 s51, 0, 0x18000
	s_add_i32 s68, 0, 0x1c000
	v_add_u32_e32 v14, s51, v188
	v_add_u32_e32 v30, s68, v188
	ds_read_b128 v[2:5], v14
	ds_read_b128 v[6:9], v14 offset:1024
	ds_read_b128 v[10:13], v14 offset:2048
	ds_read_b128 v[14:17], v14 offset:3072
	ds_read_b128 v[18:21], v30
	ds_read_b128 v[22:25], v30 offset:1024
	ds_read_b128 v[26:29], v30 offset:2048
	ds_read_b128 v[30:33], v30 offset:3072
	s_add_u32 s22, s22, 0xb0000
	s_addc_u32 s23, s23, 0
	s_mov_b32 m0, s28
	v_lshl_add_u64 v[226:227], s[22:23], 0, v[162:163]
	ds_read_b128 v[194:197], v192 offset:32768
	ds_read_b128 v[198:201], v192 offset:33792
	ds_read_b128 v[202:205], v192 offset:34816
	ds_read_b128 v[206:209], v192 offset:35840
	ds_read_b128 v[210:213], v192 offset:36864
	ds_read_b128 v[214:217], v192 offset:37888
	ds_read_b128 v[218:221], v192 offset:38912
	ds_read_b128 v[222:225], v192 offset:39936
	global_load_lds_dwordx4 v[226:227], off
	v_lshl_add_u64 v[226:227], s[22:23], 0, v[166:167]
	s_mov_b32 m0, s29
	s_nop 0
	global_load_lds_dwordx4 v[226:227], off
	s_waitcnt vmcnt(8)
	s_waitcnt lgkmcnt(0)
	s_setprio 1
	s_barrier
	v_mfma_scale_f32_16x16x128_f8f6f4 v[158:161], v[2:9], v[194:201], v[158:161], v186, v186 op_sel_hi:[0,0,0]
	v_mfma_scale_f32_16x16x128_f8f6f4 v[154:157], v[10:17], v[194:201], v[154:157], v186, v186 op_sel_hi:[0,0,0]
	v_mfma_scale_f32_16x16x128_f8f6f4 v[150:153], v[2:9], v[202:209], v[150:153], v186, v186 op_sel_hi:[0,0,0]
	v_mfma_scale_f32_16x16x128_f8f6f4 v[142:145], v[10:17], v[202:209], v[142:145], v186, v186 op_sel_hi:[0,0,0]
	v_mfma_scale_f32_16x16x128_f8f6f4 v[134:137], v[2:9], v[210:217], v[134:137], v186, v186 op_sel_hi:[0,0,0]
	v_mfma_scale_f32_16x16x128_f8f6f4 v[126:129], v[10:17], v[210:217], v[126:129], v186, v186 op_sel_hi:[0,0,0]
	v_mfma_scale_f32_16x16x128_f8f6f4 v[118:121], v[2:9], v[218:225], v[118:121], v186, v186 op_sel_hi:[0,0,0]
	v_mfma_scale_f32_16x16x128_f8f6f4 v[110:113], v[10:17], v[218:225], v[110:113], v186, v186 op_sel_hi:[0,0,0]
	s_setprio 0
	s_setprio 1
	v_mfma_scale_f32_16x16x128_f8f6f4 v[146:149], v[18:25], v[194:201], v[146:149], v186, v186 op_sel_hi:[0,0,0]
	v_mfma_scale_f32_16x16x128_f8f6f4 v[138:141], v[26:33], v[194:201], v[138:141], v186, v186 op_sel_hi:[0,0,0]
	v_mfma_scale_f32_16x16x128_f8f6f4 v[130:133], v[18:25], v[202:209], v[130:133], v186, v186 op_sel_hi:[0,0,0]
	v_mfma_scale_f32_16x16x128_f8f6f4 v[122:125], v[26:33], v[202:209], v[122:125], v186, v186 op_sel_hi:[0,0,0]
	v_mfma_scale_f32_16x16x128_f8f6f4 v[114:117], v[18:25], v[210:217], v[114:117], v186, v186 op_sel_hi:[0,0,0]
	v_mfma_scale_f32_16x16x128_f8f6f4 v[106:109], v[26:33], v[210:217], v[106:109], v186, v186 op_sel_hi:[0,0,0]
	v_mfma_scale_f32_16x16x128_f8f6f4 v[102:105], v[18:25], v[218:225], v[102:105], v186, v186 op_sel_hi:[0,0,0]
	v_mfma_scale_f32_16x16x128_f8f6f4 v[98:101], v[26:33], v[218:225], v[98:101], v186, v186 op_sel_hi:[0,0,0]
	s_nop 0
	s_barrier
	s_setprio 0
	s_add_i32 s22, s51, s25
	v_lshl_add_u64 v[178:179], v[178:179], 0, s[8:9]
	s_mov_b32 m0, s22
	ds_read_b128 v[194:197], v192 offset:49152
	ds_read_b128 v[198:201], v192 offset:50176
	ds_read_b128 v[202:205], v192 offset:51200
	ds_read_b128 v[206:209], v192 offset:52224
	ds_read_b128 v[210:213], v192 offset:53248
	ds_read_b128 v[214:217], v192 offset:54272
	ds_read_b128 v[218:221], v192 offset:55296
	ds_read_b128 v[222:225], v192 offset:56320
	global_load_lds_dwordx4 v[178:179], off
	s_add_i32 m0, s22, 0x2000
	s_add_u32 s20, s20, 0xb0080
	v_lshl_add_u64 v[178:179], v[180:181], 0, s[8:9]
	s_addc_u32 s21, s21, 0
	s_add_i32 s22, s68, s25
	global_load_lds_dwordx4 v[178:179], off
	v_lshl_add_u64 v[178:179], s[20:21], 0, v[164:165]
	s_mov_b32 m0, s22
	s_nop 0
	global_load_lds_dwordx4 v[178:179], off
	v_lshl_add_u64 v[178:179], s[20:21], 0, v[168:169]
	s_add_i32 m0, s22, 0x2000
	s_nop 0
	global_load_lds_dwordx4 v[178:179], off
	v_lshl_add_u64 v[178:179], v[182:183], 0, s[8:9]
	s_mov_b32 m0, s33
	s_nop 0
	global_load_lds_dwordx4 v[178:179], off
	v_lshl_add_u64 v[178:179], v[184:185], 0, s[8:9]
	s_mov_b32 m0, s34
	s_nop 0
	global_load_lds_dwordx4 v[178:179], off
	s_waitcnt vmcnt(8)
	s_waitcnt lgkmcnt(0)
	s_setprio 1
	s_barrier
	v_mfma_scale_f32_16x16x128_f8f6f4 v[94:97], v[2:9], v[194:201], v[94:97], v186, v186 op_sel_hi:[0,0,0]
	v_mfma_scale_f32_16x16x128_f8f6f4 v[90:93], v[10:17], v[194:201], v[90:93], v186, v186 op_sel_hi:[0,0,0]
	v_mfma_scale_f32_16x16x128_f8f6f4 v[86:89], v[2:9], v[202:209], v[86:89], v186, v186 op_sel_hi:[0,0,0]
	v_mfma_scale_f32_16x16x128_f8f6f4 v[78:81], v[10:17], v[202:209], v[78:81], v186, v186 op_sel_hi:[0,0,0]
	v_mfma_scale_f32_16x16x128_f8f6f4 v[70:73], v[2:9], v[210:217], v[70:73], v186, v186 op_sel_hi:[0,0,0]
	v_mfma_scale_f32_16x16x128_f8f6f4 v[62:65], v[10:17], v[210:217], v[62:65], v186, v186 op_sel_hi:[0,0,0]
	v_mfma_scale_f32_16x16x128_f8f6f4 v[54:57], v[2:9], v[218:225], v[54:57], v186, v186 op_sel_hi:[0,0,0]
	v_mfma_scale_f32_16x16x128_f8f6f4 v[46:49], v[10:17], v[218:225], v[46:49], v186, v186 op_sel_hi:[0,0,0]
	s_setprio 0
	s_setprio 1
	v_mfma_scale_f32_16x16x128_f8f6f4 v[82:85], v[18:25], v[194:201], v[82:85], v186, v186 op_sel_hi:[0,0,0]
	v_mfma_scale_f32_16x16x128_f8f6f4 v[74:77], v[26:33], v[194:201], v[74:77], v186, v186 op_sel_hi:[0,0,0]
	v_mfma_scale_f32_16x16x128_f8f6f4 v[66:69], v[18:25], v[202:209], v[66:69], v186, v186 op_sel_hi:[0,0,0]
	v_mfma_scale_f32_16x16x128_f8f6f4 v[58:61], v[26:33], v[202:209], v[58:61], v186, v186 op_sel_hi:[0,0,0]
	v_mfma_scale_f32_16x16x128_f8f6f4 v[50:53], v[18:25], v[210:217], v[50:53], v186, v186 op_sel_hi:[0,0,0]
	v_mfma_scale_f32_16x16x128_f8f6f4 v[42:45], v[26:33], v[210:217], v[42:45], v186, v186 op_sel_hi:[0,0,0]
	v_mfma_scale_f32_16x16x128_f8f6f4 v[38:41], v[18:25], v[218:225], v[38:41], v186, v186 op_sel_hi:[0,0,0]
	v_mfma_scale_f32_16x16x128_f8f6f4 v[34:37], v[26:33], v[218:225], v[34:37], v186, v186 op_sel_hi:[0,0,0]
	s_nop 0
	s_barrier
	s_setprio 0
	s_add_u32 s18, s18, 0x100
	s_addc_u32 s19, s19, 0
	s_add_u32 s48, s48, 0x100
	s_addc_u32 s49, s49, 0
	s_cmp_ge_u32 s50, s4
	s_mov_b32 s22, s50
	s_cbranch_scc0 .LBB0_393
	s_nop 15
	s_nop 15
	s_nop 15
	s_nop 15
	s_nop 15
	s_and_b64 vcc, exec, s[10:11]
	s_cbranch_vccz .LBB0_396
	s_barrier

; #define PG8_STAGE(bufoff, gbase, voff) do { _Pragma("unroll") for (int _i = 0; _i < 2; ++_i) \
;         __builtin_amdgcn_global_load_lds((const unsigned*)((const char*)(gbase) + (voff)[_i]), (PG8_LAS unsigned*)(lds + (bufoff) + ldsw + _i * 8192), 16, 0, 0); } while (0)
; #define PG8_WAIT_V(n) asm volatile("s_waitcnt vmcnt(" #n ")" ::: "memory")
; #define PG8_WAIT_L(n) asm volatile("s_waitcnt lgkmcnt(" #n ")" ::: "memory")
; #define PG8_BAR __builtin_amdgcn_s_barrier()
; #define PG8_SCHED __builtin_amdgcn_sched_barrier(0)
; template <class Epi, class Sched, bool ALIGN_EPI = true, bool SP2 = true>
; __device__ __forceinline__ void gemm_phase(PG8_LAS unsigned char* lds, const int K  , const Sched& S, const Epi& E) {
;     ...
;             const char* a1 = cA + (size_t)(t + 1) * kstep;
;             const char* a2 = last ? nA : cA + (size_t)(t + 2) * kstep; const char* b2 = last ? nB : cB + (size_t)(t + 2) * kstep;
;             const char* a3 = a2 + kstep; const char* b3 = b2 + kstep;
;             if constexpr (SP2) {
;             PG8_LDB(B0, 0, 0); PG8_LDB(B1, 0, 1); PG8_SCHED; PG8_LDA(At, 0, 0); PG8_STAGE(PG8_SA(1, 1), a1 + hstep, voffA);
;             PG8_WAIT_V(8); PG8_WAIT_L(0); PG8_BAR; PG8_MMA(0, 0, At, B0); PG8_MMA(0, 1, At, B1); PG8_BAR; PG8_SCHED;
;             PG8_LDA(At, 0, 1); PG8_STAGE(PG8_SB(0, 0), b2, voffB); PG8_STAGE(PG8_SB(0, 1), b2 + hstep, voffB); PG8_STAGE(PG8_SA(0, 0), a2, voffA);
;             PG8_WAIT_V(8); PG8_WAIT_L(0); PG8_BAR; PG8_MMA(1, 0, At, B0); PG8_MMA(1, 1, At, B1); PG8_BAR; PG8_SCHED;
.LBB0_537:
	ds_read_b128 v[150:153], v156
	ds_read_b128 v[160:163], v156 offset:1024
	ds_read_b128 v[164:167], v156 offset:2048
	ds_read_b128 v[168:171], v156 offset:3072
	ds_read_b128 v[172:175], v157
	ds_read_b128 v[176:179], v157 offset:1024
	ds_read_b128 v[180:183], v157 offset:2048
	ds_read_b128 v[184:187], v157 offset:3072
	s_add_u32 s22, s20, 0xfff80080
	s_addc_u32 s23, s21, -1
	s_cmp_eq_u32 s47, 28
	s_cselect_b32 s25, s13, s23
	s_cselect_b32 s24, s19, s22
	s_cselect_b32 s23, s11, s46
	s_cselect_b32 s22, s44, s45
	v_lshl_add_u64 v[220:221], s[20:21], 0, v[142:143]
	s_add_i32 m0, s31, 0xc000
	ds_read_b128 v[188:191], v158
	ds_read_b128 v[192:195], v158 offset:1024
	ds_read_b128 v[196:199], v158 offset:2048
	ds_read_b128 v[200:203], v158 offset:3072
	ds_read_b128 v[204:207], v158 offset:4096
	ds_read_b128 v[208:211], v158 offset:5120
	ds_read_b128 v[212:215], v158 offset:6144
	ds_read_b128 v[216:219], v158 offset:7168
	global_load_lds_dwordx4 v[220:221], off
	v_lshl_add_u64 v[220:221], s[20:21], 0, v[144:145]
	s_add_i32 m0, s31, 0xe000
	s_nop 0
	global_load_lds_dwordx4 v[220:221], off
	s_waitcnt vmcnt(8)
	s_waitcnt lgkmcnt(0)
	s_setprio 1
	s_barrier
	v_mfma_f32_16x16x32_bf16 v[126:129], v[150:153], v[188:191], v[126:129]
	v_mfma_f32_16x16x32_bf16 v[122:125], v[164:167], v[188:191], v[122:125]
	v_mfma_f32_16x16x32_bf16 v[118:121], v[150:153], v[196:199], v[118:121]
	v_mfma_f32_16x16x32_bf16 v[110:113], v[164:167], v[196:199], v[110:113]
	v_mfma_f32_16x16x32_bf16 v[102:105], v[150:153], v[204:207], v[102:105]
	v_mfma_f32_16x16x32_bf16 v[94:97], v[164:167], v[204:207], v[94:97]
	v_mfma_f32_16x16x32_bf16 v[86:89], v[150:153], v[212:215], v[86:89]
	v_mfma_f32_16x16x32_bf16 v[78:81], v[164:167], v[212:215], v[78:81]
	v_mfma_f32_16x16x32_bf16 v[126:129], v[160:163], v[192:195], v[126:129]
	v_mfma_f32_16x16x32_bf16 v[122:125], v[168:171], v[192:195], v[122:125]
	v_mfma_f32_16x16x32_bf16 v[118:121], v[160:163], v[200:203], v[118:121]
	v_mfma_f32_16x16x32_bf16 v[110:113], v[168:171], v[200:203], v[110:113]
	v_mfma_f32_16x16x32_bf16 v[102:105], v[160:163], v[208:211], v[102:105]
	v_mfma_f32_16x16x32_bf16 v[94:97], v[168:171], v[208:211], v[94:97]
	v_mfma_f32_16x16x32_bf16 v[86:89], v[160:163], v[216:219], v[86:89]
	v_mfma_f32_16x16x32_bf16 v[78:81], v[168:171], v[216:219], v[78:81]
	s_setprio 0
	s_setprio 1
	v_mfma_f32_16x16x32_bf16 v[114:117], v[172:175], v[188:191], v[114:117]
	v_mfma_f32_16x16x32_bf16 v[106:109], v[180:183], v[188:191], v[106:109]
	v_mfma_f32_16x16x32_bf16 v[98:101], v[172:175], v[196:199], v[98:101]
	v_mfma_f32_16x16x32_bf16 v[90:93], v[180:183], v[196:199], v[90:93]
	v_mfma_f32_16x16x32_bf16 v[82:85], v[172:175], v[204:207], v[82:85]
	v_mfma_f32_16x16x32_bf16 v[74:77], v[180:183], v[204:207], v[74:77]
	v_mfma_f32_16x16x32_bf16 v[70:73], v[172:175], v[212:215], v[70:73]
	v_mfma_f32_16x16x32_bf16 v[66:69], v[180:183], v[212:215], v[66:69]
	v_mfma_f32_16x16x32_bf16 v[114:117], v[176:179], v[192:195], v[114:117]
	v_mfma_f32_16x16x32_bf16 v[106:109], v[184:187], v[192:195], v[106:109]
	v_mfma_f32_16x16x32_bf16 v[98:101], v[176:179], v[200:203], v[98:101]
	v_mfma_f32_16x16x32_bf16 v[90:93], v[184:187], v[200:203], v[90:93]
	v_mfma_f32_16x16x32_bf16 v[82:85], v[176:179], v[208:211], v[82:85]
	v_mfma_f32_16x16x32_bf16 v[74:77], v[184:187], v[208:211], v[74:77]
	v_mfma_f32_16x16x32_bf16 v[70:73], v[176:179], v[216:219], v[70:73]
	v_mfma_f32_16x16x32_bf16 v[66:69], v[184:187], v[216:219], v[66:69]
	s_nop 0
	s_barrier
	s_setprio 0
	s_add_i32 s48, s40, s29
	v_lshl_add_u64 v[220:221], s[22:23], 0, v[136:137]
	s_mov_b32 m0, s48
	ds_read_b128 v[188:191], v158 offset:16384
	ds_read_b128 v[192:195], v158 offset:17408
	ds_read_b128 v[196:199], v158 offset:18432
	ds_read_b128 v[200:203], v158 offset:19456
	ds_read_b128 v[204:207], v158 offset:20480
	ds_read_b128 v[208:211], v158 offset:21504
	ds_read_b128 v[212:215], v158 offset:22528
	ds_read_b128 v[216:219], v158 offset:23552
	global_load_lds_dwordx4 v[220:221], off
	s_add_i32 m0, s48, 0x2000
	s_add_u32 s48, s22, 0x80000
	v_lshl_add_u64 v[222:223], s[22:23], 0, v[132:133]
	s_addc_u32 s49, s23, 0
	s_add_i32 s50, s41, s29
	global_load_lds_dwordx4 v[222:223], off
	v_lshl_add_u64 v[224:225], s[48:49], 0, v[136:137]
	s_mov_b32 m0, s50
	v_lshl_add_u64 v[226:227], s[24:25], 0, v[134:135]
	global_load_lds_dwordx4 v[224:225], off
	v_lshl_add_u64 v[224:225], s[48:49], 0, v[132:133]
	s_add_i32 m0, s50, 0x2000
	s_nop 0
	global_load_lds_dwordx4 v[224:225], off
	v_lshl_add_u64 v[224:225], s[24:25], 0, v[138:139]
	s_mov_b32 m0, s31
	s_nop 0
	global_load_lds_dwordx4 v[224:225], off
	s_mov_b32 m0, s33
	s_nop 0
	global_load_lds_dwordx4 v[226:227], off
	s_waitcnt vmcnt(8)
	s_waitcnt lgkmcnt(0)
	s_setprio 1
	s_barrier
; #define PG8_STAGE(bufoff, gbase, voff) do { _Pragma("unroll") for (int _i = 0; _i < 2; ++_i) \
;         __builtin_amdgcn_global_load_lds((const unsigned*)((const char*)(gbase) + (voff)[_i]), (PG8_LAS unsigned*)(lds + (bufoff) + ldsw + _i * 8192), 16, 0, 0); } while (0)
; #define PG8_WAIT_V(n) asm volatile("s_waitcnt vmcnt(" #n ")" ::: "memory")
; #define PG8_WAIT_L(n) asm volatile("s_waitcnt lgkmcnt(" #n ")" ::: "memory")
; #define PG8_BAR __builtin_amdgcn_s_barrier()
; #define PG8_SCHED __builtin_amdgcn_sched_barrier(0)
; template <class Epi, class Sched, bool ALIGN_EPI = true, bool SP2 = true>
; __device__ __forceinline__ void gemm_phase(PG8_LAS unsigned char* lds, const int K  , const Sched& S, const Epi& E) {
;     ...
;             PG8_WAIT_V(8); PG8_WAIT_L(0); PG8_BAR; PG8_MMA(1, 0, At, B0); PG8_MMA(1, 1, At, B1); PG8_BAR; PG8_SCHED;
;             PG8_LDB(B0, 1, 0); PG8_LDB(B1, 1, 1); PG8_SCHED; PG8_LDA(At, 1, 0); PG8_STAGE(PG8_SA(0, 1), a2 + hstep, voffA);
;             PG8_WAIT_V(8); PG8_WAIT_L(0); PG8_BAR; PG8_MMA(0, 0, At, B0); PG8_MMA(0, 1, At, B1); PG8_BAR; PG8_SCHED;
	v_mfma_f32_16x16x32_bf16 v[62:65], v[150:153], v[188:191], v[62:65]
	v_mfma_f32_16x16x32_bf16 v[58:61], v[164:167], v[188:191], v[58:61]
	v_mfma_f32_16x16x32_bf16 v[54:57], v[150:153], v[196:199], v[54:57]
	v_mfma_f32_16x16x32_bf16 v[46:49], v[164:167], v[196:199], v[46:49]
	v_mfma_f32_16x16x32_bf16 v[38:41], v[150:153], v[204:207], v[38:41]
	v_mfma_f32_16x16x32_bf16 v[30:33], v[164:167], v[204:207], v[30:33]
	v_mfma_f32_16x16x32_bf16 v[22:25], v[150:153], v[212:215], v[22:25]
	v_mfma_f32_16x16x32_bf16 v[14:17], v[164:167], v[212:215], v[14:17]
	v_mfma_f32_16x16x32_bf16 v[62:65], v[160:163], v[192:195], v[62:65]
	v_mfma_f32_16x16x32_bf16 v[58:61], v[168:171], v[192:195], v[58:61]
	v_mfma_f32_16x16x32_bf16 v[54:57], v[160:163], v[200:203], v[54:57]
	v_mfma_f32_16x16x32_bf16 v[46:49], v[168:171], v[200:203], v[46:49]
	v_mfma_f32_16x16x32_bf16 v[38:41], v[160:163], v[208:211], v[38:41]
	v_mfma_f32_16x16x32_bf16 v[30:33], v[168:171], v[208:211], v[30:33]
	v_mfma_f32_16x16x32_bf16 v[22:25], v[160:163], v[216:219], v[22:25]
	v_mfma_f32_16x16x32_bf16 v[14:17], v[168:171], v[216:219], v[14:17]
	s_setprio 0
	s_setprio 1
	v_mfma_f32_16x16x32_bf16 v[50:53], v[172:175], v[188:191], v[50:53]
	v_mfma_f32_16x16x32_bf16 v[42:45], v[180:183], v[188:191], v[42:45]
	v_mfma_f32_16x16x32_bf16 v[34:37], v[172:175], v[196:199], v[34:37]
	v_mfma_f32_16x16x32_bf16 v[26:29], v[180:183], v[196:199], v[26:29]
	v_mfma_f32_16x16x32_bf16 v[18:21], v[172:175], v[204:207], v[18:21]
	v_mfma_f32_16x16x32_bf16 v[10:13], v[180:183], v[204:207], v[10:13]
	v_mfma_f32_16x16x32_bf16 v[6:9], v[172:175], v[212:215], v[6:9]
	v_mfma_f32_16x16x32_bf16 v[2:5], v[180:183], v[212:215], v[2:5]
	v_mfma_f32_16x16x32_bf16 v[50:53], v[176:179], v[192:195], v[50:53]
	v_mfma_f32_16x16x32_bf16 v[42:45], v[184:187], v[192:195], v[42:45]
	v_mfma_f32_16x16x32_bf16 v[34:37], v[176:179], v[200:203], v[34:37]
	v_mfma_f32_16x16x32_bf16 v[26:29], v[184:187], v[200:203], v[26:29]
	v_mfma_f32_16x16x32_bf16 v[18:21], v[176:179], v[208:211], v[18:21]
	v_mfma_f32_16x16x32_bf16 v[10:13], v[184:187], v[208:211], v[10:13]
	v_mfma_f32_16x16x32_bf16 v[6:9], v[176:179], v[216:219], v[6:9]
	v_mfma_f32_16x16x32_bf16 v[2:5], v[184:187], v[216:219], v[2:5]
	s_nop 0
	s_barrier
	s_setprio 0
	s_add_i32 s48, 0, 0x18000
	v_add_u32_e32 v140, s48, v154
	s_add_i32 s49, 0, 0x1c000
	ds_read_b128 v[150:153], v140
	ds_read_b128 v[160:163], v140 offset:1024
	ds_read_b128 v[164:167], v140 offset:2048
	ds_read_b128 v[168:171], v140 offset:3072
	v_add_u32_e32 v140, s49, v154
	ds_read_b128 v[172:175], v140
	ds_read_b128 v[176:179], v140 offset:1024
	ds_read_b128 v[180:183], v140 offset:2048
	ds_read_b128 v[184:187], v140 offset:3072
	s_add_u32 s24, s24, 0x80000
	s_addc_u32 s25, s25, 0
	s_mov_b32 m0, s34
	v_lshl_add_u64 v[230:231], s[24:25], 0, v[138:139]
	ds_read_b128 v[188:191], v158 offset:32768
	ds_read_b128 v[192:195], v158 offset:33792
	ds_read_b128 v[196:199], v158 offset:34816
	ds_read_b128 v[200:203], v158 offset:35840
	ds_read_b128 v[204:207], v158 offset:36864
	ds_read_b128 v[208:211], v158 offset:37888
	ds_read_b128 v[212:215], v158 offset:38912
	ds_read_b128 v[216:219], v158 offset:39936
	global_load_lds_dwordx4 v[230:231], off
	v_lshl_add_u64 v[230:231], s[24:25], 0, v[134:135]
	s_mov_b32 m0, s35
	s_nop 0
	global_load_lds_dwordx4 v[230:231], off
	s_waitcnt vmcnt(8)
	s_waitcnt lgkmcnt(0)
	s_setprio 1
	s_barrier
	v_mfma_f32_16x16x32_bf16 v[126:129], v[150:153], v[188:191], v[126:129]
	v_mfma_f32_16x16x32_bf16 v[122:125], v[164:167], v[188:191], v[122:125]
	v_mfma_f32_16x16x32_bf16 v[118:121], v[150:153], v[196:199], v[118:121]
	v_mfma_f32_16x16x32_bf16 v[110:113], v[164:167], v[196:199], v[110:113]
	v_mfma_f32_16x16x32_bf16 v[102:105], v[150:153], v[204:207], v[102:105]
	v_mfma_f32_16x16x32_bf16 v[94:97], v[164:167], v[204:207], v[94:97]
	v_mfma_f32_16x16x32_bf16 v[86:89], v[150:153], v[212:215], v[86:89]
	v_mfma_f32_16x16x32_bf16 v[78:81], v[164:167], v[212:215], v[78:81]
	v_mfma_f32_16x16x32_bf16 v[126:129], v[160:163], v[192:195], v[126:129]
	v_mfma_f32_16x16x32_bf16 v[122:125], v[168:171], v[192:195], v[122:125]
	v_mfma_f32_16x16x32_bf16 v[118:121], v[160:163], v[200:203], v[118:121]
	v_mfma_f32_16x16x32_bf16 v[110:113], v[168:171], v[200:203], v[110:113]
	v_mfma_f32_16x16x32_bf16 v[102:105], v[160:163], v[208:211], v[102:105]
	v_mfma_f32_16x16x32_bf16 v[94:97], v[168:171], v[208:211], v[94:97]
	v_mfma_f32_16x16x32_bf16 v[86:89], v[160:163], v[216:219], v[86:89]
	v_mfma_f32_16x16x32_bf16 v[78:81], v[168:171], v[216:219], v[78:81]
	s_setprio 0
	s_setprio 1
	v_mfma_f32_16x16x32_bf16 v[114:117], v[172:175], v[188:191], v[114:117]
	v_mfma_f32_16x16x32_bf16 v[106:109], v[180:183], v[188:191], v[106:109]
	v_mfma_f32_16x16x32_bf16 v[98:101], v[172:175], v[196:199], v[98:101]
	v_mfma_f32_16x16x32_bf16 v[90:93], v[180:183], v[196:199], v[90:93]
	v_mfma_f32_16x16x32_bf16 v[82:85], v[172:175], v[204:207], v[82:85]
	v_mfma_f32_16x16x32_bf16 v[74:77], v[180:183], v[204:207], v[74:77]
	v_mfma_f32_16x16x32_bf16 v[70:73], v[172:175], v[212:215], v[70:73]
	v_mfma_f32_16x16x32_bf16 v[66:69], v[180:183], v[212:215], v[66:69]
	v_mfma_f32_16x16x32_bf16 v[114:117], v[176:179], v[192:195], v[114:117]
	v_mfma_f32_16x16x32_bf16 v[106:109], v[184:187], v[192:195], v[106:109]
	v_mfma_f32_16x16x32_bf16 v[98:101], v[176:179], v[200:203], v[98:101]
	v_mfma_f32_16x16x32_bf16 v[90:93], v[184:187], v[200:203], v[90:93]
	v_mfma_f32_16x16x32_bf16 v[82:85], v[176:179], v[208:211], v[82:85]
	v_mfma_f32_16x16x32_bf16 v[74:77], v[184:187], v[208:211], v[74:77]
	v_mfma_f32_16x16x32_bf16 v[70:73], v[176:179], v[216:219], v[70:73]
	v_mfma_f32_16x16x32_bf16 v[66:69], v[184:187], v[216:219], v[66:69]
	s_nop 0
	s_barrier
; #define PG8_STAGE(bufoff, gbase, voff) do { _Pragma("unroll") for (int _i = 0; _i < 2; ++_i) \
;         __builtin_amdgcn_global_load_lds((const unsigned*)((const char*)(gbase) + (voff)[_i]), (PG8_LAS unsigned*)(lds + (bufoff) + ldsw + _i * 8192), 16, 0, 0); } while (0)
; #define PG8_WAIT_V(n) asm volatile("s_waitcnt vmcnt(" #n ")" ::: "memory")
; #define PG8_WAIT_L(n) asm volatile("s_waitcnt lgkmcnt(" #n ")" ::: "memory")
; #define PG8_BAR __builtin_amdgcn_s_barrier()
; #define PG8_SCHED __builtin_amdgcn_sched_barrier(0)
;     __device__ __forceinline__ int nt(const pg8::Unit& u) const { return u.kind == 0 ? ntiles : q_nt(u.kind - 1); }
; template <class Epi, class Sched, bool ALIGN_EPI = true, bool SP2 = true>
; __device__ __forceinline__ void gemm_phase(PG8_LAS unsigned char* lds, const int K  , const Sched& S, const Epi& E) {
;     ...
;         for (int t = 0; t < nt; t += 2) {
;             const bool last = (t == nt - 2);
;             const char* a1 = cA + (size_t)(t + 1) * kstep;
;             const char* a2 = last ? nA : cA + (size_t)(t + 2) * kstep; const char* b2 = last ? nB : cB + (size_t)(t + 2) * kstep;
;     ...
;             PG8_LDA(At, 1, 1); PG8_STAGE(PG8_SB(1, 0), b3, voffB); PG8_STAGE(PG8_SB(1, 1), b3 + hstep, voffB); PG8_STAGE(PG8_SA(1, 0), a3, voffA);
;             PG8_WAIT_V(8); PG8_WAIT_L(0); PG8_BAR; PG8_MMA(1, 0, At, B0); PG8_MMA(1, 1, At, B1); PG8_BAR; PG8_SCHED;
	s_setprio 0
	s_add_i32 s24, s48, s29
	v_lshl_add_u64 v[220:221], v[220:221], 0, s[6:7]
	s_mov_b32 m0, s24
	ds_read_b128 v[188:191], v158 offset:49152
	ds_read_b128 v[192:195], v158 offset:50176
	ds_read_b128 v[196:199], v158 offset:51200
	ds_read_b128 v[200:203], v158 offset:52224
	ds_read_b128 v[204:207], v158 offset:53248
	ds_read_b128 v[208:211], v158 offset:54272
	ds_read_b128 v[212:215], v158 offset:55296
	ds_read_b128 v[216:219], v158 offset:56320
	global_load_lds_dwordx4 v[220:221], off
	s_add_i32 m0, s24, 0x2000
	s_add_u32 s22, s22, 0x80080
	v_lshl_add_u64 v[220:221], v[222:223], 0, s[6:7]
	s_addc_u32 s23, s23, 0
	s_add_i32 s24, s49, s29
	global_load_lds_dwordx4 v[220:221], off
	v_lshl_add_u64 v[220:221], s[22:23], 0, v[136:137]
	s_mov_b32 m0, s24
	s_nop 0
	global_load_lds_dwordx4 v[220:221], off
	v_lshl_add_u64 v[220:221], s[22:23], 0, v[132:133]
	s_add_i32 m0, s24, 0x2000
	s_nop 0
	global_load_lds_dwordx4 v[220:221], off
	v_lshl_add_u64 v[220:221], v[224:225], 0, s[6:7]
	s_mov_b32 m0, s37
	s_nop 0
	global_load_lds_dwordx4 v[220:221], off
	v_lshl_add_u64 v[220:221], v[226:227], 0, s[6:7]
	s_mov_b32 m0, s38
	s_nop 0
	global_load_lds_dwordx4 v[220:221], off
	s_waitcnt vmcnt(8)
	s_waitcnt lgkmcnt(0)
	s_setprio 1
	s_barrier
	v_mfma_f32_16x16x32_bf16 v[62:65], v[150:153], v[188:191], v[62:65]
	v_mfma_f32_16x16x32_bf16 v[58:61], v[164:167], v[188:191], v[58:61]
	v_mfma_f32_16x16x32_bf16 v[54:57], v[150:153], v[196:199], v[54:57]
	v_mfma_f32_16x16x32_bf16 v[46:49], v[164:167], v[196:199], v[46:49]
	v_mfma_f32_16x16x32_bf16 v[38:41], v[150:153], v[204:207], v[38:41]
	v_mfma_f32_16x16x32_bf16 v[30:33], v[164:167], v[204:207], v[30:33]
	v_mfma_f32_16x16x32_bf16 v[22:25], v[150:153], v[212:215], v[22:25]
	v_mfma_f32_16x16x32_bf16 v[14:17], v[164:167], v[212:215], v[14:17]
	v_mfma_f32_16x16x32_bf16 v[62:65], v[160:163], v[192:195], v[62:65]
	v_mfma_f32_16x16x32_bf16 v[58:61], v[168:171], v[192:195], v[58:61]
	v_mfma_f32_16x16x32_bf16 v[54:57], v[160:163], v[200:203], v[54:57]
	v_mfma_f32_16x16x32_bf16 v[46:49], v[168:171], v[200:203], v[46:49]
	v_mfma_f32_16x16x32_bf16 v[38:41], v[160:163], v[208:211], v[38:41]
	v_mfma_f32_16x16x32_bf16 v[30:33], v[168:171], v[208:211], v[30:33]
	v_mfma_f32_16x16x32_bf16 v[22:25], v[160:163], v[216:219], v[22:25]
	v_mfma_f32_16x16x32_bf16 v[14:17], v[168:171], v[216:219], v[14:17]
	s_setprio 0
	s_setprio 1
	v_mfma_f32_16x16x32_bf16 v[50:53], v[172:175], v[188:191], v[50:53]
	v_mfma_f32_16x16x32_bf16 v[42:45], v[180:183], v[188:191], v[42:45]
	v_mfma_f32_16x16x32_bf16 v[34:37], v[172:175], v[196:199], v[34:37]
	v_mfma_f32_16x16x32_bf16 v[26:29], v[180:183], v[196:199], v[26:29]
	v_mfma_f32_16x16x32_bf16 v[18:21], v[172:175], v[204:207], v[18:21]
	v_mfma_f32_16x16x32_bf16 v[10:13], v[180:183], v[204:207], v[10:13]
	v_mfma_f32_16x16x32_bf16 v[6:9], v[172:175], v[212:215], v[6:9]
	v_mfma_f32_16x16x32_bf16 v[2:5], v[180:183], v[212:215], v[2:5]
	v_mfma_f32_16x16x32_bf16 v[50:53], v[176:179], v[192:195], v[50:53]
	v_mfma_f32_16x16x32_bf16 v[42:45], v[184:187], v[192:195], v[42:45]
	v_mfma_f32_16x16x32_bf16 v[34:37], v[176:179], v[200:203], v[34:37]
	v_mfma_f32_16x16x32_bf16 v[26:29], v[184:187], v[200:203], v[26:29]
	v_mfma_f32_16x16x32_bf16 v[18:21], v[176:179], v[208:211], v[18:21]
	v_mfma_f32_16x16x32_bf16 v[10:13], v[184:187], v[208:211], v[10:13]
	v_mfma_f32_16x16x32_bf16 v[6:9], v[176:179], v[216:219], v[6:9]
	v_mfma_f32_16x16x32_bf16 v[2:5], v[184:187], v[216:219], v[2:5]
	s_nop 0
	s_barrier
	s_setprio 0
	s_add_i32 s47, s47, 2
	s_add_u32 s20, s20, 0x100
	s_addc_u32 s21, s21, 0
	s_add_u32 s45, s45, 0x100
	s_addc_u32 s46, s46, 0
	s_cmp_gt_u32 s47, 29
	s_cbranch_scc0 .LBB0_537
	s_and_b64 vcc, exec, s[8:9]
	s_cbranch_vccz .LBB0_540
	s_barrier

; #define PG8_STAGE(bufoff, gbase, voff) do { _Pragma("unroll") for (int _i = 0; _i < 2; ++_i) \
;         __builtin_amdgcn_global_load_lds((const unsigned*)((const char*)(gbase) + (voff)[_i]), (PG8_LAS unsigned*)(lds + (bufoff) + ldsw + _i * 8192), 16, 0, 0); } while (0)
; #define PG8_WAIT_V(n) asm volatile("s_waitcnt vmcnt(" #n ")" ::: "memory")
; #define PG8_WAIT_L(n) asm volatile("s_waitcnt lgkmcnt(" #n ")" ::: "memory")
; #define PG8_BAR __builtin_amdgcn_s_barrier()
; #define PG8_SCHED __builtin_amdgcn_sched_barrier(0)
; template <class Epi, class Sched, bool ALIGN_EPI = true, bool SP2 = true>
; __device__ __forceinline__ void gemm_phase(PG8_LAS unsigned char* lds, const int K  , const Sched& S, const Epi& E) {
;     ...
;             const char* a1 = cA + (size_t)(t + 1) * kstep;
;             const char* a2 = last ? nA : cA + (size_t)(t + 2) * kstep; const char* b2 = last ? nB : cB + (size_t)(t + 2) * kstep;
;             const char* a3 = a2 + kstep; const char* b3 = b2 + kstep;
;             if constexpr (SP2) {
;             PG8_LDB(B0, 0, 0); PG8_LDB(B1, 0, 1); PG8_SCHED; PG8_LDA(At, 0, 0); PG8_STAGE(PG8_SA(1, 1), a1 + hstep, voffA);
;             PG8_WAIT_V(8); PG8_WAIT_L(0); PG8_BAR; PG8_MMA(0, 0, At, B0); PG8_MMA(0, 1, At, B1); PG8_BAR; PG8_SCHED;
;             PG8_LDA(At, 0, 1); PG8_STAGE(PG8_SB(0, 0), b2, voffB); PG8_STAGE(PG8_SB(0, 1), b2 + hstep, voffB); PG8_STAGE(PG8_SA(0, 0), a2, voffA);
;             PG8_WAIT_V(8); PG8_WAIT_L(0); PG8_BAR; PG8_MMA(1, 0, At, B0); PG8_MMA(1, 1, At, B1); PG8_BAR; PG8_SCHED;
.LBB0_955:
	s_waitcnt vmcnt(0)
	ds_read_b128 v[130:133], v232
	ds_read_b128 v[134:137], v232 offset:1024
	ds_read_b128 v[138:141], v232 offset:2048
	ds_read_b128 v[142:145], v232 offset:3072
	ds_read_b128 v[146:149], v233
	ds_read_b128 v[150:153], v233 offset:1024
	ds_read_b128 v[154:157], v233 offset:2048
	ds_read_b128 v[158:161], v233 offset:3072
	s_add_i32 s73, s28, 2
	s_add_u32 s26, s24, 0xfff80080
	s_addc_u32 s27, s25, -1
	s_cmp_eq_u32 s13, s28
	s_cselect_b32 s28, s16, s26
	s_cselect_b32 s29, s17, s27
	s_cselect_b32 s27, s19, s21
	s_cselect_b32 s26, s18, s15
	v_lshl_add_u64 v[194:195], s[24:25], 0, v[214:215]
	s_add_i32 m0, s23, 0xc000
	ds_read_b128 v[162:165], v234
	ds_read_b128 v[166:169], v234 offset:1024
	ds_read_b128 v[170:173], v234 offset:2048
	ds_read_b128 v[174:177], v234 offset:3072
	ds_read_b128 v[178:181], v234 offset:4096
	ds_read_b128 v[182:185], v234 offset:5120
	ds_read_b128 v[186:189], v234 offset:6144
	ds_read_b128 v[190:193], v234 offset:7168
	global_load_lds_dwordx4 v[194:195], off
	v_lshl_add_u64 v[194:195], s[24:25], 0, v[216:217]
	s_add_i32 m0, s23, 0xe000
	s_nop 0
	global_load_lds_dwordx4 v[194:195], off
	s_waitcnt vmcnt(8)
	s_waitcnt lgkmcnt(0)
	s_setprio 1
	s_barrier
	v_mfma_f32_16x16x32_bf16 v[126:129], v[130:133], v[162:165], v[126:129]
	v_mfma_f32_16x16x32_bf16 v[122:125], v[138:141], v[162:165], v[122:125]
	v_mfma_f32_16x16x32_bf16 v[118:121], v[130:133], v[170:173], v[118:121]
	v_mfma_f32_16x16x32_bf16 v[110:113], v[138:141], v[170:173], v[110:113]
	v_mfma_f32_16x16x32_bf16 v[102:105], v[130:133], v[178:181], v[102:105]
	v_mfma_f32_16x16x32_bf16 v[94:97], v[138:141], v[178:181], v[94:97]
	v_mfma_f32_16x16x32_bf16 v[86:89], v[130:133], v[186:189], v[86:89]
	v_mfma_f32_16x16x32_bf16 v[78:81], v[138:141], v[186:189], v[78:81]
	v_mfma_f32_16x16x32_bf16 v[126:129], v[134:137], v[166:169], v[126:129]
	v_mfma_f32_16x16x32_bf16 v[122:125], v[142:145], v[166:169], v[122:125]
	v_mfma_f32_16x16x32_bf16 v[118:121], v[134:137], v[174:177], v[118:121]
	v_mfma_f32_16x16x32_bf16 v[110:113], v[142:145], v[174:177], v[110:113]
	v_mfma_f32_16x16x32_bf16 v[102:105], v[134:137], v[182:185], v[102:105]
	v_mfma_f32_16x16x32_bf16 v[94:97], v[142:145], v[182:185], v[94:97]
	v_mfma_f32_16x16x32_bf16 v[86:89], v[134:137], v[190:193], v[86:89]
	v_mfma_f32_16x16x32_bf16 v[78:81], v[142:145], v[190:193], v[78:81]
	s_setprio 0
	s_setprio 1
	v_mfma_f32_16x16x32_bf16 v[114:117], v[146:149], v[162:165], v[114:117]
	v_mfma_f32_16x16x32_bf16 v[106:109], v[154:157], v[162:165], v[106:109]
	v_mfma_f32_16x16x32_bf16 v[98:101], v[146:149], v[170:173], v[98:101]
	v_mfma_f32_16x16x32_bf16 v[90:93], v[154:157], v[170:173], v[90:93]
	v_mfma_f32_16x16x32_bf16 v[82:85], v[146:149], v[178:181], v[82:85]
	v_mfma_f32_16x16x32_bf16 v[74:77], v[154:157], v[178:181], v[74:77]
	v_mfma_f32_16x16x32_bf16 v[70:73], v[146:149], v[186:189], v[70:73]
	v_mfma_f32_16x16x32_bf16 v[66:69], v[154:157], v[186:189], v[66:69]
	v_mfma_f32_16x16x32_bf16 v[114:117], v[150:153], v[166:169], v[114:117]
	v_mfma_f32_16x16x32_bf16 v[106:109], v[158:161], v[166:169], v[106:109]
	v_mfma_f32_16x16x32_bf16 v[98:101], v[150:153], v[174:177], v[98:101]
	v_mfma_f32_16x16x32_bf16 v[90:93], v[158:161], v[174:177], v[90:93]
	v_mfma_f32_16x16x32_bf16 v[82:85], v[150:153], v[182:185], v[82:85]
	v_mfma_f32_16x16x32_bf16 v[74:77], v[158:161], v[182:185], v[74:77]
	v_mfma_f32_16x16x32_bf16 v[70:73], v[150:153], v[190:193], v[70:73]
	v_mfma_f32_16x16x32_bf16 v[66:69], v[158:161], v[190:193], v[66:69]
	s_nop 0
	s_barrier
	s_setprio 0
	s_add_i32 s74, s47, s33
	v_lshl_add_u64 v[194:195], s[26:27], 0, v[208:209]
	s_mov_b32 m0, s74
	ds_read_b128 v[162:165], v234 offset:16384
	ds_read_b128 v[166:169], v234 offset:17408
	ds_read_b128 v[170:173], v234 offset:18432
	ds_read_b128 v[174:177], v234 offset:19456
	ds_read_b128 v[178:181], v234 offset:20480
	ds_read_b128 v[182:185], v234 offset:21504
	ds_read_b128 v[186:189], v234 offset:22528
	ds_read_b128 v[190:193], v234 offset:23552
	global_load_lds_dwordx4 v[194:195], off
	s_add_i32 m0, s74, 0x2000
	s_add_u32 s74, s26, 0x80000
	v_lshl_add_u64 v[196:197], s[26:27], 0, v[212:213]
	s_addc_u32 s75, s27, 0
	s_add_i32 s76, s48, s33
	global_load_lds_dwordx4 v[196:197], off
	v_lshl_add_u64 v[198:199], s[74:75], 0, v[208:209]
	s_mov_b32 m0, s76
	v_lshl_add_u64 v[200:201], s[28:29], 0, v[210:211]
	global_load_lds_dwordx4 v[198:199], off
	v_lshl_add_u64 v[198:199], s[74:75], 0, v[212:213]
	s_add_i32 m0, s76, 0x2000
	s_nop 0
	global_load_lds_dwordx4 v[198:199], off
	v_lshl_add_u64 v[198:199], s[28:29], 0, v[206:207]
	s_mov_b32 m0, s23
	s_nop 0
	global_load_lds_dwordx4 v[198:199], off
	s_mov_b32 m0, s34
	s_nop 0
	global_load_lds_dwordx4 v[200:201], off
	s_waitcnt vmcnt(8)
	s_waitcnt lgkmcnt(0)
	s_setprio 1
	s_barrier
; #define PG8_STAGE(bufoff, gbase, voff) do { _Pragma("unroll") for (int _i = 0; _i < 2; ++_i) \
;         __builtin_amdgcn_global_load_lds((const unsigned*)((const char*)(gbase) + (voff)[_i]), (PG8_LAS unsigned*)(lds + (bufoff) + ldsw + _i * 8192), 16, 0, 0); } while (0)
; #define PG8_WAIT_V(n) asm volatile("s_waitcnt vmcnt(" #n ")" ::: "memory")
; #define PG8_WAIT_L(n) asm volatile("s_waitcnt lgkmcnt(" #n ")" ::: "memory")
; #define PG8_BAR __builtin_amdgcn_s_barrier()
; #define PG8_SCHED __builtin_amdgcn_sched_barrier(0)
; template <class Epi, class Sched, bool ALIGN_EPI = true, bool SP2 = true>
; __device__ __forceinline__ void gemm_phase(PG8_LAS unsigned char* lds, const int K  , const Sched& S, const Epi& E) {
;     ...
;             PG8_WAIT_V(8); PG8_WAIT_L(0); PG8_BAR; PG8_MMA(1, 0, At, B0); PG8_MMA(1, 1, At, B1); PG8_BAR; PG8_SCHED;
;             PG8_LDB(B0, 1, 0); PG8_LDB(B1, 1, 1); PG8_SCHED; PG8_LDA(At, 1, 0); PG8_STAGE(PG8_SA(0, 1), a2 + hstep, voffA);
;             PG8_WAIT_V(8); PG8_WAIT_L(0); PG8_BAR; PG8_MMA(0, 0, At, B0); PG8_MMA(0, 1, At, B1); PG8_BAR; PG8_SCHED;
	v_mfma_f32_16x16x32_bf16 v[62:65], v[130:133], v[162:165], v[62:65]
	v_mfma_f32_16x16x32_bf16 v[58:61], v[138:141], v[162:165], v[58:61]
	v_mfma_f32_16x16x32_bf16 v[54:57], v[130:133], v[170:173], v[54:57]
	v_mfma_f32_16x16x32_bf16 v[46:49], v[138:141], v[170:173], v[46:49]
	v_mfma_f32_16x16x32_bf16 v[38:41], v[130:133], v[178:181], v[38:41]
	v_mfma_f32_16x16x32_bf16 v[30:33], v[138:141], v[178:181], v[30:33]
	v_mfma_f32_16x16x32_bf16 v[22:25], v[130:133], v[186:189], v[22:25]
	v_mfma_f32_16x16x32_bf16 v[14:17], v[138:141], v[186:189], v[14:17]
	v_mfma_f32_16x16x32_bf16 v[62:65], v[134:137], v[166:169], v[62:65]
	v_mfma_f32_16x16x32_bf16 v[58:61], v[142:145], v[166:169], v[58:61]
	v_mfma_f32_16x16x32_bf16 v[54:57], v[134:137], v[174:177], v[54:57]
	v_mfma_f32_16x16x32_bf16 v[46:49], v[142:145], v[174:177], v[46:49]
	v_mfma_f32_16x16x32_bf16 v[38:41], v[134:137], v[182:185], v[38:41]
	v_mfma_f32_16x16x32_bf16 v[30:33], v[142:145], v[182:185], v[30:33]
	v_mfma_f32_16x16x32_bf16 v[22:25], v[134:137], v[190:193], v[22:25]
	v_mfma_f32_16x16x32_bf16 v[14:17], v[142:145], v[190:193], v[14:17]
	s_setprio 0
	s_setprio 1
	v_mfma_f32_16x16x32_bf16 v[50:53], v[146:149], v[162:165], v[50:53]
	v_mfma_f32_16x16x32_bf16 v[42:45], v[154:157], v[162:165], v[42:45]
	v_mfma_f32_16x16x32_bf16 v[34:37], v[146:149], v[170:173], v[34:37]
	v_mfma_f32_16x16x32_bf16 v[26:29], v[154:157], v[170:173], v[26:29]
	v_mfma_f32_16x16x32_bf16 v[18:21], v[146:149], v[178:181], v[18:21]
	v_mfma_f32_16x16x32_bf16 v[10:13], v[154:157], v[178:181], v[10:13]
	v_mfma_f32_16x16x32_bf16 v[6:9], v[146:149], v[186:189], v[6:9]
	v_mfma_f32_16x16x32_bf16 v[2:5], v[154:157], v[186:189], v[2:5]
	v_mfma_f32_16x16x32_bf16 v[50:53], v[150:153], v[166:169], v[50:53]
	v_mfma_f32_16x16x32_bf16 v[42:45], v[158:161], v[166:169], v[42:45]
	v_mfma_f32_16x16x32_bf16 v[34:37], v[150:153], v[174:177], v[34:37]
	v_mfma_f32_16x16x32_bf16 v[26:29], v[158:161], v[174:177], v[26:29]
	v_mfma_f32_16x16x32_bf16 v[18:21], v[150:153], v[182:185], v[18:21]
	v_mfma_f32_16x16x32_bf16 v[10:13], v[158:161], v[182:185], v[10:13]
	v_mfma_f32_16x16x32_bf16 v[6:9], v[150:153], v[190:193], v[6:9]
	v_mfma_f32_16x16x32_bf16 v[2:5], v[158:161], v[190:193], v[2:5]
	s_nop 0
	s_barrier
	s_setprio 0
	s_add_i32 s74, 0, 0x18000
	s_add_i32 s75, 0, 0x1c000
	v_add_u32_e32 v142, s74, v230
	v_add_u32_e32 v158, s75, v230
	ds_read_b128 v[130:133], v142
	ds_read_b128 v[134:137], v142 offset:1024
	ds_read_b128 v[138:141], v142 offset:2048
	ds_read_b128 v[142:145], v142 offset:3072
	ds_read_b128 v[146:149], v158
	ds_read_b128 v[150:153], v158 offset:1024
	ds_read_b128 v[154:157], v158 offset:2048
	ds_read_b128 v[158:161], v158 offset:3072
	s_add_u32 s28, s28, 0x80000
	s_addc_u32 s29, s29, 0
	s_mov_b32 m0, s35
	v_lshl_add_u64 v[202:203], s[28:29], 0, v[206:207]
	ds_read_b128 v[162:165], v234 offset:32768
	ds_read_b128 v[166:169], v234 offset:33792
	ds_read_b128 v[170:173], v234 offset:34816
	ds_read_b128 v[174:177], v234 offset:35840
	ds_read_b128 v[178:181], v234 offset:36864
	ds_read_b128 v[182:185], v234 offset:37888
	ds_read_b128 v[186:189], v234 offset:38912
	ds_read_b128 v[190:193], v234 offset:39936
	global_load_lds_dwordx4 v[202:203], off
	v_lshl_add_u64 v[202:203], s[28:29], 0, v[210:211]
	s_mov_b32 m0, s36
	s_nop 0
	global_load_lds_dwordx4 v[202:203], off
	s_waitcnt vmcnt(8)
	s_waitcnt lgkmcnt(0)
	s_setprio 1
	s_barrier
	v_mfma_f32_16x16x32_bf16 v[126:129], v[130:133], v[162:165], v[126:129]
	v_mfma_f32_16x16x32_bf16 v[122:125], v[138:141], v[162:165], v[122:125]
	v_mfma_f32_16x16x32_bf16 v[118:121], v[130:133], v[170:173], v[118:121]
	v_mfma_f32_16x16x32_bf16 v[110:113], v[138:141], v[170:173], v[110:113]
	v_mfma_f32_16x16x32_bf16 v[102:105], v[130:133], v[178:181], v[102:105]
	v_mfma_f32_16x16x32_bf16 v[94:97], v[138:141], v[178:181], v[94:97]
	v_mfma_f32_16x16x32_bf16 v[86:89], v[130:133], v[186:189], v[86:89]
	v_mfma_f32_16x16x32_bf16 v[78:81], v[138:141], v[186:189], v[78:81]
	v_mfma_f32_16x16x32_bf16 v[126:129], v[134:137], v[166:169], v[126:129]
	v_mfma_f32_16x16x32_bf16 v[122:125], v[142:145], v[166:169], v[122:125]
	v_mfma_f32_16x16x32_bf16 v[118:121], v[134:137], v[174:177], v[118:121]
	v_mfma_f32_16x16x32_bf16 v[110:113], v[142:145], v[174:177], v[110:113]
	v_mfma_f32_16x16x32_bf16 v[102:105], v[134:137], v[182:185], v[102:105]
	v_mfma_f32_16x16x32_bf16 v[94:97], v[142:145], v[182:185], v[94:97]
	v_mfma_f32_16x16x32_bf16 v[86:89], v[134:137], v[190:193], v[86:89]
	v_mfma_f32_16x16x32_bf16 v[78:81], v[142:145], v[190:193], v[78:81]
	s_setprio 0
	s_setprio 1
	v_mfma_f32_16x16x32_bf16 v[114:117], v[146:149], v[162:165], v[114:117]
	v_mfma_f32_16x16x32_bf16 v[106:109], v[154:157], v[162:165], v[106:109]
	v_mfma_f32_16x16x32_bf16 v[98:101], v[146:149], v[170:173], v[98:101]
	v_mfma_f32_16x16x32_bf16 v[90:93], v[154:157], v[170:173], v[90:93]
	v_mfma_f32_16x16x32_bf16 v[82:85], v[146:149], v[178:181], v[82:85]
	v_mfma_f32_16x16x32_bf16 v[74:77], v[154:157], v[178:181], v[74:77]
	v_mfma_f32_16x16x32_bf16 v[70:73], v[146:149], v[186:189], v[70:73]
	v_mfma_f32_16x16x32_bf16 v[66:69], v[154:157], v[186:189], v[66:69]
	v_mfma_f32_16x16x32_bf16 v[114:117], v[150:153], v[166:169], v[114:117]
	v_mfma_f32_16x16x32_bf16 v[106:109], v[158:161], v[166:169], v[106:109]
	v_mfma_f32_16x16x32_bf16 v[98:101], v[150:153], v[174:177], v[98:101]
	v_mfma_f32_16x16x32_bf16 v[90:93], v[158:161], v[174:177], v[90:93]
	v_mfma_f32_16x16x32_bf16 v[82:85], v[150:153], v[182:185], v[82:85]
	v_mfma_f32_16x16x32_bf16 v[74:77], v[158:161], v[182:185], v[74:77]
	v_mfma_f32_16x16x32_bf16 v[70:73], v[150:153], v[190:193], v[70:73]
	v_mfma_f32_16x16x32_bf16 v[66:69], v[158:161], v[190:193], v[66:69]
	s_nop 0
	s_barrier
; #define PG8_STAGE(bufoff, gbase, voff) do { _Pragma("unroll") for (int _i = 0; _i < 2; ++_i) \
;         __builtin_amdgcn_global_load_lds((const unsigned*)((const char*)(gbase) + (voff)[_i]), (PG8_LAS unsigned*)(lds + (bufoff) + ldsw + _i * 8192), 16, 0, 0); } while (0)
; #define PG8_WAIT_V(n) asm volatile("s_waitcnt vmcnt(" #n ")" ::: "memory")
; #define PG8_WAIT_L(n) asm volatile("s_waitcnt lgkmcnt(" #n ")" ::: "memory")
; #define PG8_BAR __builtin_amdgcn_s_barrier()
; #define PG8_SCHED __builtin_amdgcn_sched_barrier(0)
;     __device__ __forceinline__ int nt(const pg8::Unit& u) const { return u.kind == 0 ? ntiles : q_nt(u.kind - 1); }
; template <class Epi, class Sched, bool ALIGN_EPI = true, bool SP2 = true>
; __device__ __forceinline__ void gemm_phase(PG8_LAS unsigned char* lds, const int K  , const Sched& S, const Epi& E) {
;     ...
;         for (int t = 0; t < nt; t += 2) {
;             const bool last = (t == nt - 2);
;             const char* a1 = cA + (size_t)(t + 1) * kstep;
;             const char* a2 = last ? nA : cA + (size_t)(t + 2) * kstep; const char* b2 = last ? nB : cB + (size_t)(t + 2) * kstep;
;     ...
;             PG8_LDA(At, 1, 1); PG8_STAGE(PG8_SB(1, 0), b3, voffB); PG8_STAGE(PG8_SB(1, 1), b3 + hstep, voffB); PG8_STAGE(PG8_SA(1, 0), a3, voffA);
;             PG8_WAIT_V(8); PG8_WAIT_L(0); PG8_BAR; PG8_MMA(1, 0, At, B0); PG8_MMA(1, 1, At, B1); PG8_BAR; PG8_SCHED;
	s_setprio 0
	s_add_i32 s28, s74, s33
	v_lshl_add_u64 v[194:195], v[194:195], 0, s[8:9]
	s_mov_b32 m0, s28
	ds_read_b128 v[162:165], v234 offset:49152
	ds_read_b128 v[166:169], v234 offset:50176
	ds_read_b128 v[170:173], v234 offset:51200
	ds_read_b128 v[174:177], v234 offset:52224
	ds_read_b128 v[178:181], v234 offset:53248
	ds_read_b128 v[182:185], v234 offset:54272
	ds_read_b128 v[186:189], v234 offset:55296
	ds_read_b128 v[190:193], v234 offset:56320
	global_load_lds_dwordx4 v[194:195], off
	s_add_i32 m0, s28, 0x2000
	s_add_u32 s26, s26, 0x80080
	v_lshl_add_u64 v[194:195], v[196:197], 0, s[8:9]
	s_addc_u32 s27, s27, 0
	s_add_i32 s28, s75, s33
	global_load_lds_dwordx4 v[194:195], off
	v_lshl_add_u64 v[194:195], s[26:27], 0, v[208:209]
	s_mov_b32 m0, s28
	s_nop 0
	global_load_lds_dwordx4 v[194:195], off
	v_lshl_add_u64 v[194:195], s[26:27], 0, v[212:213]
	s_add_i32 m0, s28, 0x2000
	s_nop 0
	global_load_lds_dwordx4 v[194:195], off
	v_lshl_add_u64 v[194:195], v[198:199], 0, s[8:9]
	s_mov_b32 m0, s42
	s_nop 0
	global_load_lds_dwordx4 v[194:195], off
	v_lshl_add_u64 v[194:195], v[200:201], 0, s[8:9]
	s_mov_b32 m0, s43
	s_nop 0
	global_load_lds_dwordx4 v[194:195], off
	s_waitcnt vmcnt(8)
	s_waitcnt lgkmcnt(0)
	s_setprio 1
	s_barrier
	v_mfma_f32_16x16x32_bf16 v[62:65], v[130:133], v[162:165], v[62:65]
	v_mfma_f32_16x16x32_bf16 v[58:61], v[138:141], v[162:165], v[58:61]
	v_mfma_f32_16x16x32_bf16 v[54:57], v[130:133], v[170:173], v[54:57]
	v_mfma_f32_16x16x32_bf16 v[46:49], v[138:141], v[170:173], v[46:49]
	v_mfma_f32_16x16x32_bf16 v[38:41], v[130:133], v[178:181], v[38:41]
	v_mfma_f32_16x16x32_bf16 v[30:33], v[138:141], v[178:181], v[30:33]
	v_mfma_f32_16x16x32_bf16 v[22:25], v[130:133], v[186:189], v[22:25]
	v_mfma_f32_16x16x32_bf16 v[14:17], v[138:141], v[186:189], v[14:17]
	v_mfma_f32_16x16x32_bf16 v[62:65], v[134:137], v[166:169], v[62:65]
	v_mfma_f32_16x16x32_bf16 v[58:61], v[142:145], v[166:169], v[58:61]
	v_mfma_f32_16x16x32_bf16 v[54:57], v[134:137], v[174:177], v[54:57]
	v_mfma_f32_16x16x32_bf16 v[46:49], v[142:145], v[174:177], v[46:49]
	v_mfma_f32_16x16x32_bf16 v[38:41], v[134:137], v[182:185], v[38:41]
	v_mfma_f32_16x16x32_bf16 v[30:33], v[142:145], v[182:185], v[30:33]
	v_mfma_f32_16x16x32_bf16 v[22:25], v[134:137], v[190:193], v[22:25]
	v_mfma_f32_16x16x32_bf16 v[14:17], v[142:145], v[190:193], v[14:17]
	s_setprio 0
	s_setprio 1
	v_mfma_f32_16x16x32_bf16 v[50:53], v[146:149], v[162:165], v[50:53]
	v_mfma_f32_16x16x32_bf16 v[42:45], v[154:157], v[162:165], v[42:45]
	v_mfma_f32_16x16x32_bf16 v[34:37], v[146:149], v[170:173], v[34:37]
	v_mfma_f32_16x16x32_bf16 v[26:29], v[154:157], v[170:173], v[26:29]
	v_mfma_f32_16x16x32_bf16 v[18:21], v[146:149], v[178:181], v[18:21]
	v_mfma_f32_16x16x32_bf16 v[10:13], v[154:157], v[178:181], v[10:13]
	v_mfma_f32_16x16x32_bf16 v[6:9], v[146:149], v[186:189], v[6:9]
	v_mfma_f32_16x16x32_bf16 v[2:5], v[154:157], v[186:189], v[2:5]
	v_mfma_f32_16x16x32_bf16 v[50:53], v[150:153], v[166:169], v[50:53]
	v_mfma_f32_16x16x32_bf16 v[42:45], v[158:161], v[166:169], v[42:45]
	v_mfma_f32_16x16x32_bf16 v[34:37], v[150:153], v[174:177], v[34:37]
	v_mfma_f32_16x16x32_bf16 v[26:29], v[158:161], v[174:177], v[26:29]
	v_mfma_f32_16x16x32_bf16 v[18:21], v[150:153], v[182:185], v[18:21]
	v_mfma_f32_16x16x32_bf16 v[10:13], v[158:161], v[182:185], v[10:13]
	v_mfma_f32_16x16x32_bf16 v[6:9], v[150:153], v[190:193], v[6:9]
	v_mfma_f32_16x16x32_bf16 v[2:5], v[158:161], v[190:193], v[2:5]
	s_nop 0
	s_barrier
	s_setprio 0
	s_add_u32 s24, s24, 0x100
	s_addc_u32 s25, s25, 0
	s_add_u32 s15, s15, 0x100
	s_addc_u32 s21, s21, 0
	s_cmp_ge_u32 s73, s4
	s_mov_b32 s28, s73
	s_cbranch_scc0 .LBB0_955
	s_and_b64 vcc, exec, s[10:11]
	s_cbranch_vccz .LBB0_958
	s_barrier

; #define PG8_STAGE(bufoff, gbase, voff) do { _Pragma("unroll") for (int _i = 0; _i < 2; ++_i) \
;         __builtin_amdgcn_global_load_lds((const unsigned*)((const char*)(gbase) + (voff)[_i]), (PG8_LAS unsigned*)(lds + (bufoff) + ldsw + _i * 8192), 16, 0, 0); } while (0)
; #define PG8_WAIT_V(n) asm volatile("s_waitcnt vmcnt(" #n ")" ::: "memory")
; #define PG8_WAIT_L(n) asm volatile("s_waitcnt lgkmcnt(" #n ")" ::: "memory")
; #define PG8_BAR __builtin_amdgcn_s_barrier()
; #define PG8_SCHED __builtin_amdgcn_sched_barrier(0)
; template <class Epi, class Sched, bool ALIGN_EPI = true, bool SP2 = true>
; __device__ __forceinline__ void gemm_phase(PG8_LAS unsigned char* lds, const int K  , const Sched& S, const Epi& E) {
;     ...
;             const char* a1 = cA + (size_t)(t + 1) * kstep;
;             const char* a2 = last ? nA : cA + (size_t)(t + 2) * kstep; const char* b2 = last ? nB : cB + (size_t)(t + 2) * kstep;
;             const char* a3 = a2 + kstep; const char* b3 = b2 + kstep;
;             if constexpr (SP2) {
;             PG8_LDB(B0, 0, 0); PG8_LDB(B1, 0, 1); PG8_SCHED; PG8_LDA(At, 0, 0); PG8_STAGE(PG8_SA(1, 1), a1 + hstep, voffA);
;             PG8_WAIT_V(8); PG8_WAIT_L(0); PG8_BAR; PG8_MMA(0, 0, At, B0); PG8_MMA(0, 1, At, B1); PG8_BAR; PG8_SCHED;
;             PG8_LDA(At, 0, 1); PG8_STAGE(PG8_SB(0, 0), b2, voffB); PG8_STAGE(PG8_SB(0, 1), b2 + hstep, voffB); PG8_STAGE(PG8_SA(0, 0), a2, voffA);
;             PG8_WAIT_V(8); PG8_WAIT_L(0); PG8_BAR; PG8_MMA(1, 0, At, B0); PG8_MMA(1, 1, At, B1); PG8_BAR; PG8_SCHED;
.LBB0_1099:
	ds_read_b128 v[148:151], v154
	ds_read_b128 v[160:163], v154 offset:1024
	ds_read_b128 v[164:167], v154 offset:2048
	ds_read_b128 v[168:171], v154 offset:3072
	ds_read_b128 v[172:175], v155
	ds_read_b128 v[176:179], v155 offset:1024
	ds_read_b128 v[180:183], v155 offset:2048
	ds_read_b128 v[184:187], v155 offset:3072
	s_add_u32 s24, s22, 0xfff80080
	s_addc_u32 s25, s23, -1
	s_cmp_eq_u32 s48, 28
	s_cselect_b32 s27, s15, s25
	s_cselect_b32 s26, s44, s24
	s_cselect_b32 s25, s11, s47
	s_cselect_b32 s24, s45, s46
	v_lshl_add_u64 v[220:221], s[22:23], 0, v[140:141]
	s_add_i32 m0, s21, 0xc000
	ds_read_b128 v[188:191], v156
	ds_read_b128 v[192:195], v156 offset:1024
	ds_read_b128 v[196:199], v156 offset:2048
	ds_read_b128 v[200:203], v156 offset:3072
	ds_read_b128 v[204:207], v156 offset:4096
	ds_read_b128 v[208:211], v156 offset:5120
	ds_read_b128 v[212:215], v156 offset:6144
	ds_read_b128 v[216:219], v156 offset:7168
	global_load_lds_dwordx4 v[220:221], off
	v_lshl_add_u64 v[220:221], s[22:23], 0, v[142:143]
	s_add_i32 m0, s21, 0xe000
	s_nop 0
	global_load_lds_dwordx4 v[220:221], off
	s_waitcnt vmcnt(8)
	s_waitcnt lgkmcnt(0)
	s_setprio 1
	s_barrier
	v_mfma_f32_16x16x32_bf16 v[126:129], v[148:151], v[188:191], v[126:129]
	v_mfma_f32_16x16x32_bf16 v[118:121], v[164:167], v[188:191], v[118:121]
	v_mfma_f32_16x16x32_bf16 v[110:113], v[148:151], v[196:199], v[110:113]
	v_mfma_f32_16x16x32_bf16 v[102:105], v[164:167], v[196:199], v[102:105]
	v_mfma_f32_16x16x32_bf16 v[94:97], v[148:151], v[204:207], v[94:97]
	v_mfma_f32_16x16x32_bf16 v[86:89], v[164:167], v[204:207], v[86:89]
	v_mfma_f32_16x16x32_bf16 v[78:81], v[148:151], v[212:215], v[78:81]
	v_mfma_f32_16x16x32_bf16 v[70:73], v[164:167], v[212:215], v[70:73]
	v_mfma_f32_16x16x32_bf16 v[126:129], v[160:163], v[192:195], v[126:129]
	v_mfma_f32_16x16x32_bf16 v[118:121], v[168:171], v[192:195], v[118:121]
	v_mfma_f32_16x16x32_bf16 v[110:113], v[160:163], v[200:203], v[110:113]
	v_mfma_f32_16x16x32_bf16 v[102:105], v[168:171], v[200:203], v[102:105]
	v_mfma_f32_16x16x32_bf16 v[94:97], v[160:163], v[208:211], v[94:97]
	v_mfma_f32_16x16x32_bf16 v[86:89], v[168:171], v[208:211], v[86:89]
	v_mfma_f32_16x16x32_bf16 v[78:81], v[160:163], v[216:219], v[78:81]
	v_mfma_f32_16x16x32_bf16 v[70:73], v[168:171], v[216:219], v[70:73]
	s_setprio 0
	s_setprio 1
	v_mfma_f32_16x16x32_bf16 v[122:125], v[172:175], v[188:191], v[122:125]
	v_mfma_f32_16x16x32_bf16 v[114:117], v[180:183], v[188:191], v[114:117]
	v_mfma_f32_16x16x32_bf16 v[106:109], v[172:175], v[196:199], v[106:109]
	v_mfma_f32_16x16x32_bf16 v[98:101], v[180:183], v[196:199], v[98:101]
	v_mfma_f32_16x16x32_bf16 v[90:93], v[172:175], v[204:207], v[90:93]
	v_mfma_f32_16x16x32_bf16 v[82:85], v[180:183], v[204:207], v[82:85]
	v_mfma_f32_16x16x32_bf16 v[74:77], v[172:175], v[212:215], v[74:77]
	v_mfma_f32_16x16x32_bf16 v[66:69], v[180:183], v[212:215], v[66:69]
	v_mfma_f32_16x16x32_bf16 v[122:125], v[176:179], v[192:195], v[122:125]
	v_mfma_f32_16x16x32_bf16 v[114:117], v[184:187], v[192:195], v[114:117]
	v_mfma_f32_16x16x32_bf16 v[106:109], v[176:179], v[200:203], v[106:109]
	v_mfma_f32_16x16x32_bf16 v[98:101], v[184:187], v[200:203], v[98:101]
	v_mfma_f32_16x16x32_bf16 v[90:93], v[176:179], v[208:211], v[90:93]
	v_mfma_f32_16x16x32_bf16 v[82:85], v[184:187], v[208:211], v[82:85]
	v_mfma_f32_16x16x32_bf16 v[74:77], v[176:179], v[216:219], v[74:77]
	v_mfma_f32_16x16x32_bf16 v[66:69], v[184:187], v[216:219], v[66:69]
	s_nop 0
	s_barrier
	s_setprio 0
	s_add_i32 s49, s39, s29
	v_lshl_add_u64 v[220:221], s[24:25], 0, v[136:137]
	s_mov_b32 m0, s49
	ds_read_b128 v[188:191], v156 offset:16384
	ds_read_b128 v[192:195], v156 offset:17408
	ds_read_b128 v[196:199], v156 offset:18432
	ds_read_b128 v[200:203], v156 offset:19456
	ds_read_b128 v[204:207], v156 offset:20480
	ds_read_b128 v[208:211], v156 offset:21504
	ds_read_b128 v[212:215], v156 offset:22528
	ds_read_b128 v[216:219], v156 offset:23552
	global_load_lds_dwordx4 v[220:221], off
	s_add_i32 m0, s49, 0x2000
	s_add_u32 s50, s24, 0x80000
	v_lshl_add_u64 v[222:223], s[24:25], 0, v[132:133]
	s_addc_u32 s51, s25, 0
	s_add_i32 s49, s40, s29
	global_load_lds_dwordx4 v[222:223], off
	v_lshl_add_u64 v[224:225], s[50:51], 0, v[136:137]
	s_mov_b32 m0, s49
	v_lshl_add_u64 v[226:227], s[26:27], 0, v[134:135]
	global_load_lds_dwordx4 v[224:225], off
	v_lshl_add_u64 v[224:225], s[50:51], 0, v[132:133]
	s_add_i32 m0, s49, 0x2000
	s_nop 0
	global_load_lds_dwordx4 v[224:225], off
	v_lshl_add_u64 v[224:225], s[26:27], 0, v[138:139]
	s_mov_b32 m0, s21
	s_nop 0
	global_load_lds_dwordx4 v[224:225], off
	s_mov_b32 m0, s31
	s_nop 0
	global_load_lds_dwordx4 v[226:227], off
	s_waitcnt vmcnt(8)
	s_waitcnt lgkmcnt(0)
	s_setprio 1
	s_barrier
; #define PG8_STAGE(bufoff, gbase, voff) do { _Pragma("unroll") for (int _i = 0; _i < 2; ++_i) \
;         __builtin_amdgcn_global_load_lds((const unsigned*)((const char*)(gbase) + (voff)[_i]), (PG8_LAS unsigned*)(lds + (bufoff) + ldsw + _i * 8192), 16, 0, 0); } while (0)
; #define PG8_WAIT_V(n) asm volatile("s_waitcnt vmcnt(" #n ")" ::: "memory")
; #define PG8_WAIT_L(n) asm volatile("s_waitcnt lgkmcnt(" #n ")" ::: "memory")
; #define PG8_BAR __builtin_amdgcn_s_barrier()
; #define PG8_SCHED __builtin_amdgcn_sched_barrier(0)
; template <class Epi, class Sched, bool ALIGN_EPI = true, bool SP2 = true>
; __device__ __forceinline__ void gemm_phase(PG8_LAS unsigned char* lds, const int K  , const Sched& S, const Epi& E) {
;     ...
;             PG8_WAIT_V(8); PG8_WAIT_L(0); PG8_BAR; PG8_MMA(1, 0, At, B0); PG8_MMA(1, 1, At, B1); PG8_BAR; PG8_SCHED;
;             PG8_LDB(B0, 1, 0); PG8_LDB(B1, 1, 1); PG8_SCHED; PG8_LDA(At, 1, 0); PG8_STAGE(PG8_SA(0, 1), a2 + hstep, voffA);
;             PG8_WAIT_V(8); PG8_WAIT_L(0); PG8_BAR; PG8_MMA(0, 0, At, B0); PG8_MMA(0, 1, At, B1); PG8_BAR; PG8_SCHED;
	v_mfma_f32_16x16x32_bf16 v[62:65], v[148:151], v[188:191], v[62:65]
	v_mfma_f32_16x16x32_bf16 v[54:57], v[164:167], v[188:191], v[54:57]
	v_mfma_f32_16x16x32_bf16 v[46:49], v[148:151], v[196:199], v[46:49]
	v_mfma_f32_16x16x32_bf16 v[38:41], v[164:167], v[196:199], v[38:41]
	v_mfma_f32_16x16x32_bf16 v[30:33], v[148:151], v[204:207], v[30:33]
	v_mfma_f32_16x16x32_bf16 v[22:25], v[164:167], v[204:207], v[22:25]
	v_mfma_f32_16x16x32_bf16 v[14:17], v[148:151], v[212:215], v[14:17]
	v_mfma_f32_16x16x32_bf16 v[6:9], v[164:167], v[212:215], v[6:9]
	v_mfma_f32_16x16x32_bf16 v[62:65], v[160:163], v[192:195], v[62:65]
	v_mfma_f32_16x16x32_bf16 v[54:57], v[168:171], v[192:195], v[54:57]
	v_mfma_f32_16x16x32_bf16 v[46:49], v[160:163], v[200:203], v[46:49]
	v_mfma_f32_16x16x32_bf16 v[38:41], v[168:171], v[200:203], v[38:41]
	v_mfma_f32_16x16x32_bf16 v[30:33], v[160:163], v[208:211], v[30:33]
	v_mfma_f32_16x16x32_bf16 v[22:25], v[168:171], v[208:211], v[22:25]
	v_mfma_f32_16x16x32_bf16 v[14:17], v[160:163], v[216:219], v[14:17]
	v_mfma_f32_16x16x32_bf16 v[6:9], v[168:171], v[216:219], v[6:9]
	s_setprio 0
	s_setprio 1
	v_mfma_f32_16x16x32_bf16 v[58:61], v[172:175], v[188:191], v[58:61]
	v_mfma_f32_16x16x32_bf16 v[50:53], v[180:183], v[188:191], v[50:53]
	v_mfma_f32_16x16x32_bf16 v[42:45], v[172:175], v[196:199], v[42:45]
	v_mfma_f32_16x16x32_bf16 v[34:37], v[180:183], v[196:199], v[34:37]
	v_mfma_f32_16x16x32_bf16 v[26:29], v[172:175], v[204:207], v[26:29]
	v_mfma_f32_16x16x32_bf16 v[18:21], v[180:183], v[204:207], v[18:21]
	v_mfma_f32_16x16x32_bf16 v[10:13], v[172:175], v[212:215], v[10:13]
	v_mfma_f32_16x16x32_bf16 v[2:5], v[180:183], v[212:215], v[2:5]
	v_mfma_f32_16x16x32_bf16 v[58:61], v[176:179], v[192:195], v[58:61]
	v_mfma_f32_16x16x32_bf16 v[50:53], v[184:187], v[192:195], v[50:53]
	v_mfma_f32_16x16x32_bf16 v[42:45], v[176:179], v[200:203], v[42:45]
	v_mfma_f32_16x16x32_bf16 v[34:37], v[184:187], v[200:203], v[34:37]
	v_mfma_f32_16x16x32_bf16 v[26:29], v[176:179], v[208:211], v[26:29]
	v_mfma_f32_16x16x32_bf16 v[18:21], v[184:187], v[208:211], v[18:21]
	v_mfma_f32_16x16x32_bf16 v[10:13], v[176:179], v[216:219], v[10:13]
	v_mfma_f32_16x16x32_bf16 v[2:5], v[184:187], v[216:219], v[2:5]
	s_nop 0
	s_barrier
	s_setprio 0
	s_add_i32 s49, 0, 0x18000
	v_add_u32_e32 v159, s49, v152
	s_add_i32 s50, 0, 0x1c000
	ds_read_b128 v[148:151], v159
	ds_read_b128 v[160:163], v159 offset:1024
	ds_read_b128 v[164:167], v159 offset:2048
	ds_read_b128 v[168:171], v159 offset:3072
	v_add_u32_e32 v159, s50, v152
	ds_read_b128 v[172:175], v159
	ds_read_b128 v[176:179], v159 offset:1024
	ds_read_b128 v[180:183], v159 offset:2048
	ds_read_b128 v[184:187], v159 offset:3072
	s_add_u32 s26, s26, 0x80000
	s_addc_u32 s27, s27, 0
	s_mov_b32 m0, s33
	v_lshl_add_u64 v[230:231], s[26:27], 0, v[138:139]
	ds_read_b128 v[188:191], v156 offset:32768
	ds_read_b128 v[192:195], v156 offset:33792
	ds_read_b128 v[196:199], v156 offset:34816
	ds_read_b128 v[200:203], v156 offset:35840
	ds_read_b128 v[204:207], v156 offset:36864
	ds_read_b128 v[208:211], v156 offset:37888
	ds_read_b128 v[212:215], v156 offset:38912
	ds_read_b128 v[216:219], v156 offset:39936
	global_load_lds_dwordx4 v[230:231], off
	v_lshl_add_u64 v[230:231], s[26:27], 0, v[134:135]
	s_mov_b32 m0, s34
	s_nop 0
	global_load_lds_dwordx4 v[230:231], off
	s_waitcnt vmcnt(8)
	s_waitcnt lgkmcnt(0)
	s_setprio 1
	s_barrier
	v_mfma_f32_16x16x32_bf16 v[126:129], v[148:151], v[188:191], v[126:129]
	v_mfma_f32_16x16x32_bf16 v[118:121], v[164:167], v[188:191], v[118:121]
	v_mfma_f32_16x16x32_bf16 v[110:113], v[148:151], v[196:199], v[110:113]
	v_mfma_f32_16x16x32_bf16 v[102:105], v[164:167], v[196:199], v[102:105]
	v_mfma_f32_16x16x32_bf16 v[94:97], v[148:151], v[204:207], v[94:97]
	v_mfma_f32_16x16x32_bf16 v[86:89], v[164:167], v[204:207], v[86:89]
	v_mfma_f32_16x16x32_bf16 v[78:81], v[148:151], v[212:215], v[78:81]
	v_mfma_f32_16x16x32_bf16 v[70:73], v[164:167], v[212:215], v[70:73]
	v_mfma_f32_16x16x32_bf16 v[126:129], v[160:163], v[192:195], v[126:129]
	v_mfma_f32_16x16x32_bf16 v[118:121], v[168:171], v[192:195], v[118:121]
	v_mfma_f32_16x16x32_bf16 v[110:113], v[160:163], v[200:203], v[110:113]
	v_mfma_f32_16x16x32_bf16 v[102:105], v[168:171], v[200:203], v[102:105]
	v_mfma_f32_16x16x32_bf16 v[94:97], v[160:163], v[208:211], v[94:97]
	v_mfma_f32_16x16x32_bf16 v[86:89], v[168:171], v[208:211], v[86:89]
	v_mfma_f32_16x16x32_bf16 v[78:81], v[160:163], v[216:219], v[78:81]
	v_mfma_f32_16x16x32_bf16 v[70:73], v[168:171], v[216:219], v[70:73]
	s_setprio 0
	s_setprio 1
	v_mfma_f32_16x16x32_bf16 v[122:125], v[172:175], v[188:191], v[122:125]
	v_mfma_f32_16x16x32_bf16 v[114:117], v[180:183], v[188:191], v[114:117]
	v_mfma_f32_16x16x32_bf16 v[106:109], v[172:175], v[196:199], v[106:109]
	v_mfma_f32_16x16x32_bf16 v[98:101], v[180:183], v[196:199], v[98:101]
	v_mfma_f32_16x16x32_bf16 v[90:93], v[172:175], v[204:207], v[90:93]
	v_mfma_f32_16x16x32_bf16 v[82:85], v[180:183], v[204:207], v[82:85]
	v_mfma_f32_16x16x32_bf16 v[74:77], v[172:175], v[212:215], v[74:77]
	v_mfma_f32_16x16x32_bf16 v[66:69], v[180:183], v[212:215], v[66:69]
	v_mfma_f32_16x16x32_bf16 v[122:125], v[176:179], v[192:195], v[122:125]
	v_mfma_f32_16x16x32_bf16 v[114:117], v[184:187], v[192:195], v[114:117]
	v_mfma_f32_16x16x32_bf16 v[106:109], v[176:179], v[200:203], v[106:109]
	v_mfma_f32_16x16x32_bf16 v[98:101], v[184:187], v[200:203], v[98:101]
	v_mfma_f32_16x16x32_bf16 v[90:93], v[176:179], v[208:211], v[90:93]
	v_mfma_f32_16x16x32_bf16 v[82:85], v[184:187], v[208:211], v[82:85]
	v_mfma_f32_16x16x32_bf16 v[74:77], v[176:179], v[216:219], v[74:77]
	v_mfma_f32_16x16x32_bf16 v[66:69], v[184:187], v[216:219], v[66:69]
	s_nop 0
	s_barrier
; #define PG8_STAGE(bufoff, gbase, voff) do { _Pragma("unroll") for (int _i = 0; _i < 2; ++_i) \
;         __builtin_amdgcn_global_load_lds((const unsigned*)((const char*)(gbase) + (voff)[_i]), (PG8_LAS unsigned*)(lds + (bufoff) + ldsw + _i * 8192), 16, 0, 0); } while (0)
; #define PG8_WAIT_V(n) asm volatile("s_waitcnt vmcnt(" #n ")" ::: "memory")
; #define PG8_WAIT_L(n) asm volatile("s_waitcnt lgkmcnt(" #n ")" ::: "memory")
; #define PG8_BAR __builtin_amdgcn_s_barrier()
; #define PG8_SCHED __builtin_amdgcn_sched_barrier(0)
;     __device__ __forceinline__ int nt(const pg8::Unit& u) const { return u.kind == 0 ? ntiles : q_nt(u.kind - 1); }
; template <class Epi, class Sched, bool ALIGN_EPI = true, bool SP2 = true>
; __device__ __forceinline__ void gemm_phase(PG8_LAS unsigned char* lds, const int K  , const Sched& S, const Epi& E) {
;     ...
;         for (int t = 0; t < nt; t += 2) {
;             const bool last = (t == nt - 2);
;             const char* a1 = cA + (size_t)(t + 1) * kstep;
;             const char* a2 = last ? nA : cA + (size_t)(t + 2) * kstep; const char* b2 = last ? nB : cB + (size_t)(t + 2) * kstep;
;     ...
;             PG8_LDA(At, 1, 1); PG8_STAGE(PG8_SB(1, 0), b3, voffB); PG8_STAGE(PG8_SB(1, 1), b3 + hstep, voffB); PG8_STAGE(PG8_SA(1, 0), a3, voffA);
;             PG8_WAIT_V(8); PG8_WAIT_L(0); PG8_BAR; PG8_MMA(1, 0, At, B0); PG8_MMA(1, 1, At, B1); PG8_BAR; PG8_SCHED;
	s_setprio 0
	s_add_i32 s26, s49, s29
	v_lshl_add_u64 v[220:221], v[220:221], 0, s[4:5]
	s_mov_b32 m0, s26
	ds_read_b128 v[188:191], v156 offset:49152
	ds_read_b128 v[192:195], v156 offset:50176
	ds_read_b128 v[196:199], v156 offset:51200
	ds_read_b128 v[200:203], v156 offset:52224
	ds_read_b128 v[204:207], v156 offset:53248
	ds_read_b128 v[208:211], v156 offset:54272
	ds_read_b128 v[212:215], v156 offset:55296
	ds_read_b128 v[216:219], v156 offset:56320
	global_load_lds_dwordx4 v[220:221], off
	s_add_i32 m0, s26, 0x2000
	s_add_u32 s24, s24, 0x80080
	v_lshl_add_u64 v[220:221], v[222:223], 0, s[4:5]
	s_addc_u32 s25, s25, 0
	s_add_i32 s26, s50, s29
	global_load_lds_dwordx4 v[220:221], off
	v_lshl_add_u64 v[220:221], s[24:25], 0, v[136:137]
	s_mov_b32 m0, s26
	s_nop 0
	global_load_lds_dwordx4 v[220:221], off
	v_lshl_add_u64 v[220:221], s[24:25], 0, v[132:133]
	s_add_i32 m0, s26, 0x2000
	s_nop 0
	global_load_lds_dwordx4 v[220:221], off
	v_lshl_add_u64 v[220:221], v[224:225], 0, s[4:5]
	s_mov_b32 m0, s36
	s_nop 0
	global_load_lds_dwordx4 v[220:221], off
	v_lshl_add_u64 v[220:221], v[226:227], 0, s[4:5]
	s_mov_b32 m0, s37
	s_nop 0
	global_load_lds_dwordx4 v[220:221], off
	s_waitcnt vmcnt(8)
	s_waitcnt lgkmcnt(0)
	s_setprio 1
	s_barrier
	v_mfma_f32_16x16x32_bf16 v[62:65], v[148:151], v[188:191], v[62:65]
	v_mfma_f32_16x16x32_bf16 v[54:57], v[164:167], v[188:191], v[54:57]
	v_mfma_f32_16x16x32_bf16 v[46:49], v[148:151], v[196:199], v[46:49]
	v_mfma_f32_16x16x32_bf16 v[38:41], v[164:167], v[196:199], v[38:41]
	v_mfma_f32_16x16x32_bf16 v[30:33], v[148:151], v[204:207], v[30:33]
	v_mfma_f32_16x16x32_bf16 v[22:25], v[164:167], v[204:207], v[22:25]
	v_mfma_f32_16x16x32_bf16 v[14:17], v[148:151], v[212:215], v[14:17]
	v_mfma_f32_16x16x32_bf16 v[6:9], v[164:167], v[212:215], v[6:9]
	v_mfma_f32_16x16x32_bf16 v[62:65], v[160:163], v[192:195], v[62:65]
	v_mfma_f32_16x16x32_bf16 v[54:57], v[168:171], v[192:195], v[54:57]
	v_mfma_f32_16x16x32_bf16 v[46:49], v[160:163], v[200:203], v[46:49]
	v_mfma_f32_16x16x32_bf16 v[38:41], v[168:171], v[200:203], v[38:41]
	v_mfma_f32_16x16x32_bf16 v[30:33], v[160:163], v[208:211], v[30:33]
	v_mfma_f32_16x16x32_bf16 v[22:25], v[168:171], v[208:211], v[22:25]
	v_mfma_f32_16x16x32_bf16 v[14:17], v[160:163], v[216:219], v[14:17]
	v_mfma_f32_16x16x32_bf16 v[6:9], v[168:171], v[216:219], v[6:9]
	s_setprio 0
	s_setprio 1
	v_mfma_f32_16x16x32_bf16 v[58:61], v[172:175], v[188:191], v[58:61]
	v_mfma_f32_16x16x32_bf16 v[50:53], v[180:183], v[188:191], v[50:53]
	v_mfma_f32_16x16x32_bf16 v[42:45], v[172:175], v[196:199], v[42:45]
	v_mfma_f32_16x16x32_bf16 v[34:37], v[180:183], v[196:199], v[34:37]
	v_mfma_f32_16x16x32_bf16 v[26:29], v[172:175], v[204:207], v[26:29]
	v_mfma_f32_16x16x32_bf16 v[18:21], v[180:183], v[204:207], v[18:21]
	v_mfma_f32_16x16x32_bf16 v[10:13], v[172:175], v[212:215], v[10:13]
	v_mfma_f32_16x16x32_bf16 v[2:5], v[180:183], v[212:215], v[2:5]
	v_mfma_f32_16x16x32_bf16 v[58:61], v[176:179], v[192:195], v[58:61]
	v_mfma_f32_16x16x32_bf16 v[50:53], v[184:187], v[192:195], v[50:53]
	v_mfma_f32_16x16x32_bf16 v[42:45], v[176:179], v[200:203], v[42:45]
	v_mfma_f32_16x16x32_bf16 v[34:37], v[184:187], v[200:203], v[34:37]
	v_mfma_f32_16x16x32_bf16 v[26:29], v[176:179], v[208:211], v[26:29]
	v_mfma_f32_16x16x32_bf16 v[18:21], v[184:187], v[208:211], v[18:21]
	v_mfma_f32_16x16x32_bf16 v[10:13], v[176:179], v[216:219], v[10:13]
	v_mfma_f32_16x16x32_bf16 v[2:5], v[184:187], v[216:219], v[2:5]
	s_nop 0
	s_barrier
	s_setprio 0
	s_add_i32 s48, s48, 2
	s_add_u32 s22, s22, 0x100
	s_addc_u32 s23, s23, 0
	s_add_u32 s46, s46, 0x100
	s_addc_u32 s47, s47, 0
	s_cmp_gt_u32 s48, 29
	s_cbranch_scc0 .LBB0_1099
	s_and_b64 vcc, exec, s[8:9]
	s_cbranch_vccz .LBB0_1102
	s_barrier

; #define PG8_STAGE(bufoff, gbase, voff) do { _Pragma("unroll") for (int _i = 0; _i < 2; ++_i) \
;         __builtin_amdgcn_global_load_lds((const unsigned*)((const char*)(gbase) + (voff)[_i]), (PG8_LAS unsigned*)(lds + (bufoff) + ldsw + _i * 8192), 16, 0, 0); } while (0)
; #define PG8_WAIT_V(n) asm volatile("s_waitcnt vmcnt(" #n ")" ::: "memory")
; #define PG8_WAIT_L(n) asm volatile("s_waitcnt lgkmcnt(" #n ")" ::: "memory")
; #define PG8_BAR __builtin_amdgcn_s_barrier()
; #define PG8_SCHED __builtin_amdgcn_sched_barrier(0)
; template <class Epi, class Sched, bool ALIGN_EPI = true, bool SP2 = true>
; __device__ __forceinline__ void gemm_phase(PG8_LAS unsigned char* lds, const int K  , const Sched& S, const Epi& E) {
;     ...
;             const char* a1 = cA + (size_t)(t + 1) * kstep;
;             const char* a2 = last ? nA : cA + (size_t)(t + 2) * kstep; const char* b2 = last ? nB : cB + (size_t)(t + 2) * kstep;
;             const char* a3 = a2 + kstep; const char* b3 = b2 + kstep;
;             if constexpr (SP2) {
;             PG8_LDB(B0, 0, 0); PG8_LDB(B1, 0, 1); PG8_SCHED; PG8_LDA(At, 0, 0); PG8_STAGE(PG8_SA(1, 1), a1 + hstep, voffA);
;             PG8_WAIT_V(8); PG8_WAIT_L(0); PG8_BAR; PG8_MMA(0, 0, At, B0); PG8_MMA(0, 1, At, B1); PG8_BAR; PG8_SCHED;
;             PG8_LDA(At, 0, 1); PG8_STAGE(PG8_SB(0, 0), b2, voffB); PG8_STAGE(PG8_SB(0, 1), b2 + hstep, voffB); PG8_STAGE(PG8_SA(0, 0), a2, voffA);
;             PG8_WAIT_V(8); PG8_WAIT_L(0); PG8_BAR; PG8_MMA(1, 0, At, B0); PG8_MMA(1, 1, At, B1); PG8_BAR; PG8_SCHED;
.LBB0_1304:
	ds_read_b128 v[18:21], v233
	ds_read_b128 v[22:25], v233 offset:1024
	ds_read_b128 v[26:29], v233 offset:2048
	ds_read_b128 v[30:33], v233 offset:3072
	ds_read_b128 v[2:5], v234
	ds_read_b128 v[6:9], v234 offset:1024
	ds_read_b128 v[10:13], v234 offset:2048
	ds_read_b128 v[14:17], v234 offset:3072
	s_add_i32 s74, s22, 2
	s_add_u32 s20, s18, 0xfff50080
	s_addc_u32 s21, s19, -1
	s_cmp_eq_u32 s71, s22
	s_cselect_b32 s22, s14, s20
	s_cselect_b32 s23, s15, s21
	s_cselect_b32 s21, s17, s73
	s_cselect_b32 s20, s16, s72
	v_lshl_add_u64 v[186:187], s[18:19], 0, v[198:199]
	s_add_i32 m0, s26, 0xc000
	ds_read_b128 v[162:165], v235
	ds_read_b128 v[166:169], v235 offset:1024
	ds_read_b128 v[170:173], v235 offset:2048
	ds_read_b128 v[174:177], v235 offset:3072
	ds_read_b128 v[178:181], v235 offset:4096
	ds_read_b128 v[182:185], v235 offset:5120
	ds_read_b128 v[206:209], v235 offset:6144
	ds_read_b128 v[210:213], v235 offset:7168
	global_load_lds_dwordx4 v[186:187], off
	v_lshl_add_u64 v[186:187], s[18:19], 0, v[200:201]
	s_add_i32 m0, s26, 0xe000
	s_nop 0
	global_load_lds_dwordx4 v[186:187], off
	s_waitcnt vmcnt(8)
	s_waitcnt lgkmcnt(0)
	s_setprio 1
	s_barrier
	v_mfma_scale_f32_16x16x128_f8f6f4 v[158:161], v[18:25], v[162:169], v[158:161], v229, v229 op_sel_hi:[0,0,0]
	v_mfma_scale_f32_16x16x128_f8f6f4 v[154:157], v[26:33], v[162:169], v[154:157], v229, v229 op_sel_hi:[0,0,0]
	v_mfma_scale_f32_16x16x128_f8f6f4 v[150:153], v[18:25], v[170:177], v[150:153], v229, v229 op_sel_hi:[0,0,0]
	v_mfma_scale_f32_16x16x128_f8f6f4 v[142:145], v[26:33], v[170:177], v[142:145], v229, v229 op_sel_hi:[0,0,0]
	v_mfma_scale_f32_16x16x128_f8f6f4 v[134:137], v[18:25], v[178:185], v[134:137], v229, v229 op_sel_hi:[0,0,0]
	v_mfma_scale_f32_16x16x128_f8f6f4 v[126:129], v[26:33], v[178:185], v[126:129], v229, v229 op_sel_hi:[0,0,0]
	v_mfma_scale_f32_16x16x128_f8f6f4 v[118:121], v[18:25], v[206:213], v[118:121], v229, v229 op_sel_hi:[0,0,0]
	v_mfma_scale_f32_16x16x128_f8f6f4 v[110:113], v[26:33], v[206:213], v[110:113], v229, v229 op_sel_hi:[0,0,0]
	s_setprio 0
	s_setprio 1
	v_mfma_scale_f32_16x16x128_f8f6f4 v[146:149], v[2:9], v[162:169], v[146:149], v229, v229 op_sel_hi:[0,0,0]
	v_mfma_scale_f32_16x16x128_f8f6f4 v[138:141], v[10:17], v[162:169], v[138:141], v229, v229 op_sel_hi:[0,0,0]
	v_mfma_scale_f32_16x16x128_f8f6f4 v[130:133], v[2:9], v[170:177], v[130:133], v229, v229 op_sel_hi:[0,0,0]
	v_mfma_scale_f32_16x16x128_f8f6f4 v[122:125], v[10:17], v[170:177], v[122:125], v229, v229 op_sel_hi:[0,0,0]
	v_mfma_scale_f32_16x16x128_f8f6f4 v[114:117], v[2:9], v[178:185], v[114:117], v229, v229 op_sel_hi:[0,0,0]
	v_mfma_scale_f32_16x16x128_f8f6f4 v[106:109], v[10:17], v[178:185], v[106:109], v229, v229 op_sel_hi:[0,0,0]
	v_mfma_scale_f32_16x16x128_f8f6f4 v[102:105], v[2:9], v[206:213], v[102:105], v229, v229 op_sel_hi:[0,0,0]
	v_mfma_scale_f32_16x16x128_f8f6f4 v[98:101], v[10:17], v[206:213], v[98:101], v229, v229 op_sel_hi:[0,0,0]
	s_nop 0
	s_barrier
	s_setprio 0
	s_add_i32 s75, s40, s25
	v_lshl_add_u64 v[162:163], s[20:21], 0, v[192:193]
	s_mov_b32 m0, s75
	ds_read_b128 v[170:173], v235 offset:16384
	ds_read_b128 v[174:177], v235 offset:17408
	ds_read_b128 v[178:181], v235 offset:18432
	ds_read_b128 v[182:185], v235 offset:19456
	ds_read_b128 v[206:209], v235 offset:20480
	ds_read_b128 v[210:213], v235 offset:21504
	ds_read_b128 v[214:217], v235 offset:22528
	ds_read_b128 v[218:221], v235 offset:23552
	global_load_lds_dwordx4 v[162:163], off
	s_add_i32 m0, s75, 0x2000
	s_add_u32 s76, s20, 0xb0000
	v_lshl_add_u64 v[164:165], s[20:21], 0, v[196:197]
	s_addc_u32 s77, s21, 0
	s_add_i32 s75, s41, s25
	global_load_lds_dwordx4 v[164:165], off
	v_lshl_add_u64 v[166:167], s[76:77], 0, v[192:193]
	s_mov_b32 m0, s75
	v_lshl_add_u64 v[168:169], s[22:23], 0, v[194:195]
	global_load_lds_dwordx4 v[166:167], off
	v_lshl_add_u64 v[166:167], s[76:77], 0, v[196:197]
	s_add_i32 m0, s75, 0x2000
	s_nop 0
	global_load_lds_dwordx4 v[166:167], off
	v_lshl_add_u64 v[166:167], s[22:23], 0, v[190:191]
	s_mov_b32 m0, s26
	s_nop 0
	global_load_lds_dwordx4 v[166:167], off
	s_mov_b32 m0, s27
	s_nop 0
	global_load_lds_dwordx4 v[168:169], off
	s_waitcnt vmcnt(8)
	s_waitcnt lgkmcnt(0)
	s_setprio 1
	s_barrier
	v_mfma_scale_f32_16x16x128_f8f6f4 v[94:97], v[18:25], v[170:177], v[94:97], v229, v229 op_sel_hi:[0,0,0]
	v_mfma_scale_f32_16x16x128_f8f6f4 v[90:93], v[26:33], v[170:177], v[90:93], v229, v229 op_sel_hi:[0,0,0]
	v_mfma_scale_f32_16x16x128_f8f6f4 v[86:89], v[18:25], v[178:185], v[86:89], v229, v229 op_sel_hi:[0,0,0]
	v_mfma_scale_f32_16x16x128_f8f6f4 v[78:81], v[26:33], v[178:185], v[78:81], v229, v229 op_sel_hi:[0,0,0]
	v_mfma_scale_f32_16x16x128_f8f6f4 v[70:73], v[18:25], v[206:213], v[70:73], v229, v229 op_sel_hi:[0,0,0]
	v_mfma_scale_f32_16x16x128_f8f6f4 v[62:65], v[26:33], v[206:213], v[62:65], v229, v229 op_sel_hi:[0,0,0]
	v_mfma_scale_f32_16x16x128_f8f6f4 v[54:57], v[18:25], v[214:221], v[54:57], v229, v229 op_sel_hi:[0,0,0]
	v_mfma_scale_f32_16x16x128_f8f6f4 v[46:49], v[26:33], v[214:221], v[46:49], v229, v229 op_sel_hi:[0,0,0]
	s_setprio 0
	s_setprio 1
	v_mfma_scale_f32_16x16x128_f8f6f4 v[82:85], v[2:9], v[170:177], v[82:85], v229, v229 op_sel_hi:[0,0,0]
	v_mfma_scale_f32_16x16x128_f8f6f4 v[74:77], v[10:17], v[170:177], v[74:77], v229, v229 op_sel_hi:[0,0,0]
	v_mfma_scale_f32_16x16x128_f8f6f4 v[66:69], v[2:9], v[178:185], v[66:69], v229, v229 op_sel_hi:[0,0,0]
	v_mfma_scale_f32_16x16x128_f8f6f4 v[58:61], v[10:17], v[178:185], v[58:61], v229, v229 op_sel_hi:[0,0,0]
	v_mfma_scale_f32_16x16x128_f8f6f4 v[50:53], v[2:9], v[206:213], v[50:53], v229, v229 op_sel_hi:[0,0,0]
	v_mfma_scale_f32_16x16x128_f8f6f4 v[42:45], v[10:17], v[206:213], v[42:45], v229, v229 op_sel_hi:[0,0,0]
	v_mfma_scale_f32_16x16x128_f8f6f4 v[38:41], v[2:9], v[214:221], v[38:41], v229, v229 op_sel_hi:[0,0,0]
	v_mfma_scale_f32_16x16x128_f8f6f4 v[34:37], v[10:17], v[214:221], v[34:37], v229, v229 op_sel_hi:[0,0,0]
	s_nop 0
	s_barrier
; #define PG8_STAGE(bufoff, gbase, voff) do { _Pragma("unroll") for (int _i = 0; _i < 2; ++_i) \
;         __builtin_amdgcn_global_load_lds((const unsigned*)((const char*)(gbase) + (voff)[_i]), (PG8_LAS unsigned*)(lds + (bufoff) + ldsw + _i * 8192), 16, 0, 0); } while (0)
; #define PG8_WAIT_V(n) asm volatile("s_waitcnt vmcnt(" #n ")" ::: "memory")
; #define PG8_WAIT_L(n) asm volatile("s_waitcnt lgkmcnt(" #n ")" ::: "memory")
; #define PG8_BAR __builtin_amdgcn_s_barrier()
; #define PG8_SCHED __builtin_amdgcn_sched_barrier(0)
; template <class Epi, class Sched, bool ALIGN_EPI = true, bool SP2 = true>
; __device__ __forceinline__ void gemm_phase(PG8_LAS unsigned char* lds, const int K  , const Sched& S, const Epi& E) {
;     ...
;             PG8_LDB(B0, 1, 0); PG8_LDB(B1, 1, 1); PG8_SCHED; PG8_LDA(At, 1, 0); PG8_STAGE(PG8_SA(0, 1), a2 + hstep, voffA);
;             PG8_WAIT_V(8); PG8_WAIT_L(0); PG8_BAR; PG8_MMA(0, 0, At, B0); PG8_MMA(0, 1, At, B1); PG8_BAR; PG8_SCHED;
;             PG8_LDA(At, 1, 1); PG8_STAGE(PG8_SB(1, 0), b3, voffB); PG8_STAGE(PG8_SB(1, 1), b3 + hstep, voffB); PG8_STAGE(PG8_SA(1, 0), a3, voffA);
;             PG8_WAIT_V(8); PG8_WAIT_L(0); PG8_BAR; PG8_MMA(1, 0, At, B0); PG8_MMA(1, 1, At, B1); PG8_BAR; PG8_SCHED;
;     ...
;         if constexpr (Epi::FP8) asm volatile("s_nop 15\n\ts_nop 15\n\ts_nop 15\n\ts_nop 15\n\ts_nop 15" ::: "memory");
;         if constexpr (ALIGN_EPI) { if (wr == 0) PG8_BAR; }
	s_setprio 0
	s_add_i32 s75, 0, 0x18000
	s_add_i32 s76, 0, 0x1c000
	v_add_u32_e32 v14, s75, v231
	v_add_u32_e32 v30, s76, v231
	ds_read_b128 v[2:5], v14
	ds_read_b128 v[6:9], v14 offset:1024
	ds_read_b128 v[10:13], v14 offset:2048
	ds_read_b128 v[14:17], v14 offset:3072
	ds_read_b128 v[18:21], v30
	ds_read_b128 v[22:25], v30 offset:1024
	ds_read_b128 v[26:29], v30 offset:2048
	ds_read_b128 v[30:33], v30 offset:3072
	s_add_u32 s22, s22, 0xb0000
	s_addc_u32 s23, s23, 0
	s_mov_b32 m0, s28
	v_lshl_add_u64 v[186:187], s[22:23], 0, v[190:191]
	ds_read_b128 v[170:173], v235 offset:32768
	ds_read_b128 v[174:177], v235 offset:33792
	ds_read_b128 v[178:181], v235 offset:34816
	ds_read_b128 v[182:185], v235 offset:35840
	ds_read_b128 v[206:209], v235 offset:36864
	ds_read_b128 v[210:213], v235 offset:37888
	ds_read_b128 v[214:217], v235 offset:38912
	ds_read_b128 v[218:221], v235 offset:39936
	global_load_lds_dwordx4 v[186:187], off
	v_lshl_add_u64 v[186:187], s[22:23], 0, v[194:195]
	s_mov_b32 m0, s29
	s_nop 0
	global_load_lds_dwordx4 v[186:187], off
	s_waitcnt vmcnt(8)
	s_waitcnt lgkmcnt(0)
	s_setprio 1
	s_barrier
	v_mfma_scale_f32_16x16x128_f8f6f4 v[158:161], v[2:9], v[170:177], v[158:161], v229, v229 op_sel_hi:[0,0,0]
	v_mfma_scale_f32_16x16x128_f8f6f4 v[154:157], v[10:17], v[170:177], v[154:157], v229, v229 op_sel_hi:[0,0,0]
	v_mfma_scale_f32_16x16x128_f8f6f4 v[150:153], v[2:9], v[178:185], v[150:153], v229, v229 op_sel_hi:[0,0,0]
	v_mfma_scale_f32_16x16x128_f8f6f4 v[142:145], v[10:17], v[178:185], v[142:145], v229, v229 op_sel_hi:[0,0,0]
	v_mfma_scale_f32_16x16x128_f8f6f4 v[134:137], v[2:9], v[206:213], v[134:137], v229, v229 op_sel_hi:[0,0,0]
	v_mfma_scale_f32_16x16x128_f8f6f4 v[126:129], v[10:17], v[206:213], v[126:129], v229, v229 op_sel_hi:[0,0,0]
	v_mfma_scale_f32_16x16x128_f8f6f4 v[118:121], v[2:9], v[214:221], v[118:121], v229, v229 op_sel_hi:[0,0,0]
	v_mfma_scale_f32_16x16x128_f8f6f4 v[110:113], v[10:17], v[214:221], v[110:113], v229, v229 op_sel_hi:[0,0,0]
	s_setprio 0
	s_setprio 1
	v_mfma_scale_f32_16x16x128_f8f6f4 v[146:149], v[18:25], v[170:177], v[146:149], v229, v229 op_sel_hi:[0,0,0]
	v_mfma_scale_f32_16x16x128_f8f6f4 v[138:141], v[26:33], v[170:177], v[138:141], v229, v229 op_sel_hi:[0,0,0]
	v_mfma_scale_f32_16x16x128_f8f6f4 v[130:133], v[18:25], v[178:185], v[130:133], v229, v229 op_sel_hi:[0,0,0]
	v_mfma_scale_f32_16x16x128_f8f6f4 v[122:125], v[26:33], v[178:185], v[122:125], v229, v229 op_sel_hi:[0,0,0]
	v_mfma_scale_f32_16x16x128_f8f6f4 v[114:117], v[18:25], v[206:213], v[114:117], v229, v229 op_sel_hi:[0,0,0]
	v_mfma_scale_f32_16x16x128_f8f6f4 v[106:109], v[26:33], v[206:213], v[106:109], v229, v229 op_sel_hi:[0,0,0]
	v_mfma_scale_f32_16x16x128_f8f6f4 v[102:105], v[18:25], v[214:221], v[102:105], v229, v229 op_sel_hi:[0,0,0]
	v_mfma_scale_f32_16x16x128_f8f6f4 v[98:101], v[26:33], v[214:221], v[98:101], v229, v229 op_sel_hi:[0,0,0]
	s_nop 0
	s_barrier
	s_setprio 0
	s_add_i32 s22, s75, s25
	v_lshl_add_u64 v[162:163], v[162:163], 0, s[8:9]
	s_mov_b32 m0, s22
	ds_read_b128 v[170:173], v235 offset:49152
	ds_read_b128 v[174:177], v235 offset:50176
	ds_read_b128 v[178:181], v235 offset:51200
	ds_read_b128 v[182:185], v235 offset:52224
	ds_read_b128 v[206:209], v235 offset:53248
	ds_read_b128 v[210:213], v235 offset:54272
	ds_read_b128 v[214:217], v235 offset:55296
	ds_read_b128 v[218:221], v235 offset:56320
	global_load_lds_dwordx4 v[162:163], off
	s_add_i32 m0, s22, 0x2000
	s_add_u32 s20, s20, 0xb0080
	v_lshl_add_u64 v[162:163], v[164:165], 0, s[8:9]
	s_addc_u32 s21, s21, 0
	s_add_i32 s22, s76, s25
	global_load_lds_dwordx4 v[162:163], off
	v_lshl_add_u64 v[162:163], s[20:21], 0, v[192:193]
	s_mov_b32 m0, s22
	s_nop 0
	global_load_lds_dwordx4 v[162:163], off
	v_lshl_add_u64 v[162:163], s[20:21], 0, v[196:197]
	s_add_i32 m0, s22, 0x2000
	s_nop 0
	global_load_lds_dwordx4 v[162:163], off
	v_lshl_add_u64 v[162:163], v[166:167], 0, s[8:9]
	s_mov_b32 m0, s36
	s_nop 0
	global_load_lds_dwordx4 v[162:163], off
	v_lshl_add_u64 v[162:163], v[168:169], 0, s[8:9]
	s_mov_b32 m0, s37
	s_nop 0
	global_load_lds_dwordx4 v[162:163], off
	s_waitcnt vmcnt(8)
	s_waitcnt lgkmcnt(0)
	s_setprio 1
	s_barrier
	v_mfma_scale_f32_16x16x128_f8f6f4 v[94:97], v[2:9], v[170:177], v[94:97], v229, v229 op_sel_hi:[0,0,0]
	v_mfma_scale_f32_16x16x128_f8f6f4 v[90:93], v[10:17], v[170:177], v[90:93], v229, v229 op_sel_hi:[0,0,0]
	v_mfma_scale_f32_16x16x128_f8f6f4 v[86:89], v[2:9], v[178:185], v[86:89], v229, v229 op_sel_hi:[0,0,0]
	v_mfma_scale_f32_16x16x128_f8f6f4 v[78:81], v[10:17], v[178:185], v[78:81], v229, v229 op_sel_hi:[0,0,0]
	v_mfma_scale_f32_16x16x128_f8f6f4 v[70:73], v[2:9], v[206:213], v[70:73], v229, v229 op_sel_hi:[0,0,0]
	v_mfma_scale_f32_16x16x128_f8f6f4 v[62:65], v[10:17], v[206:213], v[62:65], v229, v229 op_sel_hi:[0,0,0]
	v_mfma_scale_f32_16x16x128_f8f6f4 v[54:57], v[2:9], v[214:221], v[54:57], v229, v229 op_sel_hi:[0,0,0]
	v_mfma_scale_f32_16x16x128_f8f6f4 v[46:49], v[10:17], v[214:221], v[46:49], v229, v229 op_sel_hi:[0,0,0]
	s_setprio 0
	s_setprio 1
	v_mfma_scale_f32_16x16x128_f8f6f4 v[82:85], v[18:25], v[170:177], v[82:85], v229, v229 op_sel_hi:[0,0,0]
	v_mfma_scale_f32_16x16x128_f8f6f4 v[74:77], v[26:33], v[170:177], v[74:77], v229, v229 op_sel_hi:[0,0,0]
	v_mfma_scale_f32_16x16x128_f8f6f4 v[66:69], v[18:25], v[178:185], v[66:69], v229, v229 op_sel_hi:[0,0,0]
	v_mfma_scale_f32_16x16x128_f8f6f4 v[58:61], v[26:33], v[178:185], v[58:61], v229, v229 op_sel_hi:[0,0,0]
	v_mfma_scale_f32_16x16x128_f8f6f4 v[50:53], v[18:25], v[206:213], v[50:53], v229, v229 op_sel_hi:[0,0,0]
	v_mfma_scale_f32_16x16x128_f8f6f4 v[42:45], v[26:33], v[206:213], v[42:45], v229, v229 op_sel_hi:[0,0,0]
	v_mfma_scale_f32_16x16x128_f8f6f4 v[38:41], v[18:25], v[214:221], v[38:41], v229, v229 op_sel_hi:[0,0,0]
	v_mfma_scale_f32_16x16x128_f8f6f4 v[34:37], v[26:33], v[214:221], v[34:37], v229, v229 op_sel_hi:[0,0,0]
	s_nop 0
	s_barrier
	s_setprio 0
	s_add_u32 s18, s18, 0x100
	s_addc_u32 s19, s19, 0
	s_add_u32 s72, s72, 0x100
	s_addc_u32 s73, s73, 0
	s_cmp_ge_u32 s74, s4
	s_mov_b32 s22, s74
	s_cbranch_scc0 .LBB0_1304
	s_nop 15
	s_nop 15
	s_nop 15
	s_nop 15
	s_nop 15
	s_and_b64 vcc, exec, s[10:11]
	s_cbranch_vccz .LBB0_1307
	s_barrier

; #define PG8_STAGE(bufoff, gbase, voff) do { _Pragma("unroll") for (int _i = 0; _i < 2; ++_i) \
;         __builtin_amdgcn_global_load_lds((const unsigned*)((const char*)(gbase) + (voff)[_i]), (PG8_LAS unsigned*)(lds + (bufoff) + ldsw + _i * 8192), 16, 0, 0); } while (0)
; #define PG8_WAIT_V(n) asm volatile("s_waitcnt vmcnt(" #n ")" ::: "memory")
; #define PG8_WAIT_L(n) asm volatile("s_waitcnt lgkmcnt(" #n ")" ::: "memory")
; #define PG8_BAR __builtin_amdgcn_s_barrier()
; #define PG8_SCHED __builtin_amdgcn_sched_barrier(0)
; template <class Epi, class Sched, bool ALIGN_EPI = true, bool SP2 = true>
; __device__ __forceinline__ void gemm_phase(PG8_LAS unsigned char* lds, const int K  , const Sched& S, const Epi& E) {
;     ...
;             PG8_LDB(B0, 0, 0); PG8_LDB(B1, 0, 1); PG8_SCHED; PG8_LDA(At, 0, 0); PG8_STAGE(PG8_SA(1, 1), a1 + hstep, voffA);
;             PG8_WAIT_V(8); PG8_WAIT_L(0); PG8_BAR; PG8_MMA(0, 0, At, B0); PG8_MMA(0, 1, At, B1); PG8_BAR; PG8_SCHED;
;             PG8_LDA(At, 0, 1); PG8_STAGE(PG8_SB(0, 0), b2, voffB); PG8_STAGE(PG8_SB(0, 1), b2 + hstep, voffB); PG8_STAGE(PG8_SA(0, 0), a2, voffA);
;             PG8_WAIT_V(8); PG8_WAIT_L(0); PG8_BAR; PG8_MMA(1, 0, At, B0); PG8_MMA(1, 1, At, B1); PG8_BAR; PG8_SCHED;
.LBB0_1448:
	ds_read_b128 v[148:151], v154
	ds_read_b128 v[160:163], v154 offset:1024
	ds_read_b128 v[164:167], v154 offset:2048
	ds_read_b128 v[168:171], v154 offset:3072
	ds_read_b128 v[172:175], v155
	ds_read_b128 v[176:179], v155 offset:1024
	ds_read_b128 v[180:183], v155 offset:2048
	ds_read_b128 v[184:187], v155 offset:3072
	s_add_u32 s26, s24, 0xfff80080
	s_addc_u32 s27, s25, -1
	s_cmp_eq_u32 s50, 28
	s_cselect_b32 s29, s17, s27
	s_cselect_b32 s28, s46, s26
	s_cselect_b32 s27, s11, s49
	s_cselect_b32 s26, s47, s48
	v_lshl_add_u64 v[220:221], s[24:25], 0, v[140:141]
	s_add_i32 m0, s23, 0xc000
	ds_read_b128 v[188:191], v156
	ds_read_b128 v[192:195], v156 offset:1024
	ds_read_b128 v[196:199], v156 offset:2048
	ds_read_b128 v[200:203], v156 offset:3072
	ds_read_b128 v[204:207], v156 offset:4096
	ds_read_b128 v[208:211], v156 offset:5120
	ds_read_b128 v[212:215], v156 offset:6144
	ds_read_b128 v[216:219], v156 offset:7168
	global_load_lds_dwordx4 v[220:221], off
	v_lshl_add_u64 v[220:221], s[24:25], 0, v[142:143]
	s_add_i32 m0, s23, 0xe000
	s_nop 0
	global_load_lds_dwordx4 v[220:221], off
	s_waitcnt vmcnt(8)
	s_waitcnt lgkmcnt(0)
	s_setprio 1
	s_barrier
	v_mfma_f32_16x16x32_bf16 v[126:129], v[148:151], v[188:191], v[126:129]
	v_mfma_f32_16x16x32_bf16 v[118:121], v[164:167], v[188:191], v[118:121]
	v_mfma_f32_16x16x32_bf16 v[110:113], v[148:151], v[196:199], v[110:113]
	v_mfma_f32_16x16x32_bf16 v[102:105], v[164:167], v[196:199], v[102:105]
	v_mfma_f32_16x16x32_bf16 v[94:97], v[148:151], v[204:207], v[94:97]
	v_mfma_f32_16x16x32_bf16 v[86:89], v[164:167], v[204:207], v[86:89]
	v_mfma_f32_16x16x32_bf16 v[78:81], v[148:151], v[212:215], v[78:81]
	v_mfma_f32_16x16x32_bf16 v[70:73], v[164:167], v[212:215], v[70:73]
	v_mfma_f32_16x16x32_bf16 v[126:129], v[160:163], v[192:195], v[126:129]
	v_mfma_f32_16x16x32_bf16 v[118:121], v[168:171], v[192:195], v[118:121]
	v_mfma_f32_16x16x32_bf16 v[110:113], v[160:163], v[200:203], v[110:113]
	v_mfma_f32_16x16x32_bf16 v[102:105], v[168:171], v[200:203], v[102:105]
	v_mfma_f32_16x16x32_bf16 v[94:97], v[160:163], v[208:211], v[94:97]
	v_mfma_f32_16x16x32_bf16 v[86:89], v[168:171], v[208:211], v[86:89]
	v_mfma_f32_16x16x32_bf16 v[78:81], v[160:163], v[216:219], v[78:81]
	v_mfma_f32_16x16x32_bf16 v[70:73], v[168:171], v[216:219], v[70:73]
	s_setprio 0
	s_setprio 1
	v_mfma_f32_16x16x32_bf16 v[122:125], v[172:175], v[188:191], v[122:125]
	v_mfma_f32_16x16x32_bf16 v[114:117], v[180:183], v[188:191], v[114:117]
	v_mfma_f32_16x16x32_bf16 v[106:109], v[172:175], v[196:199], v[106:109]
	v_mfma_f32_16x16x32_bf16 v[98:101], v[180:183], v[196:199], v[98:101]
	v_mfma_f32_16x16x32_bf16 v[90:93], v[172:175], v[204:207], v[90:93]
	v_mfma_f32_16x16x32_bf16 v[82:85], v[180:183], v[204:207], v[82:85]
	v_mfma_f32_16x16x32_bf16 v[74:77], v[172:175], v[212:215], v[74:77]
	v_mfma_f32_16x16x32_bf16 v[66:69], v[180:183], v[212:215], v[66:69]
	v_mfma_f32_16x16x32_bf16 v[122:125], v[176:179], v[192:195], v[122:125]
	v_mfma_f32_16x16x32_bf16 v[114:117], v[184:187], v[192:195], v[114:117]
	v_mfma_f32_16x16x32_bf16 v[106:109], v[176:179], v[200:203], v[106:109]
	v_mfma_f32_16x16x32_bf16 v[98:101], v[184:187], v[200:203], v[98:101]
	v_mfma_f32_16x16x32_bf16 v[90:93], v[176:179], v[208:211], v[90:93]
	v_mfma_f32_16x16x32_bf16 v[82:85], v[184:187], v[208:211], v[82:85]
	v_mfma_f32_16x16x32_bf16 v[74:77], v[176:179], v[216:219], v[74:77]
	v_mfma_f32_16x16x32_bf16 v[66:69], v[184:187], v[216:219], v[66:69]
	s_nop 0
	s_barrier
	s_setprio 0
	s_add_i32 s51, s41, s31
	v_lshl_add_u64 v[220:221], s[26:27], 0, v[136:137]
	s_mov_b32 m0, s51
	ds_read_b128 v[188:191], v156 offset:16384
	ds_read_b128 v[192:195], v156 offset:17408
	ds_read_b128 v[196:199], v156 offset:18432
	ds_read_b128 v[200:203], v156 offset:19456
	ds_read_b128 v[204:207], v156 offset:20480
	ds_read_b128 v[208:211], v156 offset:21504
	ds_read_b128 v[212:215], v156 offset:22528
	ds_read_b128 v[216:219], v156 offset:23552
	global_load_lds_dwordx4 v[220:221], off
	s_add_i32 m0, s51, 0x2000
	s_add_u32 s68, s26, 0x80000
	v_lshl_add_u64 v[222:223], s[26:27], 0, v[132:133]
	s_addc_u32 s69, s27, 0
	s_add_i32 s51, s42, s31
	global_load_lds_dwordx4 v[222:223], off
	v_lshl_add_u64 v[224:225], s[68:69], 0, v[136:137]
	s_mov_b32 m0, s51
	v_lshl_add_u64 v[226:227], s[28:29], 0, v[134:135]
	global_load_lds_dwordx4 v[224:225], off
	v_lshl_add_u64 v[224:225], s[68:69], 0, v[132:133]
	s_add_i32 m0, s51, 0x2000
	s_nop 0
	global_load_lds_dwordx4 v[224:225], off
	v_lshl_add_u64 v[224:225], s[28:29], 0, v[138:139]
	s_mov_b32 m0, s23
	s_nop 0
	global_load_lds_dwordx4 v[224:225], off
	s_mov_b32 m0, s34
	s_nop 0
	global_load_lds_dwordx4 v[226:227], off
	s_waitcnt vmcnt(8)
	s_waitcnt lgkmcnt(0)
	s_setprio 1
	s_barrier
; #define PG8_STAGE(bufoff, gbase, voff) do { _Pragma("unroll") for (int _i = 0; _i < 2; ++_i) \
;         __builtin_amdgcn_global_load_lds((const unsigned*)((const char*)(gbase) + (voff)[_i]), (PG8_LAS unsigned*)(lds + (bufoff) + ldsw + _i * 8192), 16, 0, 0); } while (0)
; #define PG8_WAIT_V(n) asm volatile("s_waitcnt vmcnt(" #n ")" ::: "memory")
; #define PG8_WAIT_L(n) asm volatile("s_waitcnt lgkmcnt(" #n ")" ::: "memory")
; #define PG8_BAR __builtin_amdgcn_s_barrier()
; #define PG8_SCHED __builtin_amdgcn_sched_barrier(0)
; template <class Epi, class Sched, bool ALIGN_EPI = true, bool SP2 = true>
; __device__ __forceinline__ void gemm_phase(PG8_LAS unsigned char* lds, const int K  , const Sched& S, const Epi& E) {
;     ...
;             PG8_WAIT_V(8); PG8_WAIT_L(0); PG8_BAR; PG8_MMA(1, 0, At, B0); PG8_MMA(1, 1, At, B1); PG8_BAR; PG8_SCHED;
;             PG8_LDB(B0, 1, 0); PG8_LDB(B1, 1, 1); PG8_SCHED; PG8_LDA(At, 1, 0); PG8_STAGE(PG8_SA(0, 1), a2 + hstep, voffA);
;             PG8_WAIT_V(8); PG8_WAIT_L(0); PG8_BAR; PG8_MMA(0, 0, At, B0); PG8_MMA(0, 1, At, B1); PG8_BAR; PG8_SCHED;
	v_mfma_f32_16x16x32_bf16 v[62:65], v[148:151], v[188:191], v[62:65]
	v_mfma_f32_16x16x32_bf16 v[54:57], v[164:167], v[188:191], v[54:57]
	v_mfma_f32_16x16x32_bf16 v[46:49], v[148:151], v[196:199], v[46:49]
	v_mfma_f32_16x16x32_bf16 v[38:41], v[164:167], v[196:199], v[38:41]
	v_mfma_f32_16x16x32_bf16 v[30:33], v[148:151], v[204:207], v[30:33]
	v_mfma_f32_16x16x32_bf16 v[22:25], v[164:167], v[204:207], v[22:25]
	v_mfma_f32_16x16x32_bf16 v[14:17], v[148:151], v[212:215], v[14:17]
	v_mfma_f32_16x16x32_bf16 v[6:9], v[164:167], v[212:215], v[6:9]
	v_mfma_f32_16x16x32_bf16 v[62:65], v[160:163], v[192:195], v[62:65]
	v_mfma_f32_16x16x32_bf16 v[54:57], v[168:171], v[192:195], v[54:57]
	v_mfma_f32_16x16x32_bf16 v[46:49], v[160:163], v[200:203], v[46:49]
	v_mfma_f32_16x16x32_bf16 v[38:41], v[168:171], v[200:203], v[38:41]
	v_mfma_f32_16x16x32_bf16 v[30:33], v[160:163], v[208:211], v[30:33]
	v_mfma_f32_16x16x32_bf16 v[22:25], v[168:171], v[208:211], v[22:25]
	v_mfma_f32_16x16x32_bf16 v[14:17], v[160:163], v[216:219], v[14:17]
	v_mfma_f32_16x16x32_bf16 v[6:9], v[168:171], v[216:219], v[6:9]
	s_setprio 0
	s_setprio 1
	v_mfma_f32_16x16x32_bf16 v[58:61], v[172:175], v[188:191], v[58:61]
	v_mfma_f32_16x16x32_bf16 v[50:53], v[180:183], v[188:191], v[50:53]
	v_mfma_f32_16x16x32_bf16 v[42:45], v[172:175], v[196:199], v[42:45]
	v_mfma_f32_16x16x32_bf16 v[34:37], v[180:183], v[196:199], v[34:37]
	v_mfma_f32_16x16x32_bf16 v[26:29], v[172:175], v[204:207], v[26:29]
	v_mfma_f32_16x16x32_bf16 v[18:21], v[180:183], v[204:207], v[18:21]
	v_mfma_f32_16x16x32_bf16 v[10:13], v[172:175], v[212:215], v[10:13]
	v_mfma_f32_16x16x32_bf16 v[2:5], v[180:183], v[212:215], v[2:5]
	v_mfma_f32_16x16x32_bf16 v[58:61], v[176:179], v[192:195], v[58:61]
	v_mfma_f32_16x16x32_bf16 v[50:53], v[184:187], v[192:195], v[50:53]
	v_mfma_f32_16x16x32_bf16 v[42:45], v[176:179], v[200:203], v[42:45]
	v_mfma_f32_16x16x32_bf16 v[34:37], v[184:187], v[200:203], v[34:37]
	v_mfma_f32_16x16x32_bf16 v[26:29], v[176:179], v[208:211], v[26:29]
	v_mfma_f32_16x16x32_bf16 v[18:21], v[184:187], v[208:211], v[18:21]
	v_mfma_f32_16x16x32_bf16 v[10:13], v[176:179], v[216:219], v[10:13]
	v_mfma_f32_16x16x32_bf16 v[2:5], v[184:187], v[216:219], v[2:5]
	s_nop 0
	s_barrier
	s_setprio 0
	s_add_i32 s51, 0, 0x18000
	v_add_u32_e32 v159, s51, v152
	s_add_i32 s68, 0, 0x1c000
	ds_read_b128 v[148:151], v159
	ds_read_b128 v[160:163], v159 offset:1024
	ds_read_b128 v[164:167], v159 offset:2048
	ds_read_b128 v[168:171], v159 offset:3072
	v_add_u32_e32 v159, s68, v152
	ds_read_b128 v[172:175], v159
	ds_read_b128 v[176:179], v159 offset:1024
	ds_read_b128 v[180:183], v159 offset:2048
	ds_read_b128 v[184:187], v159 offset:3072
	s_add_u32 s28, s28, 0x80000
	s_addc_u32 s29, s29, 0
	s_mov_b32 m0, s35
	v_lshl_add_u64 v[230:231], s[28:29], 0, v[138:139]
	ds_read_b128 v[188:191], v156 offset:32768
	ds_read_b128 v[192:195], v156 offset:33792
	ds_read_b128 v[196:199], v156 offset:34816
	ds_read_b128 v[200:203], v156 offset:35840
	ds_read_b128 v[204:207], v156 offset:36864
	ds_read_b128 v[208:211], v156 offset:37888
	ds_read_b128 v[212:215], v156 offset:38912
	ds_read_b128 v[216:219], v156 offset:39936
	global_load_lds_dwordx4 v[230:231], off
	v_lshl_add_u64 v[230:231], s[28:29], 0, v[134:135]
	s_mov_b32 m0, s36
	s_nop 0
	global_load_lds_dwordx4 v[230:231], off
	s_waitcnt vmcnt(8)
	s_waitcnt lgkmcnt(0)
	s_setprio 1
	s_barrier
	v_mfma_f32_16x16x32_bf16 v[126:129], v[148:151], v[188:191], v[126:129]
	v_mfma_f32_16x16x32_bf16 v[118:121], v[164:167], v[188:191], v[118:121]
	v_mfma_f32_16x16x32_bf16 v[110:113], v[148:151], v[196:199], v[110:113]
	v_mfma_f32_16x16x32_bf16 v[102:105], v[164:167], v[196:199], v[102:105]
	v_mfma_f32_16x16x32_bf16 v[94:97], v[148:151], v[204:207], v[94:97]
	v_mfma_f32_16x16x32_bf16 v[86:89], v[164:167], v[204:207], v[86:89]
	v_mfma_f32_16x16x32_bf16 v[78:81], v[148:151], v[212:215], v[78:81]
	v_mfma_f32_16x16x32_bf16 v[70:73], v[164:167], v[212:215], v[70:73]
	v_mfma_f32_16x16x32_bf16 v[126:129], v[160:163], v[192:195], v[126:129]
	v_mfma_f32_16x16x32_bf16 v[118:121], v[168:171], v[192:195], v[118:121]
	v_mfma_f32_16x16x32_bf16 v[110:113], v[160:163], v[200:203], v[110:113]
	v_mfma_f32_16x16x32_bf16 v[102:105], v[168:171], v[200:203], v[102:105]
	v_mfma_f32_16x16x32_bf16 v[94:97], v[160:163], v[208:211], v[94:97]
	v_mfma_f32_16x16x32_bf16 v[86:89], v[168:171], v[208:211], v[86:89]
	v_mfma_f32_16x16x32_bf16 v[78:81], v[160:163], v[216:219], v[78:81]
	v_mfma_f32_16x16x32_bf16 v[70:73], v[168:171], v[216:219], v[70:73]
	s_setprio 0
	s_setprio 1
	v_mfma_f32_16x16x32_bf16 v[122:125], v[172:175], v[188:191], v[122:125]
	v_mfma_f32_16x16x32_bf16 v[114:117], v[180:183], v[188:191], v[114:117]
	v_mfma_f32_16x16x32_bf16 v[106:109], v[172:175], v[196:199], v[106:109]
	v_mfma_f32_16x16x32_bf16 v[98:101], v[180:183], v[196:199], v[98:101]
	v_mfma_f32_16x16x32_bf16 v[90:93], v[172:175], v[204:207], v[90:93]
	v_mfma_f32_16x16x32_bf16 v[82:85], v[180:183], v[204:207], v[82:85]
	v_mfma_f32_16x16x32_bf16 v[74:77], v[172:175], v[212:215], v[74:77]
	v_mfma_f32_16x16x32_bf16 v[66:69], v[180:183], v[212:215], v[66:69]
	v_mfma_f32_16x16x32_bf16 v[122:125], v[176:179], v[192:195], v[122:125]
	v_mfma_f32_16x16x32_bf16 v[114:117], v[184:187], v[192:195], v[114:117]
	v_mfma_f32_16x16x32_bf16 v[106:109], v[176:179], v[200:203], v[106:109]
	v_mfma_f32_16x16x32_bf16 v[98:101], v[184:187], v[200:203], v[98:101]
	v_mfma_f32_16x16x32_bf16 v[90:93], v[176:179], v[208:211], v[90:93]
	v_mfma_f32_16x16x32_bf16 v[82:85], v[184:187], v[208:211], v[82:85]
	v_mfma_f32_16x16x32_bf16 v[74:77], v[176:179], v[216:219], v[74:77]
	v_mfma_f32_16x16x32_bf16 v[66:69], v[184:187], v[216:219], v[66:69]
	s_nop 0
	s_barrier
; #define PG8_STAGE(bufoff, gbase, voff) do { _Pragma("unroll") for (int _i = 0; _i < 2; ++_i) \
;         __builtin_amdgcn_global_load_lds((const unsigned*)((const char*)(gbase) + (voff)[_i]), (PG8_LAS unsigned*)(lds + (bufoff) + ldsw + _i * 8192), 16, 0, 0); } while (0)
; #define PG8_WAIT_V(n) asm volatile("s_waitcnt vmcnt(" #n ")" ::: "memory")
; #define PG8_WAIT_L(n) asm volatile("s_waitcnt lgkmcnt(" #n ")" ::: "memory")
; #define PG8_BAR __builtin_amdgcn_s_barrier()
; #define PG8_SCHED __builtin_amdgcn_sched_barrier(0)
; template <class Epi, class Sched, bool ALIGN_EPI = true, bool SP2 = true>
; __device__ __forceinline__ void gemm_phase(PG8_LAS unsigned char* lds, const int K  , const Sched& S, const Epi& E) {
;     ...
;             PG8_LDA(At, 1, 1); PG8_STAGE(PG8_SB(1, 0), b3, voffB); PG8_STAGE(PG8_SB(1, 1), b3 + hstep, voffB); PG8_STAGE(PG8_SA(1, 0), a3, voffA);
;             PG8_WAIT_V(8); PG8_WAIT_L(0); PG8_BAR; PG8_MMA(1, 0, At, B0); PG8_MMA(1, 1, At, B1); PG8_BAR; PG8_SCHED;
;     ...
;         if constexpr (ALIGN_EPI) { if (wr == 0) PG8_BAR; }
	s_setprio 0
	s_add_i32 s28, s51, s31
	v_lshl_add_u64 v[220:221], v[220:221], 0, s[4:5]
	s_mov_b32 m0, s28
	ds_read_b128 v[188:191], v156 offset:49152
	ds_read_b128 v[192:195], v156 offset:50176
	ds_read_b128 v[196:199], v156 offset:51200
	ds_read_b128 v[200:203], v156 offset:52224
	ds_read_b128 v[204:207], v156 offset:53248
	ds_read_b128 v[208:211], v156 offset:54272
	ds_read_b128 v[212:215], v156 offset:55296
	ds_read_b128 v[216:219], v156 offset:56320
	global_load_lds_dwordx4 v[220:221], off
	s_add_i32 m0, s28, 0x2000
	s_add_u32 s26, s26, 0x80080
	v_lshl_add_u64 v[220:221], v[222:223], 0, s[4:5]
	s_addc_u32 s27, s27, 0
	s_add_i32 s28, s68, s31
	global_load_lds_dwordx4 v[220:221], off
	v_lshl_add_u64 v[220:221], s[26:27], 0, v[136:137]
	s_mov_b32 m0, s28
	s_nop 0
	global_load_lds_dwordx4 v[220:221], off
	v_lshl_add_u64 v[220:221], s[26:27], 0, v[132:133]
	s_add_i32 m0, s28, 0x2000
	s_nop 0
	global_load_lds_dwordx4 v[220:221], off
	v_lshl_add_u64 v[220:221], v[224:225], 0, s[4:5]
	s_mov_b32 m0, s38
	s_nop 0
	global_load_lds_dwordx4 v[220:221], off
	v_lshl_add_u64 v[220:221], v[226:227], 0, s[4:5]
	s_mov_b32 m0, s39
	s_nop 0
	global_load_lds_dwordx4 v[220:221], off
	s_waitcnt vmcnt(8)
	s_waitcnt lgkmcnt(0)
	s_setprio 1
	s_barrier
	v_mfma_f32_16x16x32_bf16 v[62:65], v[148:151], v[188:191], v[62:65]
	v_mfma_f32_16x16x32_bf16 v[54:57], v[164:167], v[188:191], v[54:57]
	v_mfma_f32_16x16x32_bf16 v[46:49], v[148:151], v[196:199], v[46:49]
	v_mfma_f32_16x16x32_bf16 v[38:41], v[164:167], v[196:199], v[38:41]
	v_mfma_f32_16x16x32_bf16 v[30:33], v[148:151], v[204:207], v[30:33]
	v_mfma_f32_16x16x32_bf16 v[22:25], v[164:167], v[204:207], v[22:25]
	v_mfma_f32_16x16x32_bf16 v[14:17], v[148:151], v[212:215], v[14:17]
	v_mfma_f32_16x16x32_bf16 v[6:9], v[164:167], v[212:215], v[6:9]
	v_mfma_f32_16x16x32_bf16 v[62:65], v[160:163], v[192:195], v[62:65]
	v_mfma_f32_16x16x32_bf16 v[54:57], v[168:171], v[192:195], v[54:57]
	v_mfma_f32_16x16x32_bf16 v[46:49], v[160:163], v[200:203], v[46:49]
	v_mfma_f32_16x16x32_bf16 v[38:41], v[168:171], v[200:203], v[38:41]
	v_mfma_f32_16x16x32_bf16 v[30:33], v[160:163], v[208:211], v[30:33]
	v_mfma_f32_16x16x32_bf16 v[22:25], v[168:171], v[208:211], v[22:25]
	v_mfma_f32_16x16x32_bf16 v[14:17], v[160:163], v[216:219], v[14:17]
	v_mfma_f32_16x16x32_bf16 v[6:9], v[168:171], v[216:219], v[6:9]
	s_setprio 0
	s_setprio 1
	v_mfma_f32_16x16x32_bf16 v[58:61], v[172:175], v[188:191], v[58:61]
	v_mfma_f32_16x16x32_bf16 v[50:53], v[180:183], v[188:191], v[50:53]
	v_mfma_f32_16x16x32_bf16 v[42:45], v[172:175], v[196:199], v[42:45]
	v_mfma_f32_16x16x32_bf16 v[34:37], v[180:183], v[196:199], v[34:37]
	v_mfma_f32_16x16x32_bf16 v[26:29], v[172:175], v[204:207], v[26:29]
	v_mfma_f32_16x16x32_bf16 v[18:21], v[180:183], v[204:207], v[18:21]
	v_mfma_f32_16x16x32_bf16 v[10:13], v[172:175], v[212:215], v[10:13]
	v_mfma_f32_16x16x32_bf16 v[2:5], v[180:183], v[212:215], v[2:5]
	v_mfma_f32_16x16x32_bf16 v[58:61], v[176:179], v[192:195], v[58:61]
	v_mfma_f32_16x16x32_bf16 v[50:53], v[184:187], v[192:195], v[50:53]
	v_mfma_f32_16x16x32_bf16 v[42:45], v[176:179], v[200:203], v[42:45]
	v_mfma_f32_16x16x32_bf16 v[34:37], v[184:187], v[200:203], v[34:37]
	v_mfma_f32_16x16x32_bf16 v[26:29], v[176:179], v[208:211], v[26:29]
	v_mfma_f32_16x16x32_bf16 v[18:21], v[184:187], v[208:211], v[18:21]
	v_mfma_f32_16x16x32_bf16 v[10:13], v[176:179], v[216:219], v[10:13]
	v_mfma_f32_16x16x32_bf16 v[2:5], v[184:187], v[216:219], v[2:5]
	s_nop 0
	s_barrier
	s_setprio 0
	s_add_i32 s50, s50, 2
	s_add_u32 s24, s24, 0x100
	s_addc_u32 s25, s25, 0
	s_add_u32 s48, s48, 0x100
	s_addc_u32 s49, s49, 0
	s_cmp_gt_u32 s50, 29
	s_cbranch_scc0 .LBB0_1448
	s_and_b64 vcc, exec, s[8:9]
	s_cbranch_vccz .LBB0_1451
	s_barrier

; #define PG8_STAGE(bufoff, gbase, voff) do { _Pragma("unroll") for (int _i = 0; _i < 2; ++_i) \
;         __builtin_amdgcn_global_load_lds((const unsigned*)((const char*)(gbase) + (voff)[_i]), (PG8_LAS unsigned*)(lds + (bufoff) + ldsw + _i * 8192), 16, 0, 0); } while (0)
; #define PG8_WAIT_V(n) asm volatile("s_waitcnt vmcnt(" #n ")" ::: "memory")
; #define PG8_WAIT_L(n) asm volatile("s_waitcnt lgkmcnt(" #n ")" ::: "memory")
; #define PG8_BAR __builtin_amdgcn_s_barrier()
; #define PG8_SCHED __builtin_amdgcn_sched_barrier(0)
; template <class Epi, class Sched, bool ALIGN_EPI = true, bool SP2 = true>
; __device__ __forceinline__ void gemm_phase(PG8_LAS unsigned char* lds, const int K  , const Sched& S, const Epi& E) {
;     ...
;             PG8_LDB(B0, 0, 0); PG8_LDB(B1, 0, 1); PG8_SCHED; PG8_LDA(At, 0, 0); PG8_STAGE(PG8_SA(1, 1), a1 + hstep, voffA);
;             PG8_WAIT_V(8); PG8_WAIT_L(0); PG8_BAR; PG8_MMA(0, 0, At, B0); PG8_MMA(0, 1, At, B1); PG8_BAR; PG8_SCHED;
;             PG8_LDA(At, 0, 1); PG8_STAGE(PG8_SB(0, 0), b2, voffB); PG8_STAGE(PG8_SB(0, 1), b2 + hstep, voffB); PG8_STAGE(PG8_SA(0, 0), a2, voffA);
;             PG8_WAIT_V(8); PG8_WAIT_L(0); PG8_BAR; PG8_MMA(1, 0, At, B0); PG8_MMA(1, 1, At, B1); PG8_BAR; PG8_SCHED;
.LBB0_1695:
	ds_read_b128 v[18:21], v233
	ds_read_b128 v[22:25], v233 offset:1024
	ds_read_b128 v[26:29], v233 offset:2048
	ds_read_b128 v[30:33], v233 offset:3072
	ds_read_b128 v[2:5], v234
	ds_read_b128 v[6:9], v234 offset:1024
	ds_read_b128 v[10:13], v234 offset:2048
	ds_read_b128 v[14:17], v234 offset:3072
	s_add_i32 s74, s24, 2
	s_add_u32 s22, s20, 0xfff50080
	s_addc_u32 s23, s21, -1
	s_cmp_eq_u32 s71, s24
	s_cselect_b32 s24, s16, s22
	s_cselect_b32 s25, s17, s23
	s_cselect_b32 s23, s19, s73
	s_cselect_b32 s22, s18, s72
	v_lshl_add_u64 v[186:187], s[20:21], 0, v[198:199]
	s_add_i32 m0, s28, 0xc000
	ds_read_b128 v[162:165], v235
	ds_read_b128 v[166:169], v235 offset:1024
	ds_read_b128 v[170:173], v235 offset:2048
	ds_read_b128 v[174:177], v235 offset:3072
	ds_read_b128 v[178:181], v235 offset:4096
	ds_read_b128 v[182:185], v235 offset:5120
	ds_read_b128 v[206:209], v235 offset:6144
	ds_read_b128 v[210:213], v235 offset:7168
	global_load_lds_dwordx4 v[186:187], off
	v_lshl_add_u64 v[186:187], s[20:21], 0, v[200:201]
	s_add_i32 m0, s28, 0xe000
	s_nop 0
	global_load_lds_dwordx4 v[186:187], off
	s_waitcnt vmcnt(8)
	s_waitcnt lgkmcnt(0)
	s_setprio 1
	s_barrier
	v_mfma_scale_f32_16x16x128_f8f6f4 v[158:161], v[18:25], v[162:169], v[158:161], v229, v229 op_sel_hi:[0,0,0]
	v_mfma_scale_f32_16x16x128_f8f6f4 v[154:157], v[26:33], v[162:169], v[154:157], v229, v229 op_sel_hi:[0,0,0]
	v_mfma_scale_f32_16x16x128_f8f6f4 v[150:153], v[18:25], v[170:177], v[150:153], v229, v229 op_sel_hi:[0,0,0]
	v_mfma_scale_f32_16x16x128_f8f6f4 v[142:145], v[26:33], v[170:177], v[142:145], v229, v229 op_sel_hi:[0,0,0]
	v_mfma_scale_f32_16x16x128_f8f6f4 v[134:137], v[18:25], v[178:185], v[134:137], v229, v229 op_sel_hi:[0,0,0]
	v_mfma_scale_f32_16x16x128_f8f6f4 v[126:129], v[26:33], v[178:185], v[126:129], v229, v229 op_sel_hi:[0,0,0]
	v_mfma_scale_f32_16x16x128_f8f6f4 v[118:121], v[18:25], v[206:213], v[118:121], v229, v229 op_sel_hi:[0,0,0]
	v_mfma_scale_f32_16x16x128_f8f6f4 v[110:113], v[26:33], v[206:213], v[110:113], v229, v229 op_sel_hi:[0,0,0]
	s_setprio 0
	s_setprio 1
	v_mfma_scale_f32_16x16x128_f8f6f4 v[146:149], v[2:9], v[162:169], v[146:149], v229, v229 op_sel_hi:[0,0,0]
	v_mfma_scale_f32_16x16x128_f8f6f4 v[138:141], v[10:17], v[162:169], v[138:141], v229, v229 op_sel_hi:[0,0,0]
	v_mfma_scale_f32_16x16x128_f8f6f4 v[130:133], v[2:9], v[170:177], v[130:133], v229, v229 op_sel_hi:[0,0,0]
	v_mfma_scale_f32_16x16x128_f8f6f4 v[122:125], v[10:17], v[170:177], v[122:125], v229, v229 op_sel_hi:[0,0,0]
	v_mfma_scale_f32_16x16x128_f8f6f4 v[114:117], v[2:9], v[178:185], v[114:117], v229, v229 op_sel_hi:[0,0,0]
	v_mfma_scale_f32_16x16x128_f8f6f4 v[106:109], v[10:17], v[178:185], v[106:109], v229, v229 op_sel_hi:[0,0,0]
	v_mfma_scale_f32_16x16x128_f8f6f4 v[102:105], v[2:9], v[206:213], v[102:105], v229, v229 op_sel_hi:[0,0,0]
	v_mfma_scale_f32_16x16x128_f8f6f4 v[98:101], v[10:17], v[206:213], v[98:101], v229, v229 op_sel_hi:[0,0,0]
	s_nop 0
	s_barrier
	s_setprio 0
	s_add_i32 s75, s40, s27
	v_lshl_add_u64 v[162:163], s[22:23], 0, v[192:193]
	s_mov_b32 m0, s75
	ds_read_b128 v[170:173], v235 offset:16384
	ds_read_b128 v[174:177], v235 offset:17408
	ds_read_b128 v[178:181], v235 offset:18432
	ds_read_b128 v[182:185], v235 offset:19456
	ds_read_b128 v[206:209], v235 offset:20480
	ds_read_b128 v[210:213], v235 offset:21504
	ds_read_b128 v[214:217], v235 offset:22528
	ds_read_b128 v[218:221], v235 offset:23552
	global_load_lds_dwordx4 v[162:163], off
	s_add_i32 m0, s75, 0x2000
	s_add_u32 s78, s22, 0xb0000
	v_lshl_add_u64 v[164:165], s[22:23], 0, v[196:197]
	s_addc_u32 s79, s23, 0
	s_add_i32 s75, s41, s27
	global_load_lds_dwordx4 v[164:165], off
	v_lshl_add_u64 v[166:167], s[78:79], 0, v[192:193]
	s_mov_b32 m0, s75
	v_lshl_add_u64 v[168:169], s[24:25], 0, v[194:195]
	global_load_lds_dwordx4 v[166:167], off
	v_lshl_add_u64 v[166:167], s[78:79], 0, v[196:197]
	s_add_i32 m0, s75, 0x2000
	s_nop 0
	global_load_lds_dwordx4 v[166:167], off
	v_lshl_add_u64 v[166:167], s[24:25], 0, v[190:191]
	s_mov_b32 m0, s28
	s_nop 0
	global_load_lds_dwordx4 v[166:167], off
	s_mov_b32 m0, s29
	s_nop 0
	global_load_lds_dwordx4 v[168:169], off
	s_waitcnt vmcnt(8)
	s_waitcnt lgkmcnt(0)
	s_setprio 1
	s_barrier
	v_mfma_scale_f32_16x16x128_f8f6f4 v[94:97], v[18:25], v[170:177], v[94:97], v229, v229 op_sel_hi:[0,0,0]
	v_mfma_scale_f32_16x16x128_f8f6f4 v[90:93], v[26:33], v[170:177], v[90:93], v229, v229 op_sel_hi:[0,0,0]
	v_mfma_scale_f32_16x16x128_f8f6f4 v[86:89], v[18:25], v[178:185], v[86:89], v229, v229 op_sel_hi:[0,0,0]
	v_mfma_scale_f32_16x16x128_f8f6f4 v[78:81], v[26:33], v[178:185], v[78:81], v229, v229 op_sel_hi:[0,0,0]
	v_mfma_scale_f32_16x16x128_f8f6f4 v[70:73], v[18:25], v[206:213], v[70:73], v229, v229 op_sel_hi:[0,0,0]
	v_mfma_scale_f32_16x16x128_f8f6f4 v[62:65], v[26:33], v[206:213], v[62:65], v229, v229 op_sel_hi:[0,0,0]
	v_mfma_scale_f32_16x16x128_f8f6f4 v[54:57], v[18:25], v[214:221], v[54:57], v229, v229 op_sel_hi:[0,0,0]
	v_mfma_scale_f32_16x16x128_f8f6f4 v[46:49], v[26:33], v[214:221], v[46:49], v229, v229 op_sel_hi:[0,0,0]
	s_setprio 0
	s_setprio 1
	v_mfma_scale_f32_16x16x128_f8f6f4 v[82:85], v[2:9], v[170:177], v[82:85], v229, v229 op_sel_hi:[0,0,0]
	v_mfma_scale_f32_16x16x128_f8f6f4 v[74:77], v[10:17], v[170:177], v[74:77], v229, v229 op_sel_hi:[0,0,0]
	v_mfma_scale_f32_16x16x128_f8f6f4 v[66:69], v[2:9], v[178:185], v[66:69], v229, v229 op_sel_hi:[0,0,0]
	v_mfma_scale_f32_16x16x128_f8f6f4 v[58:61], v[10:17], v[178:185], v[58:61], v229, v229 op_sel_hi:[0,0,0]
	v_mfma_scale_f32_16x16x128_f8f6f4 v[50:53], v[2:9], v[206:213], v[50:53], v229, v229 op_sel_hi:[0,0,0]
	v_mfma_scale_f32_16x16x128_f8f6f4 v[42:45], v[10:17], v[206:213], v[42:45], v229, v229 op_sel_hi:[0,0,0]
	v_mfma_scale_f32_16x16x128_f8f6f4 v[38:41], v[2:9], v[214:221], v[38:41], v229, v229 op_sel_hi:[0,0,0]
	v_mfma_scale_f32_16x16x128_f8f6f4 v[34:37], v[10:17], v[214:221], v[34:37], v229, v229 op_sel_hi:[0,0,0]
	s_nop 0
	s_barrier
; #define PG8_STAGE(bufoff, gbase, voff) do { _Pragma("unroll") for (int _i = 0; _i < 2; ++_i) \
;         __builtin_amdgcn_global_load_lds((const unsigned*)((const char*)(gbase) + (voff)[_i]), (PG8_LAS unsigned*)(lds + (bufoff) + ldsw + _i * 8192), 16, 0, 0); } while (0)
; #define PG8_WAIT_V(n) asm volatile("s_waitcnt vmcnt(" #n ")" ::: "memory")
; #define PG8_WAIT_L(n) asm volatile("s_waitcnt lgkmcnt(" #n ")" ::: "memory")
; #define PG8_BAR __builtin_amdgcn_s_barrier()
; #define PG8_SCHED __builtin_amdgcn_sched_barrier(0)
; template <class Epi, class Sched, bool ALIGN_EPI = true, bool SP2 = true>
; __device__ __forceinline__ void gemm_phase(PG8_LAS unsigned char* lds, const int K  , const Sched& S, const Epi& E) {
;     ...
;             PG8_LDB(B0, 1, 0); PG8_LDB(B1, 1, 1); PG8_SCHED; PG8_LDA(At, 1, 0); PG8_STAGE(PG8_SA(0, 1), a2 + hstep, voffA);
;             PG8_WAIT_V(8); PG8_WAIT_L(0); PG8_BAR; PG8_MMA(0, 0, At, B0); PG8_MMA(0, 1, At, B1); PG8_BAR; PG8_SCHED;
;             PG8_LDA(At, 1, 1); PG8_STAGE(PG8_SB(1, 0), b3, voffB); PG8_STAGE(PG8_SB(1, 1), b3 + hstep, voffB); PG8_STAGE(PG8_SA(1, 0), a3, voffA);
;             PG8_WAIT_V(8); PG8_WAIT_L(0); PG8_BAR; PG8_MMA(1, 0, At, B0); PG8_MMA(1, 1, At, B1); PG8_BAR; PG8_SCHED;
;     ...
;         if constexpr (Epi::FP8) asm volatile("s_nop 15\n\ts_nop 15\n\ts_nop 15\n\ts_nop 15\n\ts_nop 15" ::: "memory");
;         if constexpr (ALIGN_EPI) { if (wr == 0) PG8_BAR; }
	s_setprio 0
	s_add_i32 s75, 0, 0x18000
	s_add_i32 s78, 0, 0x1c000
	v_add_u32_e32 v14, s75, v231
	v_add_u32_e32 v30, s78, v231
	ds_read_b128 v[2:5], v14
	ds_read_b128 v[6:9], v14 offset:1024
	ds_read_b128 v[10:13], v14 offset:2048
	ds_read_b128 v[14:17], v14 offset:3072
	ds_read_b128 v[18:21], v30
	ds_read_b128 v[22:25], v30 offset:1024
	ds_read_b128 v[26:29], v30 offset:2048
	ds_read_b128 v[30:33], v30 offset:3072
	s_add_u32 s24, s24, 0xb0000
	s_addc_u32 s25, s25, 0
	s_mov_b32 m0, s30
	v_lshl_add_u64 v[186:187], s[24:25], 0, v[190:191]
	ds_read_b128 v[170:173], v235 offset:32768
	ds_read_b128 v[174:177], v235 offset:33792
	ds_read_b128 v[178:181], v235 offset:34816
	ds_read_b128 v[182:185], v235 offset:35840
	ds_read_b128 v[206:209], v235 offset:36864
	ds_read_b128 v[210:213], v235 offset:37888
	ds_read_b128 v[214:217], v235 offset:38912
	ds_read_b128 v[218:221], v235 offset:39936
	global_load_lds_dwordx4 v[186:187], off
	v_lshl_add_u64 v[186:187], s[24:25], 0, v[194:195]
	s_mov_b32 m0, s31
	s_nop 0
	global_load_lds_dwordx4 v[186:187], off
	s_waitcnt vmcnt(8)
	s_waitcnt lgkmcnt(0)
	s_setprio 1
	s_barrier
	v_mfma_scale_f32_16x16x128_f8f6f4 v[158:161], v[2:9], v[170:177], v[158:161], v229, v229 op_sel_hi:[0,0,0]
	v_mfma_scale_f32_16x16x128_f8f6f4 v[154:157], v[10:17], v[170:177], v[154:157], v229, v229 op_sel_hi:[0,0,0]
	v_mfma_scale_f32_16x16x128_f8f6f4 v[150:153], v[2:9], v[178:185], v[150:153], v229, v229 op_sel_hi:[0,0,0]
	v_mfma_scale_f32_16x16x128_f8f6f4 v[142:145], v[10:17], v[178:185], v[142:145], v229, v229 op_sel_hi:[0,0,0]
	v_mfma_scale_f32_16x16x128_f8f6f4 v[134:137], v[2:9], v[206:213], v[134:137], v229, v229 op_sel_hi:[0,0,0]
	v_mfma_scale_f32_16x16x128_f8f6f4 v[126:129], v[10:17], v[206:213], v[126:129], v229, v229 op_sel_hi:[0,0,0]
	v_mfma_scale_f32_16x16x128_f8f6f4 v[118:121], v[2:9], v[214:221], v[118:121], v229, v229 op_sel_hi:[0,0,0]
	v_mfma_scale_f32_16x16x128_f8f6f4 v[110:113], v[10:17], v[214:221], v[110:113], v229, v229 op_sel_hi:[0,0,0]
	s_setprio 0
	s_setprio 1
	v_mfma_scale_f32_16x16x128_f8f6f4 v[146:149], v[18:25], v[170:177], v[146:149], v229, v229 op_sel_hi:[0,0,0]
	v_mfma_scale_f32_16x16x128_f8f6f4 v[138:141], v[26:33], v[170:177], v[138:141], v229, v229 op_sel_hi:[0,0,0]
	v_mfma_scale_f32_16x16x128_f8f6f4 v[130:133], v[18:25], v[178:185], v[130:133], v229, v229 op_sel_hi:[0,0,0]
	v_mfma_scale_f32_16x16x128_f8f6f4 v[122:125], v[26:33], v[178:185], v[122:125], v229, v229 op_sel_hi:[0,0,0]
	v_mfma_scale_f32_16x16x128_f8f6f4 v[114:117], v[18:25], v[206:213], v[114:117], v229, v229 op_sel_hi:[0,0,0]
	v_mfma_scale_f32_16x16x128_f8f6f4 v[106:109], v[26:33], v[206:213], v[106:109], v229, v229 op_sel_hi:[0,0,0]
	v_mfma_scale_f32_16x16x128_f8f6f4 v[102:105], v[18:25], v[214:221], v[102:105], v229, v229 op_sel_hi:[0,0,0]
	v_mfma_scale_f32_16x16x128_f8f6f4 v[98:101], v[26:33], v[214:221], v[98:101], v229, v229 op_sel_hi:[0,0,0]
	s_nop 0
	s_barrier
	s_setprio 0
	s_add_i32 s24, s75, s27
	v_lshl_add_u64 v[162:163], v[162:163], 0, s[10:11]
	s_mov_b32 m0, s24
	ds_read_b128 v[170:173], v235 offset:49152
	ds_read_b128 v[174:177], v235 offset:50176
	ds_read_b128 v[178:181], v235 offset:51200
	ds_read_b128 v[182:185], v235 offset:52224
	ds_read_b128 v[206:209], v235 offset:53248
	ds_read_b128 v[210:213], v235 offset:54272
	ds_read_b128 v[214:217], v235 offset:55296
	ds_read_b128 v[218:221], v235 offset:56320
	global_load_lds_dwordx4 v[162:163], off
	s_add_i32 m0, s24, 0x2000
	s_add_u32 s22, s22, 0xb0080
	v_lshl_add_u64 v[162:163], v[164:165], 0, s[10:11]
	s_addc_u32 s23, s23, 0
	s_add_i32 s24, s78, s27
	global_load_lds_dwordx4 v[162:163], off
	v_lshl_add_u64 v[162:163], s[22:23], 0, v[192:193]
	s_mov_b32 m0, s24
	s_nop 0
	global_load_lds_dwordx4 v[162:163], off
	v_lshl_add_u64 v[162:163], s[22:23], 0, v[196:197]
	s_add_i32 m0, s24, 0x2000
	s_nop 0
	global_load_lds_dwordx4 v[162:163], off
	v_lshl_add_u64 v[162:163], v[166:167], 0, s[10:11]
	s_mov_b32 m0, s36
	s_nop 0
	global_load_lds_dwordx4 v[162:163], off
	v_lshl_add_u64 v[162:163], v[168:169], 0, s[10:11]
	s_mov_b32 m0, s37
	s_nop 0
	global_load_lds_dwordx4 v[162:163], off
	s_waitcnt vmcnt(8)
	s_waitcnt lgkmcnt(0)
	s_setprio 1
	s_barrier
	v_mfma_scale_f32_16x16x128_f8f6f4 v[94:97], v[2:9], v[170:177], v[94:97], v229, v229 op_sel_hi:[0,0,0]
	v_mfma_scale_f32_16x16x128_f8f6f4 v[90:93], v[10:17], v[170:177], v[90:93], v229, v229 op_sel_hi:[0,0,0]
	v_mfma_scale_f32_16x16x128_f8f6f4 v[86:89], v[2:9], v[178:185], v[86:89], v229, v229 op_sel_hi:[0,0,0]
	v_mfma_scale_f32_16x16x128_f8f6f4 v[78:81], v[10:17], v[178:185], v[78:81], v229, v229 op_sel_hi:[0,0,0]
	v_mfma_scale_f32_16x16x128_f8f6f4 v[70:73], v[2:9], v[206:213], v[70:73], v229, v229 op_sel_hi:[0,0,0]
	v_mfma_scale_f32_16x16x128_f8f6f4 v[62:65], v[10:17], v[206:213], v[62:65], v229, v229 op_sel_hi:[0,0,0]
	v_mfma_scale_f32_16x16x128_f8f6f4 v[54:57], v[2:9], v[214:221], v[54:57], v229, v229 op_sel_hi:[0,0,0]
	v_mfma_scale_f32_16x16x128_f8f6f4 v[46:49], v[10:17], v[214:221], v[46:49], v229, v229 op_sel_hi:[0,0,0]
	s_setprio 0
	s_setprio 1
	v_mfma_scale_f32_16x16x128_f8f6f4 v[82:85], v[18:25], v[170:177], v[82:85], v229, v229 op_sel_hi:[0,0,0]
	v_mfma_scale_f32_16x16x128_f8f6f4 v[74:77], v[26:33], v[170:177], v[74:77], v229, v229 op_sel_hi:[0,0,0]
	v_mfma_scale_f32_16x16x128_f8f6f4 v[66:69], v[18:25], v[178:185], v[66:69], v229, v229 op_sel_hi:[0,0,0]
	v_mfma_scale_f32_16x16x128_f8f6f4 v[58:61], v[26:33], v[178:185], v[58:61], v229, v229 op_sel_hi:[0,0,0]
	v_mfma_scale_f32_16x16x128_f8f6f4 v[50:53], v[18:25], v[206:213], v[50:53], v229, v229 op_sel_hi:[0,0,0]
	v_mfma_scale_f32_16x16x128_f8f6f4 v[42:45], v[26:33], v[206:213], v[42:45], v229, v229 op_sel_hi:[0,0,0]
	v_mfma_scale_f32_16x16x128_f8f6f4 v[38:41], v[18:25], v[214:221], v[38:41], v229, v229 op_sel_hi:[0,0,0]
	v_mfma_scale_f32_16x16x128_f8f6f4 v[34:37], v[26:33], v[214:221], v[34:37], v229, v229 op_sel_hi:[0,0,0]
	s_nop 0
	s_barrier
	s_setprio 0
	s_add_u32 s20, s20, 0x100
	s_addc_u32 s21, s21, 0
	s_add_u32 s72, s72, 0x100
	s_addc_u32 s73, s73, 0
	s_cmp_ge_u32 s74, s4
	s_mov_b32 s24, s74
	s_cbranch_scc0 .LBB0_1695
	s_nop 15
	s_nop 15
	s_nop 15
	s_nop 15
	s_nop 15
	s_and_b64 vcc, exec, s[12:13]
	s_cbranch_vccz .LBB0_1698
	s_barrier

; #define PG8_STAGE(bufoff, gbase, voff) do { _Pragma("unroll") for (int _i = 0; _i < 2; ++_i) \
;         __builtin_amdgcn_global_load_lds((const unsigned*)((const char*)(gbase) + (voff)[_i]), (PG8_LAS unsigned*)(lds + (bufoff) + ldsw + _i * 8192), 16, 0, 0); } while (0)
; #define PG8_WAIT_V(n) asm volatile("s_waitcnt vmcnt(" #n ")" ::: "memory")
; #define PG8_WAIT_L(n) asm volatile("s_waitcnt lgkmcnt(" #n ")" ::: "memory")
; #define PG8_BAR __builtin_amdgcn_s_barrier()
; #define PG8_SCHED __builtin_amdgcn_sched_barrier(0)
; template <class Epi, class Sched, bool ALIGN_EPI = true, bool SP2 = true>
; __device__ __forceinline__ void gemm_phase(PG8_LAS unsigned char* lds, const int K  , const Sched& S, const Epi& E) {
;     ...
;             PG8_LDB(B0, 0, 0); PG8_LDB(B1, 0, 1); PG8_SCHED; PG8_LDA(At, 0, 0); PG8_STAGE(PG8_SA(1, 1), a1 + hstep, voffA);
;             PG8_WAIT_V(8); PG8_WAIT_L(0); PG8_BAR; PG8_MMA(0, 0, At, B0); PG8_MMA(0, 1, At, B1); PG8_BAR; PG8_SCHED;
;             PG8_LDA(At, 0, 1); PG8_STAGE(PG8_SB(0, 0), b2, voffB); PG8_STAGE(PG8_SB(0, 1), b2 + hstep, voffB); PG8_STAGE(PG8_SA(0, 0), a2, voffA);
;             PG8_WAIT_V(8); PG8_WAIT_L(0); PG8_BAR; PG8_MMA(1, 0, At, B0); PG8_MMA(1, 1, At, B1); PG8_BAR; PG8_SCHED;
.LBB0_1847:
	ds_read_b128 v[130:133], v176
	ds_read_b128 v[134:137], v176 offset:1024
	ds_read_b128 v[138:141], v176 offset:2048
	ds_read_b128 v[142:145], v176 offset:3072
	ds_read_b128 v[168:171], v177
	ds_read_b128 v[184:187], v177 offset:1024
	ds_read_b128 v[188:191], v177 offset:2048
	ds_read_b128 v[192:195], v177 offset:3072
	s_add_u32 s22, s0, 0xfff80080
	s_addc_u32 s23, s1, -1
	s_cmp_eq_u32 s51, 28
	s_cselect_b32 s25, s7, s23
	s_cselect_b32 s24, s47, s22
	s_cselect_b32 s23, s11, s50
	s_cselect_b32 s22, s48, s49
	v_lshl_add_u64 v[230:231], s[0:1], 0, v[160:161]
	s_add_i32 m0, s27, 0xc000
	ds_read_b128 v[196:199], v178
	ds_read_b128 v[200:203], v178 offset:1024
	ds_read_b128 v[204:207], v178 offset:2048
	ds_read_b128 v[208:211], v178 offset:3072
	ds_read_b128 v[212:215], v178 offset:4096
	ds_read_b128 v[216:219], v178 offset:5120
	ds_read_b128 v[220:223], v178 offset:6144
	ds_read_b128 v[224:227], v178 offset:7168
	global_load_lds_dwordx4 v[230:231], off
	v_lshl_add_u64 v[230:231], s[0:1], 0, v[162:163]
	s_add_i32 m0, s27, 0xe000
	s_nop 0
	global_load_lds_dwordx4 v[230:231], off
	s_waitcnt vmcnt(8)
	s_waitcnt lgkmcnt(0)
	s_setprio 1
	s_barrier
	v_mfma_f32_16x16x32_bf16 v[126:129], v[130:133], v[196:199], v[126:129]
	v_mfma_f32_16x16x32_bf16 v[122:125], v[138:141], v[196:199], v[122:125]
	v_mfma_f32_16x16x32_bf16 v[110:113], v[130:133], v[204:207], v[110:113]
	v_mfma_f32_16x16x32_bf16 v[106:109], v[138:141], v[204:207], v[106:109]
	v_mfma_f32_16x16x32_bf16 v[94:97], v[130:133], v[212:215], v[94:97]
	v_mfma_f32_16x16x32_bf16 v[90:93], v[138:141], v[212:215], v[90:93]
	v_mfma_f32_16x16x32_bf16 v[78:81], v[130:133], v[220:223], v[78:81]
	v_mfma_f32_16x16x32_bf16 v[74:77], v[138:141], v[220:223], v[74:77]
	v_mfma_f32_16x16x32_bf16 v[126:129], v[134:137], v[200:203], v[126:129]
	v_mfma_f32_16x16x32_bf16 v[122:125], v[142:145], v[200:203], v[122:125]
	v_mfma_f32_16x16x32_bf16 v[110:113], v[134:137], v[208:211], v[110:113]
	v_mfma_f32_16x16x32_bf16 v[106:109], v[142:145], v[208:211], v[106:109]
	v_mfma_f32_16x16x32_bf16 v[94:97], v[134:137], v[216:219], v[94:97]
	v_mfma_f32_16x16x32_bf16 v[90:93], v[142:145], v[216:219], v[90:93]
	v_mfma_f32_16x16x32_bf16 v[78:81], v[134:137], v[224:227], v[78:81]
	v_mfma_f32_16x16x32_bf16 v[74:77], v[142:145], v[224:227], v[74:77]
	s_setprio 0
	s_setprio 1
	v_mfma_f32_16x16x32_bf16 v[118:121], v[168:171], v[196:199], v[118:121]
	v_mfma_f32_16x16x32_bf16 v[114:117], v[188:191], v[196:199], v[114:117]
	v_mfma_f32_16x16x32_bf16 v[102:105], v[168:171], v[204:207], v[102:105]
	v_mfma_f32_16x16x32_bf16 v[98:101], v[188:191], v[204:207], v[98:101]
	v_mfma_f32_16x16x32_bf16 v[86:89], v[168:171], v[212:215], v[86:89]
	v_mfma_f32_16x16x32_bf16 v[82:85], v[188:191], v[212:215], v[82:85]
	v_mfma_f32_16x16x32_bf16 v[70:73], v[168:171], v[220:223], v[70:73]
	v_mfma_f32_16x16x32_bf16 v[66:69], v[188:191], v[220:223], v[66:69]
	v_mfma_f32_16x16x32_bf16 v[118:121], v[184:187], v[200:203], v[118:121]
	v_mfma_f32_16x16x32_bf16 v[114:117], v[192:195], v[200:203], v[114:117]
	v_mfma_f32_16x16x32_bf16 v[102:105], v[184:187], v[208:211], v[102:105]
	v_mfma_f32_16x16x32_bf16 v[98:101], v[192:195], v[208:211], v[98:101]
	v_mfma_f32_16x16x32_bf16 v[86:89], v[184:187], v[216:219], v[86:89]
	v_mfma_f32_16x16x32_bf16 v[82:85], v[192:195], v[216:219], v[82:85]
	v_mfma_f32_16x16x32_bf16 v[70:73], v[184:187], v[224:227], v[70:73]
	v_mfma_f32_16x16x32_bf16 v[66:69], v[192:195], v[224:227], v[66:69]
	s_nop 0
	s_barrier
	s_setprio 0
	s_add_i32 s68, s39, s26
	v_lshl_add_u64 v[230:231], s[22:23], 0, v[150:151]
	s_mov_b32 m0, s68
	ds_read_b128 v[196:199], v178 offset:16384
	ds_read_b128 v[200:203], v178 offset:17408
	ds_read_b128 v[204:207], v178 offset:18432
	ds_read_b128 v[208:211], v178 offset:19456
	ds_read_b128 v[212:215], v178 offset:20480
	ds_read_b128 v[216:219], v178 offset:21504
	ds_read_b128 v[220:223], v178 offset:22528
	ds_read_b128 v[224:227], v178 offset:23552
	global_load_lds_dwordx4 v[230:231], off
	s_add_i32 m0, s68, 0x2000
	s_add_u32 s68, s22, 0x80000
	v_lshl_add_u64 v[232:233], s[22:23], 0, v[154:155]
	s_addc_u32 s69, s23, 0
	s_add_i32 s70, s40, s26
	global_load_lds_dwordx4 v[232:233], off
	v_lshl_add_u64 v[234:235], s[68:69], 0, v[150:151]
	s_mov_b32 m0, s70
	v_lshl_add_u64 v[236:237], s[24:25], 0, v[152:153]
	global_load_lds_dwordx4 v[234:235], off
	v_lshl_add_u64 v[234:235], s[68:69], 0, v[154:155]
	s_add_i32 m0, s70, 0x2000
	s_nop 0
	global_load_lds_dwordx4 v[234:235], off
	v_lshl_add_u64 v[234:235], s[24:25], 0, v[148:149]
	s_mov_b32 m0, s27
	s_nop 0
	global_load_lds_dwordx4 v[234:235], off
	s_mov_b32 m0, s28
	s_nop 0
	global_load_lds_dwordx4 v[236:237], off
	s_waitcnt vmcnt(8)
	s_waitcnt lgkmcnt(0)
	s_setprio 1
	s_barrier
; #define PG8_STAGE(bufoff, gbase, voff) do { _Pragma("unroll") for (int _i = 0; _i < 2; ++_i) \
;         __builtin_amdgcn_global_load_lds((const unsigned*)((const char*)(gbase) + (voff)[_i]), (PG8_LAS unsigned*)(lds + (bufoff) + ldsw + _i * 8192), 16, 0, 0); } while (0)
; #define PG8_WAIT_V(n) asm volatile("s_waitcnt vmcnt(" #n ")" ::: "memory")
; #define PG8_WAIT_L(n) asm volatile("s_waitcnt lgkmcnt(" #n ")" ::: "memory")
; #define PG8_BAR __builtin_amdgcn_s_barrier()
; #define PG8_SCHED __builtin_amdgcn_sched_barrier(0)
; template <class Epi, class Sched, bool ALIGN_EPI = true, bool SP2 = true>
; __device__ __forceinline__ void gemm_phase(PG8_LAS unsigned char* lds, const int K  , const Sched& S, const Epi& E) {
;     ...
;             PG8_WAIT_V(8); PG8_WAIT_L(0); PG8_BAR; PG8_MMA(1, 0, At, B0); PG8_MMA(1, 1, At, B1); PG8_BAR; PG8_SCHED;
;             PG8_LDB(B0, 1, 0); PG8_LDB(B1, 1, 1); PG8_SCHED; PG8_LDA(At, 1, 0); PG8_STAGE(PG8_SA(0, 1), a2 + hstep, voffA);
;             PG8_WAIT_V(8); PG8_WAIT_L(0); PG8_BAR; PG8_MMA(0, 0, At, B0); PG8_MMA(0, 1, At, B1); PG8_BAR; PG8_SCHED;
	v_mfma_f32_16x16x32_bf16 v[62:65], v[130:133], v[196:199], v[62:65]
	v_mfma_f32_16x16x32_bf16 v[58:61], v[138:141], v[196:199], v[58:61]
	v_mfma_f32_16x16x32_bf16 v[46:49], v[130:133], v[204:207], v[46:49]
	v_mfma_f32_16x16x32_bf16 v[42:45], v[138:141], v[204:207], v[42:45]
	v_mfma_f32_16x16x32_bf16 v[30:33], v[130:133], v[212:215], v[30:33]
	v_mfma_f32_16x16x32_bf16 v[26:29], v[138:141], v[212:215], v[26:29]
	v_mfma_f32_16x16x32_bf16 v[14:17], v[130:133], v[220:223], v[14:17]
	v_mfma_f32_16x16x32_bf16 v[10:13], v[138:141], v[220:223], v[10:13]
	v_mfma_f32_16x16x32_bf16 v[62:65], v[134:137], v[200:203], v[62:65]
	v_mfma_f32_16x16x32_bf16 v[58:61], v[142:145], v[200:203], v[58:61]
	v_mfma_f32_16x16x32_bf16 v[46:49], v[134:137], v[208:211], v[46:49]
	v_mfma_f32_16x16x32_bf16 v[42:45], v[142:145], v[208:211], v[42:45]
	v_mfma_f32_16x16x32_bf16 v[30:33], v[134:137], v[216:219], v[30:33]
	v_mfma_f32_16x16x32_bf16 v[26:29], v[142:145], v[216:219], v[26:29]
	v_mfma_f32_16x16x32_bf16 v[14:17], v[134:137], v[224:227], v[14:17]
	v_mfma_f32_16x16x32_bf16 v[10:13], v[142:145], v[224:227], v[10:13]
	s_setprio 0
	s_setprio 1
	v_mfma_f32_16x16x32_bf16 v[54:57], v[168:171], v[196:199], v[54:57]
	v_mfma_f32_16x16x32_bf16 v[50:53], v[188:191], v[196:199], v[50:53]
	v_mfma_f32_16x16x32_bf16 v[38:41], v[168:171], v[204:207], v[38:41]
	v_mfma_f32_16x16x32_bf16 v[34:37], v[188:191], v[204:207], v[34:37]
	v_mfma_f32_16x16x32_bf16 v[22:25], v[168:171], v[212:215], v[22:25]
	v_mfma_f32_16x16x32_bf16 v[18:21], v[188:191], v[212:215], v[18:21]
	v_mfma_f32_16x16x32_bf16 v[6:9], v[168:171], v[220:223], v[6:9]
	v_mfma_f32_16x16x32_bf16 v[2:5], v[188:191], v[220:223], v[2:5]
	v_mfma_f32_16x16x32_bf16 v[54:57], v[184:187], v[200:203], v[54:57]
	v_mfma_f32_16x16x32_bf16 v[50:53], v[192:195], v[200:203], v[50:53]
	v_mfma_f32_16x16x32_bf16 v[38:41], v[184:187], v[208:211], v[38:41]
	v_mfma_f32_16x16x32_bf16 v[34:37], v[192:195], v[208:211], v[34:37]
	v_mfma_f32_16x16x32_bf16 v[22:25], v[184:187], v[216:219], v[22:25]
	v_mfma_f32_16x16x32_bf16 v[18:21], v[192:195], v[216:219], v[18:21]
	v_mfma_f32_16x16x32_bf16 v[6:9], v[184:187], v[224:227], v[6:9]
	v_mfma_f32_16x16x32_bf16 v[2:5], v[192:195], v[224:227], v[2:5]
	s_nop 0
	s_barrier
	s_setprio 0
	s_add_i32 s68, 0, 0x18000
	s_add_i32 s69, 0, 0x1c000
	v_add_u32_e32 v142, s68, v172
	v_add_u32_e32 v192, s69, v172
	ds_read_b128 v[130:133], v142
	ds_read_b128 v[134:137], v142 offset:1024
	ds_read_b128 v[138:141], v142 offset:2048
	ds_read_b128 v[142:145], v142 offset:3072
	ds_read_b128 v[168:171], v192
	ds_read_b128 v[184:187], v192 offset:1024
	ds_read_b128 v[188:191], v192 offset:2048
	ds_read_b128 v[192:195], v192 offset:3072
	s_add_u32 s24, s24, 0x80000
	s_addc_u32 s25, s25, 0
	s_mov_b32 m0, s29
	v_lshl_add_u64 v[238:239], s[24:25], 0, v[148:149]
	ds_read_b128 v[196:199], v178 offset:32768
	ds_read_b128 v[200:203], v178 offset:33792
	ds_read_b128 v[204:207], v178 offset:34816
	ds_read_b128 v[208:211], v178 offset:35840
	ds_read_b128 v[212:215], v178 offset:36864
	ds_read_b128 v[216:219], v178 offset:37888
	ds_read_b128 v[220:223], v178 offset:38912
	ds_read_b128 v[224:227], v178 offset:39936
	global_load_lds_dwordx4 v[238:239], off
	v_lshl_add_u64 v[238:239], s[24:25], 0, v[152:153]
	s_mov_b32 m0, s30
	s_nop 0
	global_load_lds_dwordx4 v[238:239], off
	s_waitcnt vmcnt(8)
	s_waitcnt lgkmcnt(0)
	s_setprio 1
	s_barrier
	v_mfma_f32_16x16x32_bf16 v[126:129], v[130:133], v[196:199], v[126:129]
	v_mfma_f32_16x16x32_bf16 v[122:125], v[138:141], v[196:199], v[122:125]
	v_mfma_f32_16x16x32_bf16 v[110:113], v[130:133], v[204:207], v[110:113]
	v_mfma_f32_16x16x32_bf16 v[106:109], v[138:141], v[204:207], v[106:109]
	v_mfma_f32_16x16x32_bf16 v[94:97], v[130:133], v[212:215], v[94:97]
	v_mfma_f32_16x16x32_bf16 v[90:93], v[138:141], v[212:215], v[90:93]
	v_mfma_f32_16x16x32_bf16 v[78:81], v[130:133], v[220:223], v[78:81]
	v_mfma_f32_16x16x32_bf16 v[74:77], v[138:141], v[220:223], v[74:77]
	v_mfma_f32_16x16x32_bf16 v[126:129], v[134:137], v[200:203], v[126:129]
	v_mfma_f32_16x16x32_bf16 v[122:125], v[142:145], v[200:203], v[122:125]
	v_mfma_f32_16x16x32_bf16 v[110:113], v[134:137], v[208:211], v[110:113]
	v_mfma_f32_16x16x32_bf16 v[106:109], v[142:145], v[208:211], v[106:109]
	v_mfma_f32_16x16x32_bf16 v[94:97], v[134:137], v[216:219], v[94:97]
	v_mfma_f32_16x16x32_bf16 v[90:93], v[142:145], v[216:219], v[90:93]
	v_mfma_f32_16x16x32_bf16 v[78:81], v[134:137], v[224:227], v[78:81]
	v_mfma_f32_16x16x32_bf16 v[74:77], v[142:145], v[224:227], v[74:77]
	s_setprio 0
	s_setprio 1
	v_mfma_f32_16x16x32_bf16 v[118:121], v[168:171], v[196:199], v[118:121]
	v_mfma_f32_16x16x32_bf16 v[114:117], v[188:191], v[196:199], v[114:117]
	v_mfma_f32_16x16x32_bf16 v[102:105], v[168:171], v[204:207], v[102:105]
	v_mfma_f32_16x16x32_bf16 v[98:101], v[188:191], v[204:207], v[98:101]
	v_mfma_f32_16x16x32_bf16 v[86:89], v[168:171], v[212:215], v[86:89]
	v_mfma_f32_16x16x32_bf16 v[82:85], v[188:191], v[212:215], v[82:85]
	v_mfma_f32_16x16x32_bf16 v[70:73], v[168:171], v[220:223], v[70:73]
	v_mfma_f32_16x16x32_bf16 v[66:69], v[188:191], v[220:223], v[66:69]
	v_mfma_f32_16x16x32_bf16 v[118:121], v[184:187], v[200:203], v[118:121]
	v_mfma_f32_16x16x32_bf16 v[114:117], v[192:195], v[200:203], v[114:117]
	v_mfma_f32_16x16x32_bf16 v[102:105], v[184:187], v[208:211], v[102:105]
	v_mfma_f32_16x16x32_bf16 v[98:101], v[192:195], v[208:211], v[98:101]
	v_mfma_f32_16x16x32_bf16 v[86:89], v[184:187], v[216:219], v[86:89]
	v_mfma_f32_16x16x32_bf16 v[82:85], v[192:195], v[216:219], v[82:85]
	v_mfma_f32_16x16x32_bf16 v[70:73], v[184:187], v[224:227], v[70:73]
	v_mfma_f32_16x16x32_bf16 v[66:69], v[192:195], v[224:227], v[66:69]
	s_nop 0
	s_barrier
; #define PG8_STAGE(bufoff, gbase, voff) do { _Pragma("unroll") for (int _i = 0; _i < 2; ++_i) \
;         __builtin_amdgcn_global_load_lds((const unsigned*)((const char*)(gbase) + (voff)[_i]), (PG8_LAS unsigned*)(lds + (bufoff) + ldsw + _i * 8192), 16, 0, 0); } while (0)
; #define PG8_WAIT_V(n) asm volatile("s_waitcnt vmcnt(" #n ")" ::: "memory")
; #define PG8_WAIT_L(n) asm volatile("s_waitcnt lgkmcnt(" #n ")" ::: "memory")
; #define PG8_BAR __builtin_amdgcn_s_barrier()
; #define PG8_SCHED __builtin_amdgcn_sched_barrier(0)
; template <class Epi, class Sched, bool ALIGN_EPI = true, bool SP2 = true>
; __device__ __forceinline__ void gemm_phase(PG8_LAS unsigned char* lds, const int K  , const Sched& S, const Epi& E) {
;     ...
;             PG8_LDA(At, 1, 1); PG8_STAGE(PG8_SB(1, 0), b3, voffB); PG8_STAGE(PG8_SB(1, 1), b3 + hstep, voffB); PG8_STAGE(PG8_SA(1, 0), a3, voffA);
;             PG8_WAIT_V(8); PG8_WAIT_L(0); PG8_BAR; PG8_MMA(1, 0, At, B0); PG8_MMA(1, 1, At, B1); PG8_BAR; PG8_SCHED;
;     ...
;         if constexpr (ALIGN_EPI) { if (wr == 0) PG8_BAR; }
	s_setprio 0
	s_add_i32 s24, s68, s26
	v_lshl_add_u64 v[230:231], v[230:231], 0, s[4:5]
	s_mov_b32 m0, s24
	ds_read_b128 v[196:199], v178 offset:49152
	ds_read_b128 v[200:203], v178 offset:50176
	ds_read_b128 v[204:207], v178 offset:51200
	ds_read_b128 v[208:211], v178 offset:52224
	ds_read_b128 v[212:215], v178 offset:53248
	ds_read_b128 v[216:219], v178 offset:54272
	ds_read_b128 v[220:223], v178 offset:55296
	ds_read_b128 v[224:227], v178 offset:56320
	global_load_lds_dwordx4 v[230:231], off
	s_add_i32 m0, s24, 0x2000
	s_add_u32 s22, s22, 0x80080
	v_lshl_add_u64 v[230:231], v[232:233], 0, s[4:5]
	s_addc_u32 s23, s23, 0
	s_add_i32 s24, s69, s26
	global_load_lds_dwordx4 v[230:231], off
	v_lshl_add_u64 v[230:231], s[22:23], 0, v[150:151]
	s_mov_b32 m0, s24
	s_nop 0
	global_load_lds_dwordx4 v[230:231], off
	v_lshl_add_u64 v[230:231], s[22:23], 0, v[154:155]
	s_add_i32 m0, s24, 0x2000
	s_nop 0
	global_load_lds_dwordx4 v[230:231], off
	v_lshl_add_u64 v[230:231], v[234:235], 0, s[4:5]
	s_mov_b32 m0, s35
	s_nop 0
	global_load_lds_dwordx4 v[230:231], off
	v_lshl_add_u64 v[230:231], v[236:237], 0, s[4:5]
	s_mov_b32 m0, s36
	s_nop 0
	global_load_lds_dwordx4 v[230:231], off
	s_waitcnt vmcnt(8)
	s_waitcnt lgkmcnt(0)
	s_setprio 1
	s_barrier
	v_mfma_f32_16x16x32_bf16 v[62:65], v[130:133], v[196:199], v[62:65]
	v_mfma_f32_16x16x32_bf16 v[58:61], v[138:141], v[196:199], v[58:61]
	v_mfma_f32_16x16x32_bf16 v[46:49], v[130:133], v[204:207], v[46:49]
	v_mfma_f32_16x16x32_bf16 v[42:45], v[138:141], v[204:207], v[42:45]
	v_mfma_f32_16x16x32_bf16 v[30:33], v[130:133], v[212:215], v[30:33]
	v_mfma_f32_16x16x32_bf16 v[26:29], v[138:141], v[212:215], v[26:29]
	v_mfma_f32_16x16x32_bf16 v[14:17], v[130:133], v[220:223], v[14:17]
	v_mfma_f32_16x16x32_bf16 v[10:13], v[138:141], v[220:223], v[10:13]
	v_mfma_f32_16x16x32_bf16 v[62:65], v[134:137], v[200:203], v[62:65]
	v_mfma_f32_16x16x32_bf16 v[58:61], v[142:145], v[200:203], v[58:61]
	v_mfma_f32_16x16x32_bf16 v[46:49], v[134:137], v[208:211], v[46:49]
	v_mfma_f32_16x16x32_bf16 v[42:45], v[142:145], v[208:211], v[42:45]
	v_mfma_f32_16x16x32_bf16 v[30:33], v[134:137], v[216:219], v[30:33]
	v_mfma_f32_16x16x32_bf16 v[26:29], v[142:145], v[216:219], v[26:29]
	v_mfma_f32_16x16x32_bf16 v[14:17], v[134:137], v[224:227], v[14:17]
	v_mfma_f32_16x16x32_bf16 v[10:13], v[142:145], v[224:227], v[10:13]
	s_setprio 0
	s_setprio 1
	v_mfma_f32_16x16x32_bf16 v[54:57], v[168:171], v[196:199], v[54:57]
	v_mfma_f32_16x16x32_bf16 v[50:53], v[188:191], v[196:199], v[50:53]
	v_mfma_f32_16x16x32_bf16 v[38:41], v[168:171], v[204:207], v[38:41]
	v_mfma_f32_16x16x32_bf16 v[34:37], v[188:191], v[204:207], v[34:37]
	v_mfma_f32_16x16x32_bf16 v[22:25], v[168:171], v[212:215], v[22:25]
	v_mfma_f32_16x16x32_bf16 v[18:21], v[188:191], v[212:215], v[18:21]
	v_mfma_f32_16x16x32_bf16 v[6:9], v[168:171], v[220:223], v[6:9]
	v_mfma_f32_16x16x32_bf16 v[2:5], v[188:191], v[220:223], v[2:5]
	v_mfma_f32_16x16x32_bf16 v[54:57], v[184:187], v[200:203], v[54:57]
	v_mfma_f32_16x16x32_bf16 v[50:53], v[192:195], v[200:203], v[50:53]
	v_mfma_f32_16x16x32_bf16 v[38:41], v[184:187], v[208:211], v[38:41]
	v_mfma_f32_16x16x32_bf16 v[34:37], v[192:195], v[208:211], v[34:37]
	v_mfma_f32_16x16x32_bf16 v[22:25], v[184:187], v[216:219], v[22:25]
	v_mfma_f32_16x16x32_bf16 v[18:21], v[192:195], v[216:219], v[18:21]
	v_mfma_f32_16x16x32_bf16 v[6:9], v[184:187], v[224:227], v[6:9]
	v_mfma_f32_16x16x32_bf16 v[2:5], v[192:195], v[224:227], v[2:5]
	s_nop 0
	s_barrier
	s_setprio 0
	s_add_i32 s51, s51, 2
	s_add_u32 s0, s0, 0x100
	s_addc_u32 s1, s1, 0
	s_add_u32 s49, s49, 0x100
	s_addc_u32 s50, s50, 0
	s_cmp_gt_u32 s51, 29
	s_cbranch_scc0 .LBB0_1847
	s_and_b64 vcc, exec, s[8:9]
	s_cbranch_vccz .LBB0_1850
	s_barrier

; #define PG8_STAGE(bufoff, gbase, voff) do { _Pragma("unroll") for (int _i = 0; _i < 2; ++_i) \
;         __builtin_amdgcn_global_load_lds((const unsigned*)((const char*)(gbase) + (voff)[_i]), (PG8_LAS unsigned*)(lds + (bufoff) + ldsw + _i * 8192), 16, 0, 0); } while (0)
; #define PG8_WAIT_V(n) asm volatile("s_waitcnt vmcnt(" #n ")" ::: "memory")
; #define PG8_WAIT_L(n) asm volatile("s_waitcnt lgkmcnt(" #n ")" ::: "memory")
; #define PG8_BAR __builtin_amdgcn_s_barrier()
; #define PG8_SCHED __builtin_amdgcn_sched_barrier(0)
; template <class Epi, class Sched, bool ALIGN_EPI = true, bool SP2 = true>
; __device__ __forceinline__ void gemm_phase(PG8_LAS unsigned char* lds, const int K  , const Sched& S, const Epi& E) {
;     ...
;             PG8_LDB(B0, 0, 0); PG8_LDB(B1, 0, 1); PG8_SCHED; PG8_LDA(At, 0, 0); PG8_STAGE(PG8_SA(1, 1), a1 + hstep, voffA);
;             PG8_WAIT_V(8); PG8_WAIT_L(0); PG8_BAR; PG8_MMA(0, 0, At, B0); PG8_MMA(0, 1, At, B1); PG8_BAR; PG8_SCHED;
;             PG8_LDA(At, 0, 1); PG8_STAGE(PG8_SB(0, 0), b2, voffB); PG8_STAGE(PG8_SB(0, 1), b2 + hstep, voffB); PG8_STAGE(PG8_SA(0, 0), a2, voffA);
;             PG8_WAIT_V(8); PG8_WAIT_L(0); PG8_BAR; PG8_MMA(1, 0, At, B0); PG8_MMA(1, 1, At, B1); PG8_BAR; PG8_SCHED;
.LBB0_2296:
	ds_read_b128 v[130:133], v203
	ds_read_b128 v[134:137], v203 offset:1024
	ds_read_b128 v[138:141], v203 offset:2048
	ds_read_b128 v[142:145], v203 offset:3072
	ds_read_b128 v[146:149], v204
	ds_read_b128 v[150:153], v204 offset:1024
	ds_read_b128 v[154:157], v204 offset:2048
	ds_read_b128 v[158:161], v204 offset:3072
	s_add_u32 s22, s20, 0xfff80080
	s_addc_u32 s23, s21, -1
	s_cmp_eq_u32 s54, 28
	s_cselect_b32 s25, s13, s23
	s_cselect_b32 s24, s50, s22
	s_cselect_b32 s23, s11, s53
	s_cselect_b32 s22, s51, s52
	v_lshl_add_u64 v[198:199], s[20:21], 0, v[190:191]
	s_add_i32 m0, s19, 0xc000
	ds_read_b128 v[162:165], v205
	ds_read_b128 v[166:169], v205 offset:1024
	ds_read_b128 v[170:173], v205 offset:2048
	ds_read_b128 v[174:177], v205 offset:3072
	ds_read_b128 v[178:181], v205 offset:4096
	ds_read_b128 v[206:209], v205 offset:5120
	ds_read_b128 v[210:213], v205 offset:6144
	ds_read_b128 v[214:217], v205 offset:7168
	global_load_lds_dwordx4 v[198:199], off
	v_lshl_add_u64 v[198:199], s[20:21], 0, v[192:193]
	s_add_i32 m0, s19, 0xe000
	s_nop 0
	global_load_lds_dwordx4 v[198:199], off
	s_waitcnt vmcnt(8)
	s_waitcnt lgkmcnt(0)
	s_setprio 1
	s_barrier
	v_mfma_f32_16x16x32_bf16 v[126:129], v[130:133], v[162:165], v[126:129]
	v_mfma_f32_16x16x32_bf16 v[122:125], v[138:141], v[162:165], v[122:125]
	v_mfma_f32_16x16x32_bf16 v[114:117], v[130:133], v[170:173], v[114:117]
	v_mfma_f32_16x16x32_bf16 v[106:109], v[138:141], v[170:173], v[106:109]
	v_mfma_f32_16x16x32_bf16 v[98:101], v[130:133], v[178:181], v[98:101]
	v_mfma_f32_16x16x32_bf16 v[90:93], v[138:141], v[178:181], v[90:93]
	v_mfma_f32_16x16x32_bf16 v[82:85], v[130:133], v[210:213], v[82:85]
	v_mfma_f32_16x16x32_bf16 v[74:77], v[138:141], v[210:213], v[74:77]
	v_mfma_f32_16x16x32_bf16 v[126:129], v[134:137], v[166:169], v[126:129]
	v_mfma_f32_16x16x32_bf16 v[122:125], v[142:145], v[166:169], v[122:125]
	v_mfma_f32_16x16x32_bf16 v[114:117], v[134:137], v[174:177], v[114:117]
	v_mfma_f32_16x16x32_bf16 v[106:109], v[142:145], v[174:177], v[106:109]
	v_mfma_f32_16x16x32_bf16 v[98:101], v[134:137], v[206:209], v[98:101]
	v_mfma_f32_16x16x32_bf16 v[90:93], v[142:145], v[206:209], v[90:93]
	v_mfma_f32_16x16x32_bf16 v[82:85], v[134:137], v[214:217], v[82:85]
	v_mfma_f32_16x16x32_bf16 v[74:77], v[142:145], v[214:217], v[74:77]
	s_setprio 0
	s_setprio 1
	v_mfma_f32_16x16x32_bf16 v[118:121], v[146:149], v[162:165], v[118:121]
	v_mfma_f32_16x16x32_bf16 v[110:113], v[154:157], v[162:165], v[110:113]
	v_mfma_f32_16x16x32_bf16 v[102:105], v[146:149], v[170:173], v[102:105]
	v_mfma_f32_16x16x32_bf16 v[94:97], v[154:157], v[170:173], v[94:97]
	v_mfma_f32_16x16x32_bf16 v[86:89], v[146:149], v[178:181], v[86:89]
	v_mfma_f32_16x16x32_bf16 v[78:81], v[154:157], v[178:181], v[78:81]
	v_mfma_f32_16x16x32_bf16 v[70:73], v[146:149], v[210:213], v[70:73]
	v_mfma_f32_16x16x32_bf16 v[66:69], v[154:157], v[210:213], v[66:69]
	v_mfma_f32_16x16x32_bf16 v[118:121], v[150:153], v[166:169], v[118:121]
	v_mfma_f32_16x16x32_bf16 v[110:113], v[158:161], v[166:169], v[110:113]
	v_mfma_f32_16x16x32_bf16 v[102:105], v[150:153], v[174:177], v[102:105]
	v_mfma_f32_16x16x32_bf16 v[94:97], v[158:161], v[174:177], v[94:97]
	v_mfma_f32_16x16x32_bf16 v[86:89], v[150:153], v[206:209], v[86:89]
	v_mfma_f32_16x16x32_bf16 v[78:81], v[158:161], v[206:209], v[78:81]
	v_mfma_f32_16x16x32_bf16 v[70:73], v[150:153], v[214:217], v[70:73]
	v_mfma_f32_16x16x32_bf16 v[66:69], v[158:161], v[214:217], v[66:69]
	s_nop 0
	s_barrier
	s_setprio 0
	s_add_i32 s55, s42, s29
	v_lshl_add_u64 v[198:199], s[22:23], 0, v[184:185]
	s_mov_b32 m0, s55
	ds_read_b128 v[162:165], v205 offset:16384
	ds_read_b128 v[166:169], v205 offset:17408
	ds_read_b128 v[170:173], v205 offset:18432
	ds_read_b128 v[174:177], v205 offset:19456
	ds_read_b128 v[178:181], v205 offset:20480
	ds_read_b128 v[206:209], v205 offset:21504
	ds_read_b128 v[210:213], v205 offset:22528
	ds_read_b128 v[214:217], v205 offset:23552
	global_load_lds_dwordx4 v[198:199], off
	s_add_i32 m0, s55, 0x2000
	s_add_u32 s56, s22, 0x80000
	v_lshl_add_u64 v[218:219], s[22:23], 0, v[188:189]
	s_addc_u32 s57, s23, 0
	s_add_i32 s55, s43, s29
	global_load_lds_dwordx4 v[218:219], off
	v_lshl_add_u64 v[220:221], s[56:57], 0, v[184:185]
	s_mov_b32 m0, s55
	v_lshl_add_u64 v[222:223], s[24:25], 0, v[186:187]
	global_load_lds_dwordx4 v[220:221], off
	v_lshl_add_u64 v[220:221], s[56:57], 0, v[188:189]
	s_add_i32 m0, s55, 0x2000
	s_nop 0
	global_load_lds_dwordx4 v[220:221], off
	v_lshl_add_u64 v[220:221], s[24:25], 0, v[182:183]
	s_mov_b32 m0, s19
	s_nop 0
	global_load_lds_dwordx4 v[220:221], off
	s_mov_b32 m0, s30
	s_nop 0
	global_load_lds_dwordx4 v[222:223], off
	s_waitcnt vmcnt(8)
	s_waitcnt lgkmcnt(0)
	s_setprio 1
	s_barrier
; #define PG8_STAGE(bufoff, gbase, voff) do { _Pragma("unroll") for (int _i = 0; _i < 2; ++_i) \
;         __builtin_amdgcn_global_load_lds((const unsigned*)((const char*)(gbase) + (voff)[_i]), (PG8_LAS unsigned*)(lds + (bufoff) + ldsw + _i * 8192), 16, 0, 0); } while (0)
; #define PG8_WAIT_V(n) asm volatile("s_waitcnt vmcnt(" #n ")" ::: "memory")
; #define PG8_WAIT_L(n) asm volatile("s_waitcnt lgkmcnt(" #n ")" ::: "memory")
; #define PG8_BAR __builtin_amdgcn_s_barrier()
; #define PG8_SCHED __builtin_amdgcn_sched_barrier(0)
; template <class Epi, class Sched, bool ALIGN_EPI = true, bool SP2 = true>
; __device__ __forceinline__ void gemm_phase(PG8_LAS unsigned char* lds, const int K  , const Sched& S, const Epi& E) {
;     ...
;             PG8_WAIT_V(8); PG8_WAIT_L(0); PG8_BAR; PG8_MMA(1, 0, At, B0); PG8_MMA(1, 1, At, B1); PG8_BAR; PG8_SCHED;
;             PG8_LDB(B0, 1, 0); PG8_LDB(B1, 1, 1); PG8_SCHED; PG8_LDA(At, 1, 0); PG8_STAGE(PG8_SA(0, 1), a2 + hstep, voffA);
;             PG8_WAIT_V(8); PG8_WAIT_L(0); PG8_BAR; PG8_MMA(0, 0, At, B0); PG8_MMA(0, 1, At, B1); PG8_BAR; PG8_SCHED;
	v_mfma_f32_16x16x32_bf16 v[62:65], v[130:133], v[162:165], v[62:65]
	v_mfma_f32_16x16x32_bf16 v[58:61], v[138:141], v[162:165], v[58:61]
	v_mfma_f32_16x16x32_bf16 v[50:53], v[130:133], v[170:173], v[50:53]
	v_mfma_f32_16x16x32_bf16 v[42:45], v[138:141], v[170:173], v[42:45]
	v_mfma_f32_16x16x32_bf16 v[34:37], v[130:133], v[178:181], v[34:37]
	v_mfma_f32_16x16x32_bf16 v[26:29], v[138:141], v[178:181], v[26:29]
	v_mfma_f32_16x16x32_bf16 v[18:21], v[130:133], v[210:213], v[18:21]
	v_mfma_f32_16x16x32_bf16 v[10:13], v[138:141], v[210:213], v[10:13]
	v_mfma_f32_16x16x32_bf16 v[62:65], v[134:137], v[166:169], v[62:65]
	v_mfma_f32_16x16x32_bf16 v[58:61], v[142:145], v[166:169], v[58:61]
	v_mfma_f32_16x16x32_bf16 v[50:53], v[134:137], v[174:177], v[50:53]
	v_mfma_f32_16x16x32_bf16 v[42:45], v[142:145], v[174:177], v[42:45]
	v_mfma_f32_16x16x32_bf16 v[34:37], v[134:137], v[206:209], v[34:37]
	v_mfma_f32_16x16x32_bf16 v[26:29], v[142:145], v[206:209], v[26:29]
	v_mfma_f32_16x16x32_bf16 v[18:21], v[134:137], v[214:217], v[18:21]
	v_mfma_f32_16x16x32_bf16 v[10:13], v[142:145], v[214:217], v[10:13]
	s_setprio 0
	s_setprio 1
	v_mfma_f32_16x16x32_bf16 v[54:57], v[146:149], v[162:165], v[54:57]
	v_mfma_f32_16x16x32_bf16 v[46:49], v[154:157], v[162:165], v[46:49]
	v_mfma_f32_16x16x32_bf16 v[38:41], v[146:149], v[170:173], v[38:41]
	v_mfma_f32_16x16x32_bf16 v[30:33], v[154:157], v[170:173], v[30:33]
	v_mfma_f32_16x16x32_bf16 v[22:25], v[146:149], v[178:181], v[22:25]
	v_mfma_f32_16x16x32_bf16 v[14:17], v[154:157], v[178:181], v[14:17]
	v_mfma_f32_16x16x32_bf16 v[6:9], v[146:149], v[210:213], v[6:9]
	v_mfma_f32_16x16x32_bf16 v[2:5], v[154:157], v[210:213], v[2:5]
	v_mfma_f32_16x16x32_bf16 v[54:57], v[150:153], v[166:169], v[54:57]
	v_mfma_f32_16x16x32_bf16 v[46:49], v[158:161], v[166:169], v[46:49]
	v_mfma_f32_16x16x32_bf16 v[38:41], v[150:153], v[174:177], v[38:41]
	v_mfma_f32_16x16x32_bf16 v[30:33], v[158:161], v[174:177], v[30:33]
	v_mfma_f32_16x16x32_bf16 v[22:25], v[150:153], v[206:209], v[22:25]
	v_mfma_f32_16x16x32_bf16 v[14:17], v[158:161], v[206:209], v[14:17]
	v_mfma_f32_16x16x32_bf16 v[6:9], v[150:153], v[214:217], v[6:9]
	v_mfma_f32_16x16x32_bf16 v[2:5], v[158:161], v[214:217], v[2:5]
	s_nop 0
	s_barrier
	s_setprio 0
	s_add_i32 s55, 0, 0x18000
	s_add_i32 s56, 0, 0x1c000
	v_add_u32_e32 v142, s55, v201
	v_add_u32_e32 v158, s56, v201
	ds_read_b128 v[130:133], v142
	ds_read_b128 v[134:137], v142 offset:1024
	ds_read_b128 v[138:141], v142 offset:2048
	ds_read_b128 v[142:145], v142 offset:3072
	ds_read_b128 v[146:149], v158
	ds_read_b128 v[150:153], v158 offset:1024
	ds_read_b128 v[154:157], v158 offset:2048
	ds_read_b128 v[158:161], v158 offset:3072
	s_add_u32 s24, s24, 0x80000
	s_addc_u32 s25, s25, 0
	s_mov_b32 m0, s31
	v_lshl_add_u64 v[224:225], s[24:25], 0, v[182:183]
	ds_read_b128 v[162:165], v205 offset:32768
	ds_read_b128 v[166:169], v205 offset:33792
	ds_read_b128 v[170:173], v205 offset:34816
	ds_read_b128 v[174:177], v205 offset:35840
	ds_read_b128 v[178:181], v205 offset:36864
	ds_read_b128 v[206:209], v205 offset:37888
	ds_read_b128 v[210:213], v205 offset:38912
	ds_read_b128 v[214:217], v205 offset:39936
	global_load_lds_dwordx4 v[224:225], off
	v_lshl_add_u64 v[224:225], s[24:25], 0, v[186:187]
	s_mov_b32 m0, s33
	s_nop 0
	global_load_lds_dwordx4 v[224:225], off
	s_waitcnt vmcnt(8)
	s_waitcnt lgkmcnt(0)
	s_setprio 1
	s_barrier
	v_mfma_f32_16x16x32_bf16 v[126:129], v[130:133], v[162:165], v[126:129]
	v_mfma_f32_16x16x32_bf16 v[122:125], v[138:141], v[162:165], v[122:125]
	v_mfma_f32_16x16x32_bf16 v[114:117], v[130:133], v[170:173], v[114:117]
	v_mfma_f32_16x16x32_bf16 v[106:109], v[138:141], v[170:173], v[106:109]
	v_mfma_f32_16x16x32_bf16 v[98:101], v[130:133], v[178:181], v[98:101]
	v_mfma_f32_16x16x32_bf16 v[90:93], v[138:141], v[178:181], v[90:93]
	v_mfma_f32_16x16x32_bf16 v[82:85], v[130:133], v[210:213], v[82:85]
	v_mfma_f32_16x16x32_bf16 v[74:77], v[138:141], v[210:213], v[74:77]
	v_mfma_f32_16x16x32_bf16 v[126:129], v[134:137], v[166:169], v[126:129]
	v_mfma_f32_16x16x32_bf16 v[122:125], v[142:145], v[166:169], v[122:125]
	v_mfma_f32_16x16x32_bf16 v[114:117], v[134:137], v[174:177], v[114:117]
	v_mfma_f32_16x16x32_bf16 v[106:109], v[142:145], v[174:177], v[106:109]
	v_mfma_f32_16x16x32_bf16 v[98:101], v[134:137], v[206:209], v[98:101]
	v_mfma_f32_16x16x32_bf16 v[90:93], v[142:145], v[206:209], v[90:93]
	v_mfma_f32_16x16x32_bf16 v[82:85], v[134:137], v[214:217], v[82:85]
	v_mfma_f32_16x16x32_bf16 v[74:77], v[142:145], v[214:217], v[74:77]
	s_setprio 0
	s_setprio 1
	v_mfma_f32_16x16x32_bf16 v[118:121], v[146:149], v[162:165], v[118:121]
	v_mfma_f32_16x16x32_bf16 v[110:113], v[154:157], v[162:165], v[110:113]
	v_mfma_f32_16x16x32_bf16 v[102:105], v[146:149], v[170:173], v[102:105]
	v_mfma_f32_16x16x32_bf16 v[94:97], v[154:157], v[170:173], v[94:97]
	v_mfma_f32_16x16x32_bf16 v[86:89], v[146:149], v[178:181], v[86:89]
	v_mfma_f32_16x16x32_bf16 v[78:81], v[154:157], v[178:181], v[78:81]
	v_mfma_f32_16x16x32_bf16 v[70:73], v[146:149], v[210:213], v[70:73]
	v_mfma_f32_16x16x32_bf16 v[66:69], v[154:157], v[210:213], v[66:69]
	v_mfma_f32_16x16x32_bf16 v[118:121], v[150:153], v[166:169], v[118:121]
	v_mfma_f32_16x16x32_bf16 v[110:113], v[158:161], v[166:169], v[110:113]
	v_mfma_f32_16x16x32_bf16 v[102:105], v[150:153], v[174:177], v[102:105]
	v_mfma_f32_16x16x32_bf16 v[94:97], v[158:161], v[174:177], v[94:97]
	v_mfma_f32_16x16x32_bf16 v[86:89], v[150:153], v[206:209], v[86:89]
	v_mfma_f32_16x16x32_bf16 v[78:81], v[158:161], v[206:209], v[78:81]
	v_mfma_f32_16x16x32_bf16 v[70:73], v[150:153], v[214:217], v[70:73]
	v_mfma_f32_16x16x32_bf16 v[66:69], v[158:161], v[214:217], v[66:69]
	s_nop 0
	s_barrier
; #define PG8_STAGE(bufoff, gbase, voff) do { _Pragma("unroll") for (int _i = 0; _i < 2; ++_i) \
;         __builtin_amdgcn_global_load_lds((const unsigned*)((const char*)(gbase) + (voff)[_i]), (PG8_LAS unsigned*)(lds + (bufoff) + ldsw + _i * 8192), 16, 0, 0); } while (0)
; #define PG8_WAIT_V(n) asm volatile("s_waitcnt vmcnt(" #n ")" ::: "memory")
; #define PG8_WAIT_L(n) asm volatile("s_waitcnt lgkmcnt(" #n ")" ::: "memory")
; #define PG8_BAR __builtin_amdgcn_s_barrier()
; #define PG8_SCHED __builtin_amdgcn_sched_barrier(0)
; template <class Epi, class Sched, bool ALIGN_EPI = true, bool SP2 = true>
; __device__ __forceinline__ void gemm_phase(PG8_LAS unsigned char* lds, const int K  , const Sched& S, const Epi& E) {
;     ...
;             PG8_LDA(At, 1, 1); PG8_STAGE(PG8_SB(1, 0), b3, voffB); PG8_STAGE(PG8_SB(1, 1), b3 + hstep, voffB); PG8_STAGE(PG8_SA(1, 0), a3, voffA);
;             PG8_WAIT_V(8); PG8_WAIT_L(0); PG8_BAR; PG8_MMA(1, 0, At, B0); PG8_MMA(1, 1, At, B1); PG8_BAR; PG8_SCHED;
;     ...
;         if constexpr (ALIGN_EPI) { if (wr == 0) PG8_BAR; }
	s_setprio 0
	s_add_i32 s24, s55, s29
	v_lshl_add_u64 v[198:199], v[198:199], 0, s[6:7]
	s_mov_b32 m0, s24
	ds_read_b128 v[162:165], v205 offset:49152
	ds_read_b128 v[166:169], v205 offset:50176
	ds_read_b128 v[170:173], v205 offset:51200
	ds_read_b128 v[174:177], v205 offset:52224
	ds_read_b128 v[178:181], v205 offset:53248
	ds_read_b128 v[206:209], v205 offset:54272
	ds_read_b128 v[210:213], v205 offset:55296
	ds_read_b128 v[214:217], v205 offset:56320
	global_load_lds_dwordx4 v[198:199], off
	s_add_i32 m0, s24, 0x2000
	s_add_u32 s22, s22, 0x80080
	v_lshl_add_u64 v[198:199], v[218:219], 0, s[6:7]
	s_addc_u32 s23, s23, 0
	s_add_i32 s24, s56, s29
	global_load_lds_dwordx4 v[198:199], off
	v_lshl_add_u64 v[198:199], s[22:23], 0, v[184:185]
	s_mov_b32 m0, s24
	s_nop 0
	global_load_lds_dwordx4 v[198:199], off
	v_lshl_add_u64 v[198:199], s[22:23], 0, v[188:189]
	s_add_i32 m0, s24, 0x2000
	s_nop 0
	global_load_lds_dwordx4 v[198:199], off
	v_lshl_add_u64 v[198:199], v[220:221], 0, s[6:7]
	s_mov_b32 m0, s38
	s_nop 0
	global_load_lds_dwordx4 v[198:199], off
	v_lshl_add_u64 v[198:199], v[222:223], 0, s[6:7]
	s_mov_b32 m0, s39
	s_nop 0
	global_load_lds_dwordx4 v[198:199], off
	s_waitcnt vmcnt(8)
	s_waitcnt lgkmcnt(0)
	s_setprio 1
	s_barrier
	v_mfma_f32_16x16x32_bf16 v[62:65], v[130:133], v[162:165], v[62:65]
	v_mfma_f32_16x16x32_bf16 v[58:61], v[138:141], v[162:165], v[58:61]
	v_mfma_f32_16x16x32_bf16 v[50:53], v[130:133], v[170:173], v[50:53]
	v_mfma_f32_16x16x32_bf16 v[42:45], v[138:141], v[170:173], v[42:45]
	v_mfma_f32_16x16x32_bf16 v[34:37], v[130:133], v[178:181], v[34:37]
	v_mfma_f32_16x16x32_bf16 v[26:29], v[138:141], v[178:181], v[26:29]
	v_mfma_f32_16x16x32_bf16 v[18:21], v[130:133], v[210:213], v[18:21]
	v_mfma_f32_16x16x32_bf16 v[10:13], v[138:141], v[210:213], v[10:13]
	v_mfma_f32_16x16x32_bf16 v[62:65], v[134:137], v[166:169], v[62:65]
	v_mfma_f32_16x16x32_bf16 v[58:61], v[142:145], v[166:169], v[58:61]
	v_mfma_f32_16x16x32_bf16 v[50:53], v[134:137], v[174:177], v[50:53]
	v_mfma_f32_16x16x32_bf16 v[42:45], v[142:145], v[174:177], v[42:45]
	v_mfma_f32_16x16x32_bf16 v[34:37], v[134:137], v[206:209], v[34:37]
	v_mfma_f32_16x16x32_bf16 v[26:29], v[142:145], v[206:209], v[26:29]
	v_mfma_f32_16x16x32_bf16 v[18:21], v[134:137], v[214:217], v[18:21]
	v_mfma_f32_16x16x32_bf16 v[10:13], v[142:145], v[214:217], v[10:13]
	s_setprio 0
	s_setprio 1
	v_mfma_f32_16x16x32_bf16 v[54:57], v[146:149], v[162:165], v[54:57]
	v_mfma_f32_16x16x32_bf16 v[46:49], v[154:157], v[162:165], v[46:49]
	v_mfma_f32_16x16x32_bf16 v[38:41], v[146:149], v[170:173], v[38:41]
	v_mfma_f32_16x16x32_bf16 v[30:33], v[154:157], v[170:173], v[30:33]
	v_mfma_f32_16x16x32_bf16 v[22:25], v[146:149], v[178:181], v[22:25]
	v_mfma_f32_16x16x32_bf16 v[14:17], v[154:157], v[178:181], v[14:17]
	v_mfma_f32_16x16x32_bf16 v[6:9], v[146:149], v[210:213], v[6:9]
	v_mfma_f32_16x16x32_bf16 v[2:5], v[154:157], v[210:213], v[2:5]
	v_mfma_f32_16x16x32_bf16 v[54:57], v[150:153], v[166:169], v[54:57]
	v_mfma_f32_16x16x32_bf16 v[46:49], v[158:161], v[166:169], v[46:49]
	v_mfma_f32_16x16x32_bf16 v[38:41], v[150:153], v[174:177], v[38:41]
	v_mfma_f32_16x16x32_bf16 v[30:33], v[158:161], v[174:177], v[30:33]
	v_mfma_f32_16x16x32_bf16 v[22:25], v[150:153], v[206:209], v[22:25]
	v_mfma_f32_16x16x32_bf16 v[14:17], v[158:161], v[206:209], v[14:17]
	v_mfma_f32_16x16x32_bf16 v[6:9], v[150:153], v[214:217], v[6:9]
	v_mfma_f32_16x16x32_bf16 v[2:5], v[158:161], v[214:217], v[2:5]
	s_nop 0
	s_barrier
	s_setprio 0
	s_add_i32 s54, s54, 2
	s_add_u32 s20, s20, 0x100
	s_addc_u32 s21, s21, 0
	s_add_u32 s52, s52, 0x100
	s_addc_u32 s53, s53, 0
	s_cmp_gt_u32 s54, 29
	s_cbranch_scc0 .LBB0_2296
	s_and_b64 vcc, exec, s[8:9]
	s_cbranch_vccz .LBB0_2299
	s_barrier

; #define PG8_STAGE(bufoff, gbase, voff) do { _Pragma("unroll") for (int _i = 0; _i < 2; ++_i) \
;         __builtin_amdgcn_global_load_lds((const unsigned*)((const char*)(gbase) + (voff)[_i]), (PG8_LAS unsigned*)(lds + (bufoff) + ldsw + _i * 8192), 16, 0, 0); } while (0)
; #define PG8_WAIT_V(n) asm volatile("s_waitcnt vmcnt(" #n ")" ::: "memory")
; #define PG8_WAIT_L(n) asm volatile("s_waitcnt lgkmcnt(" #n ")" ::: "memory")
; #define PG8_BAR __builtin_amdgcn_s_barrier()
; #define PG8_SCHED __builtin_amdgcn_sched_barrier(0)
; template <class Epi, class Sched, bool ALIGN_EPI = true, bool SP2 = true>
; __device__ __forceinline__ void gemm_phase(PG8_LAS unsigned char* lds, const int K  , const Sched& S, const Epi& E) {
;     ...
;             PG8_LDB(B0, 0, 0); PG8_LDB(B1, 0, 1); PG8_SCHED; PG8_LDA(At, 0, 0); PG8_STAGE(PG8_SA(1, 1), a1 + hstep, voffA);
;             PG8_WAIT_V(8); PG8_WAIT_L(0); PG8_BAR; PG8_MMA(0, 0, At, B0); PG8_MMA(0, 1, At, B1); PG8_BAR; PG8_SCHED;
;             PG8_LDA(At, 0, 1); PG8_STAGE(PG8_SB(0, 0), b2, voffB); PG8_STAGE(PG8_SB(0, 1), b2 + hstep, voffB); PG8_STAGE(PG8_SA(0, 0), a2, voffA);
;             PG8_WAIT_V(8); PG8_WAIT_L(0); PG8_BAR; PG8_MMA(1, 0, At, B0); PG8_MMA(1, 1, At, B1); PG8_BAR; PG8_SCHED;
.LBB0_2433:
	ds_read_b128 v[146:149], v152
	ds_read_b128 v[158:161], v152 offset:1024
	ds_read_b128 v[162:165], v152 offset:2048
	ds_read_b128 v[166:169], v152 offset:3072
	ds_read_b128 v[170:173], v153
	ds_read_b128 v[174:177], v153 offset:1024
	ds_read_b128 v[178:181], v153 offset:2048
	ds_read_b128 v[182:185], v153 offset:3072
	s_add_u32 s22, s20, 0xfff80080
	s_addc_u32 s23, s21, -1
	s_cmp_eq_u32 s48, 28
	s_cselect_b32 s25, s13, s23
	s_cselect_b32 s24, s44, s22
	s_cselect_b32 s23, s11, s47
	s_cselect_b32 s22, s45, s46
	v_lshl_add_u64 v[218:219], s[20:21], 0, v[138:139]
	s_add_i32 m0, s19, 0xc000
	ds_read_b128 v[186:189], v154
	ds_read_b128 v[190:193], v154 offset:1024
	ds_read_b128 v[194:197], v154 offset:2048
	ds_read_b128 v[198:201], v154 offset:3072
	ds_read_b128 v[202:205], v154 offset:4096
	ds_read_b128 v[206:209], v154 offset:5120
	ds_read_b128 v[210:213], v154 offset:6144
	ds_read_b128 v[214:217], v154 offset:7168
	global_load_lds_dwordx4 v[218:219], off
	v_lshl_add_u64 v[218:219], s[20:21], 0, v[140:141]
	s_add_i32 m0, s19, 0xe000
	s_nop 0
	global_load_lds_dwordx4 v[218:219], off
	s_waitcnt vmcnt(8)
	s_waitcnt lgkmcnt(0)
	s_setprio 1
	s_barrier
	v_mfma_f32_16x16x32_bf16 v[126:129], v[146:149], v[186:189], v[126:129]
	v_mfma_f32_16x16x32_bf16 v[118:121], v[162:165], v[186:189], v[118:121]
	v_mfma_f32_16x16x32_bf16 v[110:113], v[146:149], v[194:197], v[110:113]
	v_mfma_f32_16x16x32_bf16 v[102:105], v[162:165], v[194:197], v[102:105]
	v_mfma_f32_16x16x32_bf16 v[94:97], v[146:149], v[202:205], v[94:97]
	v_mfma_f32_16x16x32_bf16 v[86:89], v[162:165], v[202:205], v[86:89]
	v_mfma_f32_16x16x32_bf16 v[78:81], v[146:149], v[210:213], v[78:81]
	v_mfma_f32_16x16x32_bf16 v[70:73], v[162:165], v[210:213], v[70:73]
	v_mfma_f32_16x16x32_bf16 v[126:129], v[158:161], v[190:193], v[126:129]
	v_mfma_f32_16x16x32_bf16 v[118:121], v[166:169], v[190:193], v[118:121]
	v_mfma_f32_16x16x32_bf16 v[110:113], v[158:161], v[198:201], v[110:113]
	v_mfma_f32_16x16x32_bf16 v[102:105], v[166:169], v[198:201], v[102:105]
	v_mfma_f32_16x16x32_bf16 v[94:97], v[158:161], v[206:209], v[94:97]
	v_mfma_f32_16x16x32_bf16 v[86:89], v[166:169], v[206:209], v[86:89]
	v_mfma_f32_16x16x32_bf16 v[78:81], v[158:161], v[214:217], v[78:81]
	v_mfma_f32_16x16x32_bf16 v[70:73], v[166:169], v[214:217], v[70:73]
	s_setprio 0
	s_setprio 1
	v_mfma_f32_16x16x32_bf16 v[122:125], v[170:173], v[186:189], v[122:125]
	v_mfma_f32_16x16x32_bf16 v[114:117], v[178:181], v[186:189], v[114:117]
	v_mfma_f32_16x16x32_bf16 v[106:109], v[170:173], v[194:197], v[106:109]
	v_mfma_f32_16x16x32_bf16 v[98:101], v[178:181], v[194:197], v[98:101]
	v_mfma_f32_16x16x32_bf16 v[90:93], v[170:173], v[202:205], v[90:93]
	v_mfma_f32_16x16x32_bf16 v[82:85], v[178:181], v[202:205], v[82:85]
	v_mfma_f32_16x16x32_bf16 v[74:77], v[170:173], v[210:213], v[74:77]
	v_mfma_f32_16x16x32_bf16 v[66:69], v[178:181], v[210:213], v[66:69]
	v_mfma_f32_16x16x32_bf16 v[122:125], v[174:177], v[190:193], v[122:125]
	v_mfma_f32_16x16x32_bf16 v[114:117], v[182:185], v[190:193], v[114:117]
	v_mfma_f32_16x16x32_bf16 v[106:109], v[174:177], v[198:201], v[106:109]
	v_mfma_f32_16x16x32_bf16 v[98:101], v[182:185], v[198:201], v[98:101]
	v_mfma_f32_16x16x32_bf16 v[90:93], v[174:177], v[206:209], v[90:93]
	v_mfma_f32_16x16x32_bf16 v[82:85], v[182:185], v[206:209], v[82:85]
	v_mfma_f32_16x16x32_bf16 v[74:77], v[174:177], v[214:217], v[74:77]
	v_mfma_f32_16x16x32_bf16 v[66:69], v[182:185], v[214:217], v[66:69]
	s_nop 0
	s_barrier
	s_setprio 0
	s_add_i32 s49, s39, s28
	v_lshl_add_u64 v[218:219], s[22:23], 0, v[134:135]
	s_mov_b32 m0, s49
	ds_read_b128 v[186:189], v154 offset:16384
	ds_read_b128 v[190:193], v154 offset:17408
	ds_read_b128 v[194:197], v154 offset:18432
	ds_read_b128 v[198:201], v154 offset:19456
	ds_read_b128 v[202:205], v154 offset:20480
	ds_read_b128 v[206:209], v154 offset:21504
	ds_read_b128 v[210:213], v154 offset:22528
	ds_read_b128 v[214:217], v154 offset:23552
	global_load_lds_dwordx4 v[218:219], off
	s_add_i32 m0, s49, 0x2000
	s_add_u32 s50, s22, 0x80000
	v_lshl_add_u64 v[220:221], s[22:23], 0, v[130:131]
	s_addc_u32 s51, s23, 0
	s_add_i32 s49, s40, s28
	global_load_lds_dwordx4 v[220:221], off
	v_lshl_add_u64 v[222:223], s[50:51], 0, v[134:135]
	s_mov_b32 m0, s49
	v_lshl_add_u64 v[224:225], s[24:25], 0, v[132:133]
	global_load_lds_dwordx4 v[222:223], off
	v_lshl_add_u64 v[222:223], s[50:51], 0, v[130:131]
	s_add_i32 m0, s49, 0x2000
	s_nop 0
	global_load_lds_dwordx4 v[222:223], off
	v_lshl_add_u64 v[222:223], s[24:25], 0, v[136:137]
	s_mov_b32 m0, s19
	s_nop 0
	global_load_lds_dwordx4 v[222:223], off
	s_mov_b32 m0, s31
	s_nop 0
	global_load_lds_dwordx4 v[224:225], off
	s_waitcnt vmcnt(8)
	s_waitcnt lgkmcnt(0)
	s_setprio 1
	s_barrier
; #define PG8_STAGE(bufoff, gbase, voff) do { _Pragma("unroll") for (int _i = 0; _i < 2; ++_i) \
;         __builtin_amdgcn_global_load_lds((const unsigned*)((const char*)(gbase) + (voff)[_i]), (PG8_LAS unsigned*)(lds + (bufoff) + ldsw + _i * 8192), 16, 0, 0); } while (0)
; #define PG8_WAIT_V(n) asm volatile("s_waitcnt vmcnt(" #n ")" ::: "memory")
; #define PG8_WAIT_L(n) asm volatile("s_waitcnt lgkmcnt(" #n ")" ::: "memory")
; #define PG8_BAR __builtin_amdgcn_s_barrier()
; #define PG8_SCHED __builtin_amdgcn_sched_barrier(0)
; template <class Epi, class Sched, bool ALIGN_EPI = true, bool SP2 = true>
; __device__ __forceinline__ void gemm_phase(PG8_LAS unsigned char* lds, const int K  , const Sched& S, const Epi& E) {
;     ...
;             PG8_WAIT_V(8); PG8_WAIT_L(0); PG8_BAR; PG8_MMA(1, 0, At, B0); PG8_MMA(1, 1, At, B1); PG8_BAR; PG8_SCHED;
;             PG8_LDB(B0, 1, 0); PG8_LDB(B1, 1, 1); PG8_SCHED; PG8_LDA(At, 1, 0); PG8_STAGE(PG8_SA(0, 1), a2 + hstep, voffA);
;             PG8_WAIT_V(8); PG8_WAIT_L(0); PG8_BAR; PG8_MMA(0, 0, At, B0); PG8_MMA(0, 1, At, B1); PG8_BAR; PG8_SCHED;
	v_mfma_f32_16x16x32_bf16 v[62:65], v[146:149], v[186:189], v[62:65]
	v_mfma_f32_16x16x32_bf16 v[54:57], v[162:165], v[186:189], v[54:57]
	v_mfma_f32_16x16x32_bf16 v[46:49], v[146:149], v[194:197], v[46:49]
	v_mfma_f32_16x16x32_bf16 v[38:41], v[162:165], v[194:197], v[38:41]
	v_mfma_f32_16x16x32_bf16 v[30:33], v[146:149], v[202:205], v[30:33]
	v_mfma_f32_16x16x32_bf16 v[22:25], v[162:165], v[202:205], v[22:25]
	v_mfma_f32_16x16x32_bf16 v[14:17], v[146:149], v[210:213], v[14:17]
	v_mfma_f32_16x16x32_bf16 v[6:9], v[162:165], v[210:213], v[6:9]
	v_mfma_f32_16x16x32_bf16 v[62:65], v[158:161], v[190:193], v[62:65]
	v_mfma_f32_16x16x32_bf16 v[54:57], v[166:169], v[190:193], v[54:57]
	v_mfma_f32_16x16x32_bf16 v[46:49], v[158:161], v[198:201], v[46:49]
	v_mfma_f32_16x16x32_bf16 v[38:41], v[166:169], v[198:201], v[38:41]
	v_mfma_f32_16x16x32_bf16 v[30:33], v[158:161], v[206:209], v[30:33]
	v_mfma_f32_16x16x32_bf16 v[22:25], v[166:169], v[206:209], v[22:25]
	v_mfma_f32_16x16x32_bf16 v[14:17], v[158:161], v[214:217], v[14:17]
	v_mfma_f32_16x16x32_bf16 v[6:9], v[166:169], v[214:217], v[6:9]
	s_setprio 0
	s_setprio 1
	v_mfma_f32_16x16x32_bf16 v[58:61], v[170:173], v[186:189], v[58:61]
	v_mfma_f32_16x16x32_bf16 v[50:53], v[178:181], v[186:189], v[50:53]
	v_mfma_f32_16x16x32_bf16 v[42:45], v[170:173], v[194:197], v[42:45]
	v_mfma_f32_16x16x32_bf16 v[34:37], v[178:181], v[194:197], v[34:37]
	v_mfma_f32_16x16x32_bf16 v[26:29], v[170:173], v[202:205], v[26:29]
	v_mfma_f32_16x16x32_bf16 v[18:21], v[178:181], v[202:205], v[18:21]
	v_mfma_f32_16x16x32_bf16 v[10:13], v[170:173], v[210:213], v[10:13]
	v_mfma_f32_16x16x32_bf16 v[2:5], v[178:181], v[210:213], v[2:5]
	v_mfma_f32_16x16x32_bf16 v[58:61], v[174:177], v[190:193], v[58:61]
	v_mfma_f32_16x16x32_bf16 v[50:53], v[182:185], v[190:193], v[50:53]
	v_mfma_f32_16x16x32_bf16 v[42:45], v[174:177], v[198:201], v[42:45]
	v_mfma_f32_16x16x32_bf16 v[34:37], v[182:185], v[198:201], v[34:37]
	v_mfma_f32_16x16x32_bf16 v[26:29], v[174:177], v[206:209], v[26:29]
	v_mfma_f32_16x16x32_bf16 v[18:21], v[182:185], v[206:209], v[18:21]
	v_mfma_f32_16x16x32_bf16 v[10:13], v[174:177], v[214:217], v[10:13]
	v_mfma_f32_16x16x32_bf16 v[2:5], v[182:185], v[214:217], v[2:5]
	s_nop 0
	s_barrier
	s_setprio 0
	s_add_i32 s49, 0, 0x18000
	v_add_u32_e32 v157, s49, v150
	s_add_i32 s50, 0, 0x1c000
	ds_read_b128 v[146:149], v157
	ds_read_b128 v[158:161], v157 offset:1024
	ds_read_b128 v[162:165], v157 offset:2048
	ds_read_b128 v[166:169], v157 offset:3072
	v_add_u32_e32 v157, s50, v150
	ds_read_b128 v[170:173], v157
	ds_read_b128 v[174:177], v157 offset:1024
	ds_read_b128 v[178:181], v157 offset:2048
	ds_read_b128 v[182:185], v157 offset:3072
	s_add_u32 s24, s24, 0x80000
	s_addc_u32 s25, s25, 0
	s_mov_b32 m0, s33
	v_lshl_add_u64 v[226:227], s[24:25], 0, v[136:137]
	ds_read_b128 v[186:189], v154 offset:32768
	ds_read_b128 v[190:193], v154 offset:33792
	ds_read_b128 v[194:197], v154 offset:34816
	ds_read_b128 v[198:201], v154 offset:35840
	ds_read_b128 v[202:205], v154 offset:36864
	ds_read_b128 v[206:209], v154 offset:37888
	ds_read_b128 v[210:213], v154 offset:38912
	ds_read_b128 v[214:217], v154 offset:39936
	global_load_lds_dwordx4 v[226:227], off
	v_lshl_add_u64 v[226:227], s[24:25], 0, v[132:133]
	s_mov_b32 m0, s34
	s_nop 0
	global_load_lds_dwordx4 v[226:227], off
	s_waitcnt vmcnt(8)
	s_waitcnt lgkmcnt(0)
	s_setprio 1
	s_barrier
	v_mfma_f32_16x16x32_bf16 v[126:129], v[146:149], v[186:189], v[126:129]
	v_mfma_f32_16x16x32_bf16 v[118:121], v[162:165], v[186:189], v[118:121]
	v_mfma_f32_16x16x32_bf16 v[110:113], v[146:149], v[194:197], v[110:113]
	v_mfma_f32_16x16x32_bf16 v[102:105], v[162:165], v[194:197], v[102:105]
	v_mfma_f32_16x16x32_bf16 v[94:97], v[146:149], v[202:205], v[94:97]
	v_mfma_f32_16x16x32_bf16 v[86:89], v[162:165], v[202:205], v[86:89]
	v_mfma_f32_16x16x32_bf16 v[78:81], v[146:149], v[210:213], v[78:81]
	v_mfma_f32_16x16x32_bf16 v[70:73], v[162:165], v[210:213], v[70:73]
	v_mfma_f32_16x16x32_bf16 v[126:129], v[158:161], v[190:193], v[126:129]
	v_mfma_f32_16x16x32_bf16 v[118:121], v[166:169], v[190:193], v[118:121]
	v_mfma_f32_16x16x32_bf16 v[110:113], v[158:161], v[198:201], v[110:113]
	v_mfma_f32_16x16x32_bf16 v[102:105], v[166:169], v[198:201], v[102:105]
	v_mfma_f32_16x16x32_bf16 v[94:97], v[158:161], v[206:209], v[94:97]
	v_mfma_f32_16x16x32_bf16 v[86:89], v[166:169], v[206:209], v[86:89]
	v_mfma_f32_16x16x32_bf16 v[78:81], v[158:161], v[214:217], v[78:81]
	v_mfma_f32_16x16x32_bf16 v[70:73], v[166:169], v[214:217], v[70:73]
	s_setprio 0
	s_setprio 1
	v_mfma_f32_16x16x32_bf16 v[122:125], v[170:173], v[186:189], v[122:125]
	v_mfma_f32_16x16x32_bf16 v[114:117], v[178:181], v[186:189], v[114:117]
	v_mfma_f32_16x16x32_bf16 v[106:109], v[170:173], v[194:197], v[106:109]
	v_mfma_f32_16x16x32_bf16 v[98:101], v[178:181], v[194:197], v[98:101]
	v_mfma_f32_16x16x32_bf16 v[90:93], v[170:173], v[202:205], v[90:93]
	v_mfma_f32_16x16x32_bf16 v[82:85], v[178:181], v[202:205], v[82:85]
	v_mfma_f32_16x16x32_bf16 v[74:77], v[170:173], v[210:213], v[74:77]
	v_mfma_f32_16x16x32_bf16 v[66:69], v[178:181], v[210:213], v[66:69]
	v_mfma_f32_16x16x32_bf16 v[122:125], v[174:177], v[190:193], v[122:125]
	v_mfma_f32_16x16x32_bf16 v[114:117], v[182:185], v[190:193], v[114:117]
	v_mfma_f32_16x16x32_bf16 v[106:109], v[174:177], v[198:201], v[106:109]
	v_mfma_f32_16x16x32_bf16 v[98:101], v[182:185], v[198:201], v[98:101]
	v_mfma_f32_16x16x32_bf16 v[90:93], v[174:177], v[206:209], v[90:93]
	v_mfma_f32_16x16x32_bf16 v[82:85], v[182:185], v[206:209], v[82:85]
	v_mfma_f32_16x16x32_bf16 v[74:77], v[174:177], v[214:217], v[74:77]
	v_mfma_f32_16x16x32_bf16 v[66:69], v[182:185], v[214:217], v[66:69]
	s_nop 0
	s_barrier
; #define PG8_STAGE(bufoff, gbase, voff) do { _Pragma("unroll") for (int _i = 0; _i < 2; ++_i) \
;         __builtin_amdgcn_global_load_lds((const unsigned*)((const char*)(gbase) + (voff)[_i]), (PG8_LAS unsigned*)(lds + (bufoff) + ldsw + _i * 8192), 16, 0, 0); } while (0)
; #define PG8_WAIT_V(n) asm volatile("s_waitcnt vmcnt(" #n ")" ::: "memory")
; #define PG8_WAIT_L(n) asm volatile("s_waitcnt lgkmcnt(" #n ")" ::: "memory")
; #define PG8_BAR __builtin_amdgcn_s_barrier()
; #define PG8_SCHED __builtin_amdgcn_sched_barrier(0)
; template <class Epi, class Sched, bool ALIGN_EPI = true, bool SP2 = true>
; __device__ __forceinline__ void gemm_phase(PG8_LAS unsigned char* lds, const int K  , const Sched& S, const Epi& E) {
;     ...
;             PG8_LDA(At, 1, 1); PG8_STAGE(PG8_SB(1, 0), b3, voffB); PG8_STAGE(PG8_SB(1, 1), b3 + hstep, voffB); PG8_STAGE(PG8_SA(1, 0), a3, voffA);
;             PG8_WAIT_V(8); PG8_WAIT_L(0); PG8_BAR; PG8_MMA(1, 0, At, B0); PG8_MMA(1, 1, At, B1); PG8_BAR; PG8_SCHED;
;     ...
;         if constexpr (ALIGN_EPI) { if (wr == 0) PG8_BAR; }
	s_setprio 0
	s_add_i32 s24, s49, s28
	v_lshl_add_u64 v[218:219], v[218:219], 0, s[6:7]
	s_mov_b32 m0, s24
	ds_read_b128 v[186:189], v154 offset:49152
	ds_read_b128 v[190:193], v154 offset:50176
	ds_read_b128 v[194:197], v154 offset:51200
	ds_read_b128 v[198:201], v154 offset:52224
	ds_read_b128 v[202:205], v154 offset:53248
	ds_read_b128 v[206:209], v154 offset:54272
	ds_read_b128 v[210:213], v154 offset:55296
	ds_read_b128 v[214:217], v154 offset:56320
	global_load_lds_dwordx4 v[218:219], off
	s_add_i32 m0, s24, 0x2000
	s_add_u32 s22, s22, 0x80080
	v_lshl_add_u64 v[218:219], v[220:221], 0, s[6:7]
	s_addc_u32 s23, s23, 0
	s_add_i32 s24, s50, s28
	global_load_lds_dwordx4 v[218:219], off
	v_lshl_add_u64 v[218:219], s[22:23], 0, v[134:135]
	s_mov_b32 m0, s24
	s_nop 0
	global_load_lds_dwordx4 v[218:219], off
	v_lshl_add_u64 v[218:219], s[22:23], 0, v[130:131]
	s_add_i32 m0, s24, 0x2000
	s_nop 0
	global_load_lds_dwordx4 v[218:219], off
	v_lshl_add_u64 v[218:219], v[222:223], 0, s[6:7]
	s_mov_b32 m0, s36
	s_nop 0
	global_load_lds_dwordx4 v[218:219], off
	v_lshl_add_u64 v[218:219], v[224:225], 0, s[6:7]
	s_mov_b32 m0, s37
	s_nop 0
	global_load_lds_dwordx4 v[218:219], off
	s_waitcnt vmcnt(8)
	s_waitcnt lgkmcnt(0)
	s_setprio 1
	s_barrier
	v_mfma_f32_16x16x32_bf16 v[62:65], v[146:149], v[186:189], v[62:65]
	v_mfma_f32_16x16x32_bf16 v[54:57], v[162:165], v[186:189], v[54:57]
	v_mfma_f32_16x16x32_bf16 v[46:49], v[146:149], v[194:197], v[46:49]
	v_mfma_f32_16x16x32_bf16 v[38:41], v[162:165], v[194:197], v[38:41]
	v_mfma_f32_16x16x32_bf16 v[30:33], v[146:149], v[202:205], v[30:33]
	v_mfma_f32_16x16x32_bf16 v[22:25], v[162:165], v[202:205], v[22:25]
	v_mfma_f32_16x16x32_bf16 v[14:17], v[146:149], v[210:213], v[14:17]
	v_mfma_f32_16x16x32_bf16 v[6:9], v[162:165], v[210:213], v[6:9]
	v_mfma_f32_16x16x32_bf16 v[62:65], v[158:161], v[190:193], v[62:65]
	v_mfma_f32_16x16x32_bf16 v[54:57], v[166:169], v[190:193], v[54:57]
	v_mfma_f32_16x16x32_bf16 v[46:49], v[158:161], v[198:201], v[46:49]
	v_mfma_f32_16x16x32_bf16 v[38:41], v[166:169], v[198:201], v[38:41]
	v_mfma_f32_16x16x32_bf16 v[30:33], v[158:161], v[206:209], v[30:33]
	v_mfma_f32_16x16x32_bf16 v[22:25], v[166:169], v[206:209], v[22:25]
	v_mfma_f32_16x16x32_bf16 v[14:17], v[158:161], v[214:217], v[14:17]
	v_mfma_f32_16x16x32_bf16 v[6:9], v[166:169], v[214:217], v[6:9]
	s_setprio 0
	s_setprio 1
	v_mfma_f32_16x16x32_bf16 v[58:61], v[170:173], v[186:189], v[58:61]
	v_mfma_f32_16x16x32_bf16 v[50:53], v[178:181], v[186:189], v[50:53]
	v_mfma_f32_16x16x32_bf16 v[42:45], v[170:173], v[194:197], v[42:45]
	v_mfma_f32_16x16x32_bf16 v[34:37], v[178:181], v[194:197], v[34:37]
	v_mfma_f32_16x16x32_bf16 v[26:29], v[170:173], v[202:205], v[26:29]
	v_mfma_f32_16x16x32_bf16 v[18:21], v[178:181], v[202:205], v[18:21]
	v_mfma_f32_16x16x32_bf16 v[10:13], v[170:173], v[210:213], v[10:13]
	v_mfma_f32_16x16x32_bf16 v[2:5], v[178:181], v[210:213], v[2:5]
	v_mfma_f32_16x16x32_bf16 v[58:61], v[174:177], v[190:193], v[58:61]
	v_mfma_f32_16x16x32_bf16 v[50:53], v[182:185], v[190:193], v[50:53]
	v_mfma_f32_16x16x32_bf16 v[42:45], v[174:177], v[198:201], v[42:45]
	v_mfma_f32_16x16x32_bf16 v[34:37], v[182:185], v[198:201], v[34:37]
	v_mfma_f32_16x16x32_bf16 v[26:29], v[174:177], v[206:209], v[26:29]
	v_mfma_f32_16x16x32_bf16 v[18:21], v[182:185], v[206:209], v[18:21]
	v_mfma_f32_16x16x32_bf16 v[10:13], v[174:177], v[214:217], v[10:13]
	v_mfma_f32_16x16x32_bf16 v[2:5], v[182:185], v[214:217], v[2:5]
	s_nop 0
	s_barrier
	s_setprio 0
	s_add_i32 s48, s48, 2
	s_add_u32 s20, s20, 0x100
	s_addc_u32 s21, s21, 0
	s_add_u32 s46, s46, 0x100
	s_addc_u32 s47, s47, 0
	s_cmp_gt_u32 s48, 29
	s_cbranch_scc0 .LBB0_2433
	s_and_b64 vcc, exec, s[8:9]
	s_cbranch_vccz .LBB0_2436
	s_barrier

; #define PG8_STAGE(bufoff, gbase, voff) do { _Pragma("unroll") for (int _i = 0; _i < 2; ++_i) \
;         __builtin_amdgcn_global_load_lds((const unsigned*)((const char*)(gbase) + (voff)[_i]), (PG8_LAS unsigned*)(lds + (bufoff) + ldsw + _i * 8192), 16, 0, 0); } while (0)
; #define PG8_WAIT_V(n) asm volatile("s_waitcnt vmcnt(" #n ")" ::: "memory")
; #define PG8_WAIT_L(n) asm volatile("s_waitcnt lgkmcnt(" #n ")" ::: "memory")
; #define PG8_BAR __builtin_amdgcn_s_barrier()
; #define PG8_SCHED __builtin_amdgcn_sched_barrier(0)
; template <class Epi, class Sched, bool ALIGN_EPI = true, bool SP2 = true>
; __device__ __forceinline__ void gemm_phase(PG8_LAS unsigned char* lds, const int K  , const Sched& S, const Epi& E) {
;     ...
;             PG8_LDB(B0, 0, 0); PG8_LDB(B1, 0, 1); PG8_SCHED; PG8_LDA(At, 0, 0); PG8_STAGE(PG8_SA(1, 1), a1 + hstep, voffA);
;             PG8_WAIT_V(8); PG8_WAIT_L(0); PG8_BAR; PG8_MMA(0, 0, At, B0); PG8_MMA(0, 1, At, B1); PG8_BAR; PG8_SCHED;
;             PG8_LDA(At, 0, 1); PG8_STAGE(PG8_SB(0, 0), b2, voffB); PG8_STAGE(PG8_SB(0, 1), b2 + hstep, voffB); PG8_STAGE(PG8_SA(0, 0), a2, voffA);
;             PG8_WAIT_V(8); PG8_WAIT_L(0); PG8_BAR; PG8_MMA(1, 0, At, B0); PG8_MMA(1, 1, At, B1); PG8_BAR; PG8_SCHED;
.LBB0_2516:
	ds_read_b128 v[16:19], v206
	ds_read_b128 v[20:23], v206 offset:1024
	ds_read_b128 v[24:27], v206 offset:2048
	ds_read_b128 v[28:31], v206 offset:3072
	ds_read_b128 v[0:3], v207
	ds_read_b128 v[4:7], v207 offset:1024
	ds_read_b128 v[8:11], v207 offset:2048
	ds_read_b128 v[12:15], v207 offset:3072
	s_add_u32 s18, s16, 0xfff50080
	s_addc_u32 s19, s17, -1
	s_cmp_eq_u32 s57, 40
	s_cselect_b32 s21, s7, s19
	s_cselect_b32 s20, s6, s18
	s_cselect_b32 s19, s15, s56
	s_cselect_b32 s18, s14, s55
	v_lshl_add_u64 v[200:201], s[16:17], 0, v[176:177]
	s_add_i32 m0, s25, 0xc000
	ds_read_b128 v[160:163], v208
	ds_read_b128 v[164:167], v208 offset:1024
	ds_read_b128 v[184:187], v208 offset:2048
	ds_read_b128 v[188:191], v208 offset:3072
	ds_read_b128 v[192:195], v208 offset:4096
	ds_read_b128 v[196:199], v208 offset:5120
	ds_read_b128 v[210:213], v208 offset:6144
	ds_read_b128 v[214:217], v208 offset:7168
	global_load_lds_dwordx4 v[200:201], off
	v_lshl_add_u64 v[200:201], s[16:17], 0, v[178:179]
	s_add_i32 m0, s25, 0xe000
	s_nop 0
	global_load_lds_dwordx4 v[200:201], off
	s_waitcnt vmcnt(8)
	s_waitcnt lgkmcnt(0)
	s_setprio 1
	s_barrier
	v_mfma_scale_f32_16x16x128_f8f6f4 v[156:159], v[16:23], v[160:167], v[156:159], v202, v202 op_sel_hi:[0,0,0]
	v_mfma_scale_f32_16x16x128_f8f6f4 v[152:155], v[24:31], v[160:167], v[152:155], v202, v202 op_sel_hi:[0,0,0]
	v_mfma_scale_f32_16x16x128_f8f6f4 v[140:143], v[16:23], v[184:191], v[140:143], v202, v202 op_sel_hi:[0,0,0]
	v_mfma_scale_f32_16x16x128_f8f6f4 v[136:139], v[24:31], v[184:191], v[136:139], v202, v202 op_sel_hi:[0,0,0]
	v_mfma_scale_f32_16x16x128_f8f6f4 v[124:127], v[16:23], v[192:199], v[124:127], v202, v202 op_sel_hi:[0,0,0]
	v_mfma_scale_f32_16x16x128_f8f6f4 v[120:123], v[24:31], v[192:199], v[120:123], v202, v202 op_sel_hi:[0,0,0]
	v_mfma_scale_f32_16x16x128_f8f6f4 v[108:111], v[16:23], v[210:217], v[108:111], v202, v202 op_sel_hi:[0,0,0]
	v_mfma_scale_f32_16x16x128_f8f6f4 v[104:107], v[24:31], v[210:217], v[104:107], v202, v202 op_sel_hi:[0,0,0]
	s_setprio 0
	s_setprio 1
	v_mfma_scale_f32_16x16x128_f8f6f4 v[148:151], v[0:7], v[160:167], v[148:151], v202, v202 op_sel_hi:[0,0,0]
	v_mfma_scale_f32_16x16x128_f8f6f4 v[144:147], v[8:15], v[160:167], v[144:147], v202, v202 op_sel_hi:[0,0,0]
	v_mfma_scale_f32_16x16x128_f8f6f4 v[132:135], v[0:7], v[184:191], v[132:135], v202, v202 op_sel_hi:[0,0,0]
	v_mfma_scale_f32_16x16x128_f8f6f4 v[128:131], v[8:15], v[184:191], v[128:131], v202, v202 op_sel_hi:[0,0,0]
	v_mfma_scale_f32_16x16x128_f8f6f4 v[116:119], v[0:7], v[192:199], v[116:119], v202, v202 op_sel_hi:[0,0,0]
	v_mfma_scale_f32_16x16x128_f8f6f4 v[112:115], v[8:15], v[192:199], v[112:115], v202, v202 op_sel_hi:[0,0,0]
	v_mfma_scale_f32_16x16x128_f8f6f4 v[100:103], v[0:7], v[210:217], v[100:103], v202, v202 op_sel_hi:[0,0,0]
	v_mfma_scale_f32_16x16x128_f8f6f4 v[96:99], v[8:15], v[210:217], v[96:99], v202, v202 op_sel_hi:[0,0,0]
	s_nop 0
	s_barrier
	s_setprio 0
	s_add_i32 s58, s38, s24
	v_lshl_add_u64 v[160:161], s[18:19], 0, v[170:171]
	s_mov_b32 m0, s58
	ds_read_b128 v[184:187], v208 offset:16384
	ds_read_b128 v[188:191], v208 offset:17408
	ds_read_b128 v[192:195], v208 offset:18432
	ds_read_b128 v[196:199], v208 offset:19456
	ds_read_b128 v[210:213], v208 offset:20480
	ds_read_b128 v[214:217], v208 offset:21504
	ds_read_b128 v[218:221], v208 offset:22528
	ds_read_b128 v[222:225], v208 offset:23552
	global_load_lds_dwordx4 v[160:161], off
	s_add_i32 m0, s58, 0x2000
	s_add_u32 s58, s18, 0xb0000
	v_lshl_add_u64 v[162:163], s[18:19], 0, v[174:175]
	s_addc_u32 s59, s19, 0
	s_add_i32 s60, s39, s24
	global_load_lds_dwordx4 v[162:163], off
	v_lshl_add_u64 v[164:165], s[58:59], 0, v[170:171]
	s_mov_b32 m0, s60
	v_lshl_add_u64 v[166:167], s[20:21], 0, v[172:173]
	global_load_lds_dwordx4 v[164:165], off
	v_lshl_add_u64 v[164:165], s[58:59], 0, v[174:175]
	s_add_i32 m0, s60, 0x2000
	s_nop 0
	global_load_lds_dwordx4 v[164:165], off
	v_lshl_add_u64 v[164:165], s[20:21], 0, v[168:169]
	s_mov_b32 m0, s25
	s_nop 0
	global_load_lds_dwordx4 v[164:165], off
	s_mov_b32 m0, s26
	s_nop 0
	global_load_lds_dwordx4 v[166:167], off
	s_waitcnt vmcnt(8)
	s_waitcnt lgkmcnt(0)
	s_setprio 1
	s_barrier
	v_mfma_scale_f32_16x16x128_f8f6f4 v[92:95], v[16:23], v[184:191], v[92:95], v202, v202 op_sel_hi:[0,0,0]
	v_mfma_scale_f32_16x16x128_f8f6f4 v[88:91], v[24:31], v[184:191], v[88:91], v202, v202 op_sel_hi:[0,0,0]
	v_mfma_scale_f32_16x16x128_f8f6f4 v[76:79], v[16:23], v[192:199], v[76:79], v202, v202 op_sel_hi:[0,0,0]
	v_mfma_scale_f32_16x16x128_f8f6f4 v[72:75], v[24:31], v[192:199], v[72:75], v202, v202 op_sel_hi:[0,0,0]
	v_mfma_scale_f32_16x16x128_f8f6f4 v[60:63], v[16:23], v[210:217], v[60:63], v202, v202 op_sel_hi:[0,0,0]
	v_mfma_scale_f32_16x16x128_f8f6f4 v[56:59], v[24:31], v[210:217], v[56:59], v202, v202 op_sel_hi:[0,0,0]
	v_mfma_scale_f32_16x16x128_f8f6f4 v[44:47], v[16:23], v[218:225], v[44:47], v202, v202 op_sel_hi:[0,0,0]
	v_mfma_scale_f32_16x16x128_f8f6f4 v[40:43], v[24:31], v[218:225], v[40:43], v202, v202 op_sel_hi:[0,0,0]
	s_setprio 0
	s_setprio 1
	v_mfma_scale_f32_16x16x128_f8f6f4 v[84:87], v[0:7], v[184:191], v[84:87], v202, v202 op_sel_hi:[0,0,0]
	v_mfma_scale_f32_16x16x128_f8f6f4 v[80:83], v[8:15], v[184:191], v[80:83], v202, v202 op_sel_hi:[0,0,0]
	v_mfma_scale_f32_16x16x128_f8f6f4 v[68:71], v[0:7], v[192:199], v[68:71], v202, v202 op_sel_hi:[0,0,0]
	v_mfma_scale_f32_16x16x128_f8f6f4 v[64:67], v[8:15], v[192:199], v[64:67], v202, v202 op_sel_hi:[0,0,0]
	v_mfma_scale_f32_16x16x128_f8f6f4 v[52:55], v[0:7], v[210:217], v[52:55], v202, v202 op_sel_hi:[0,0,0]
	v_mfma_scale_f32_16x16x128_f8f6f4 v[48:51], v[8:15], v[210:217], v[48:51], v202, v202 op_sel_hi:[0,0,0]
	v_mfma_scale_f32_16x16x128_f8f6f4 v[36:39], v[0:7], v[218:225], v[36:39], v202, v202 op_sel_hi:[0,0,0]
	v_mfma_scale_f32_16x16x128_f8f6f4 v[32:35], v[8:15], v[218:225], v[32:35], v202, v202 op_sel_hi:[0,0,0]
	s_nop 0
	s_barrier
; #define PG8_STAGE(bufoff, gbase, voff) do { _Pragma("unroll") for (int _i = 0; _i < 2; ++_i) \
;         __builtin_amdgcn_global_load_lds((const unsigned*)((const char*)(gbase) + (voff)[_i]), (PG8_LAS unsigned*)(lds + (bufoff) + ldsw + _i * 8192), 16, 0, 0); } while (0)
; #define PG8_WAIT_V(n) asm volatile("s_waitcnt vmcnt(" #n ")" ::: "memory")
; #define PG8_WAIT_L(n) asm volatile("s_waitcnt lgkmcnt(" #n ")" ::: "memory")
; #define PG8_BAR __builtin_amdgcn_s_barrier()
; #define PG8_SCHED __builtin_amdgcn_sched_barrier(0)
; template <class Epi, class Sched, bool ALIGN_EPI = true, bool SP2 = true>
; __device__ __forceinline__ void gemm_phase(PG8_LAS unsigned char* lds, const int K  , const Sched& S, const Epi& E) {
;     ...
;             PG8_LDB(B0, 1, 0); PG8_LDB(B1, 1, 1); PG8_SCHED; PG8_LDA(At, 1, 0); PG8_STAGE(PG8_SA(0, 1), a2 + hstep, voffA);
;             PG8_WAIT_V(8); PG8_WAIT_L(0); PG8_BAR; PG8_MMA(0, 0, At, B0); PG8_MMA(0, 1, At, B1); PG8_BAR; PG8_SCHED;
;             PG8_LDA(At, 1, 1); PG8_STAGE(PG8_SB(1, 0), b3, voffB); PG8_STAGE(PG8_SB(1, 1), b3 + hstep, voffB); PG8_STAGE(PG8_SA(1, 0), a3, voffA);
;             PG8_WAIT_V(8); PG8_WAIT_L(0); PG8_BAR; PG8_MMA(1, 0, At, B0); PG8_MMA(1, 1, At, B1); PG8_BAR; PG8_SCHED;
;     ...
;         if constexpr (Epi::FP8) asm volatile("s_nop 15\n\ts_nop 15\n\ts_nop 15\n\ts_nop 15\n\ts_nop 15" ::: "memory");
;         if constexpr (ALIGN_EPI) { if (wr == 0) PG8_BAR; }
	s_setprio 0
	s_add_i32 s58, 0, 0x18000
	s_add_i32 s59, 0, 0x1c000
	v_add_u32_e32 v12, s58, v204
	v_add_u32_e32 v28, s59, v204
	ds_read_b128 v[0:3], v12
	ds_read_b128 v[4:7], v12 offset:1024
	ds_read_b128 v[8:11], v12 offset:2048
	ds_read_b128 v[12:15], v12 offset:3072
	ds_read_b128 v[16:19], v28
	ds_read_b128 v[20:23], v28 offset:1024
	ds_read_b128 v[24:27], v28 offset:2048
	ds_read_b128 v[28:31], v28 offset:3072
	s_add_u32 s20, s20, 0xb0000
	s_addc_u32 s21, s21, 0
	s_mov_b32 m0, s27
	v_lshl_add_u64 v[200:201], s[20:21], 0, v[168:169]
	ds_read_b128 v[184:187], v208 offset:32768
	ds_read_b128 v[188:191], v208 offset:33792
	ds_read_b128 v[192:195], v208 offset:34816
	ds_read_b128 v[196:199], v208 offset:35840
	ds_read_b128 v[210:213], v208 offset:36864
	ds_read_b128 v[214:217], v208 offset:37888
	ds_read_b128 v[218:221], v208 offset:38912
	ds_read_b128 v[222:225], v208 offset:39936
	global_load_lds_dwordx4 v[200:201], off
	v_lshl_add_u64 v[200:201], s[20:21], 0, v[172:173]
	s_mov_b32 m0, s28
	s_nop 0
	global_load_lds_dwordx4 v[200:201], off
	s_waitcnt vmcnt(8)
	s_waitcnt lgkmcnt(0)
	s_setprio 1
	s_barrier
	v_mfma_scale_f32_16x16x128_f8f6f4 v[156:159], v[0:7], v[184:191], v[156:159], v202, v202 op_sel_hi:[0,0,0]
	v_mfma_scale_f32_16x16x128_f8f6f4 v[152:155], v[8:15], v[184:191], v[152:155], v202, v202 op_sel_hi:[0,0,0]
	v_mfma_scale_f32_16x16x128_f8f6f4 v[140:143], v[0:7], v[192:199], v[140:143], v202, v202 op_sel_hi:[0,0,0]
	v_mfma_scale_f32_16x16x128_f8f6f4 v[136:139], v[8:15], v[192:199], v[136:139], v202, v202 op_sel_hi:[0,0,0]
	v_mfma_scale_f32_16x16x128_f8f6f4 v[124:127], v[0:7], v[210:217], v[124:127], v202, v202 op_sel_hi:[0,0,0]
	v_mfma_scale_f32_16x16x128_f8f6f4 v[120:123], v[8:15], v[210:217], v[120:123], v202, v202 op_sel_hi:[0,0,0]
	v_mfma_scale_f32_16x16x128_f8f6f4 v[108:111], v[0:7], v[218:225], v[108:111], v202, v202 op_sel_hi:[0,0,0]
	v_mfma_scale_f32_16x16x128_f8f6f4 v[104:107], v[8:15], v[218:225], v[104:107], v202, v202 op_sel_hi:[0,0,0]
	s_setprio 0
	s_setprio 1
	v_mfma_scale_f32_16x16x128_f8f6f4 v[148:151], v[16:23], v[184:191], v[148:151], v202, v202 op_sel_hi:[0,0,0]
	v_mfma_scale_f32_16x16x128_f8f6f4 v[144:147], v[24:31], v[184:191], v[144:147], v202, v202 op_sel_hi:[0,0,0]
	v_mfma_scale_f32_16x16x128_f8f6f4 v[132:135], v[16:23], v[192:199], v[132:135], v202, v202 op_sel_hi:[0,0,0]
	v_mfma_scale_f32_16x16x128_f8f6f4 v[128:131], v[24:31], v[192:199], v[128:131], v202, v202 op_sel_hi:[0,0,0]
	v_mfma_scale_f32_16x16x128_f8f6f4 v[116:119], v[16:23], v[210:217], v[116:119], v202, v202 op_sel_hi:[0,0,0]
	v_mfma_scale_f32_16x16x128_f8f6f4 v[112:115], v[24:31], v[210:217], v[112:115], v202, v202 op_sel_hi:[0,0,0]
	v_mfma_scale_f32_16x16x128_f8f6f4 v[100:103], v[16:23], v[218:225], v[100:103], v202, v202 op_sel_hi:[0,0,0]
	v_mfma_scale_f32_16x16x128_f8f6f4 v[96:99], v[24:31], v[218:225], v[96:99], v202, v202 op_sel_hi:[0,0,0]
	s_nop 0
	s_barrier
	s_setprio 0
	s_add_i32 s20, s58, s24
	v_lshl_add_u64 v[160:161], v[160:161], 0, s[8:9]
	s_mov_b32 m0, s20
	ds_read_b128 v[184:187], v208 offset:49152
	ds_read_b128 v[188:191], v208 offset:50176
	ds_read_b128 v[192:195], v208 offset:51200
	ds_read_b128 v[196:199], v208 offset:52224
	ds_read_b128 v[210:213], v208 offset:53248
	ds_read_b128 v[214:217], v208 offset:54272
	ds_read_b128 v[218:221], v208 offset:55296
	ds_read_b128 v[222:225], v208 offset:56320
	global_load_lds_dwordx4 v[160:161], off
	s_add_i32 m0, s20, 0x2000
	s_add_u32 s18, s18, 0xb0080
	v_lshl_add_u64 v[160:161], v[162:163], 0, s[8:9]
	s_addc_u32 s19, s19, 0
	s_add_i32 s20, s59, s24
	global_load_lds_dwordx4 v[160:161], off
	v_lshl_add_u64 v[160:161], s[18:19], 0, v[170:171]
	s_mov_b32 m0, s20
	s_nop 0
	global_load_lds_dwordx4 v[160:161], off
	v_lshl_add_u64 v[160:161], s[18:19], 0, v[174:175]
	s_add_i32 m0, s20, 0x2000
	s_nop 0
	global_load_lds_dwordx4 v[160:161], off
	v_lshl_add_u64 v[160:161], v[164:165], 0, s[8:9]
	s_mov_b32 m0, s35
	s_nop 0
	global_load_lds_dwordx4 v[160:161], off
	v_lshl_add_u64 v[160:161], v[166:167], 0, s[8:9]
	s_mov_b32 m0, s36
	s_nop 0
	global_load_lds_dwordx4 v[160:161], off
	s_waitcnt vmcnt(8)
	s_waitcnt lgkmcnt(0)
	s_setprio 1
	s_barrier
	v_mfma_scale_f32_16x16x128_f8f6f4 v[92:95], v[0:7], v[184:191], v[92:95], v202, v202 op_sel_hi:[0,0,0]
	v_mfma_scale_f32_16x16x128_f8f6f4 v[88:91], v[8:15], v[184:191], v[88:91], v202, v202 op_sel_hi:[0,0,0]
	v_mfma_scale_f32_16x16x128_f8f6f4 v[76:79], v[0:7], v[192:199], v[76:79], v202, v202 op_sel_hi:[0,0,0]
	v_mfma_scale_f32_16x16x128_f8f6f4 v[72:75], v[8:15], v[192:199], v[72:75], v202, v202 op_sel_hi:[0,0,0]
	v_mfma_scale_f32_16x16x128_f8f6f4 v[60:63], v[0:7], v[210:217], v[60:63], v202, v202 op_sel_hi:[0,0,0]
	v_mfma_scale_f32_16x16x128_f8f6f4 v[56:59], v[8:15], v[210:217], v[56:59], v202, v202 op_sel_hi:[0,0,0]
	v_mfma_scale_f32_16x16x128_f8f6f4 v[44:47], v[0:7], v[218:225], v[44:47], v202, v202 op_sel_hi:[0,0,0]
	v_mfma_scale_f32_16x16x128_f8f6f4 v[40:43], v[8:15], v[218:225], v[40:43], v202, v202 op_sel_hi:[0,0,0]
	s_setprio 0
	s_setprio 1
	v_mfma_scale_f32_16x16x128_f8f6f4 v[84:87], v[16:23], v[184:191], v[84:87], v202, v202 op_sel_hi:[0,0,0]
	v_mfma_scale_f32_16x16x128_f8f6f4 v[80:83], v[24:31], v[184:191], v[80:83], v202, v202 op_sel_hi:[0,0,0]
	v_mfma_scale_f32_16x16x128_f8f6f4 v[68:71], v[16:23], v[192:199], v[68:71], v202, v202 op_sel_hi:[0,0,0]
	v_mfma_scale_f32_16x16x128_f8f6f4 v[64:67], v[24:31], v[192:199], v[64:67], v202, v202 op_sel_hi:[0,0,0]
	v_mfma_scale_f32_16x16x128_f8f6f4 v[52:55], v[16:23], v[210:217], v[52:55], v202, v202 op_sel_hi:[0,0,0]
	v_mfma_scale_f32_16x16x128_f8f6f4 v[48:51], v[24:31], v[210:217], v[48:51], v202, v202 op_sel_hi:[0,0,0]
	v_mfma_scale_f32_16x16x128_f8f6f4 v[36:39], v[16:23], v[218:225], v[36:39], v202, v202 op_sel_hi:[0,0,0]
	v_mfma_scale_f32_16x16x128_f8f6f4 v[32:35], v[24:31], v[218:225], v[32:35], v202, v202 op_sel_hi:[0,0,0]
	s_nop 0
	s_barrier
	s_setprio 0
	s_add_i32 s57, s57, 2
	s_add_u32 s16, s16, 0x100
	s_addc_u32 s17, s17, 0
	s_add_u32 s55, s55, 0x100
	s_addc_u32 s56, s56, 0
	s_cmp_gt_u32 s57, 41
	s_cbranch_scc0 .LBB0_2516
	s_nop 15
	s_nop 15
	s_nop 15
	s_nop 15
	s_nop 15
	s_and_b64 vcc, exec, s[10:11]
	s_cbranch_vccz .LBB0_2519
	s_barrier
